# issue-slot trims on the critical segments: GEMM loops - SALU/VALU between a cluster's last MFMA and its barrier moved behind the barrier; attention PV - one lgkmcnt(0) ahead of the first PV MFMA repla
# speedup vs baseline: 1.0114x; 1.0020x over previous
;     __device__ __forceinline__ unsigned* BAR() const { return (unsigned*)(ws + OFF_BAR); }
; #define STAGE(bufoff, gbase, voff) do { _Pragma("unroll") for (int _i = 0; _i < 2; ++_i) \
;         __builtin_amdgcn_global_load_lds((const unsigned*)((const char*)(gbase) + voff[_i]), (LAS unsigned*)(lds + (bufoff) + ldsw + _i * 8192), 16, 0, 0); } while (0)
; #define LDA(dst, b, h) do { _Pragma("unroll") for (int m = 0; m < 4; ++m) _Pragma("unroll") for (int k = 0; k < 2; ++k) dst[m][k] = *(const LAS bf16x8*)(lds + SA(b, h) + aoff + m * 2048 + k * 1024); } while (0)
; #define LDB(dst, b, h) do { _Pragma("unroll") for (int n = 0; n < 2; ++n) _Pragma("unroll") for (int k = 0; k < 2; ++k) dst[n][k] = *(const LAS bf16x8*)(lds + SB(b, h) + boff + n * 2048 + k * 1024); } while (0)
; #define MMA(ai, bj, At, Bx) do { __builtin_amdgcn_s_setprio(1); _Pragma("unroll") for (int m = 0; m < 4; ++m) _Pragma("unroll") for (int n = 0; n < 2; ++n) _Pragma("unroll") for (int k = 0; k < 2; ++k) \
;       acc[ai][bj][m][n] = __builtin_amdgcn_mfma_f32_16x16x32_bf16(At[m][k], Bx[n][k], acc[ai][bj][m][n], 0, 0, 0); \
;     __builtin_amdgcn_s_setprio(0); } while (0)
; #define WAIT_L(n) asm volatile("s_waitcnt lgkmcnt(" #n ")" ::: "memory")
; #define BAR __builtin_amdgcn_s_barrier()
; #define SCHED __builtin_amdgcn_sched_barrier(0)
;     ...
;     for (int t = 0; t < nt - 2; t += 2) {
;         if (KSEG && t > 0 && (t % (KSEG ? KSEG : 1)) == 0) hook(t / (KSEG ? KSEG : 1), acc);
;         const char* a1 = pA(t + 1); const char* a2 = pA(t + 2); const char* a3 = pA(t + 3);
;         const char* b2 = pB(t + 2); const char* b3 = pB(t + 3);
;         LDB(B0, 0, 0); SCHED; LDA(At, 0, 0); STAGE(SA(1, 1), a1 + hstepA, voffA);
;         WAIT_L(8); BAR; WAIT_L(0); MMA(0, 0, At, B0); BAR; SCHED;
;         LDB(B1, 0, 1); STAGE(SB(0, 0), b2, voffB);
;         BAR; WAIT_L(0); MMA(0, 1, At, B1); BAR;
;         LDA(At, 0, 1); STAGE(SA(0, 0), a2, voffA);
.LBB0_227:
	s_add_i32 s9, 0, 0x10000
	v_add_u32_e32 v138, s9, v143
	ds_read_b128 v[144:147], v138
	ds_read_b128 v[148:151], v138 offset:1024
	ds_read_b128 v[152:155], v138 offset:2048
	ds_read_b128 v[156:159], v138 offset:3072
	v_lshl_add_u64 v[138:139], s[4:5], 0, v[136:137]
	s_add_i32 s8, s12, 0xc000
	v_lshl_add_u64 v[214:215], v[138:139], 0, s[36:37]
	s_mov_b32 m0, s8
	v_lshl_add_u64 v[230:231], s[4:5], 0, v[140:141]
	s_add_i32 s7, s12, 0xe000
	ds_read_b128 v[160:163], v142
	ds_read_b128 v[164:167], v142 offset:1024
	ds_read_b128 v[190:193], v142 offset:2048
	ds_read_b128 v[194:197], v142 offset:3072
	ds_read_b128 v[198:201], v142 offset:4096
	ds_read_b128 v[202:205], v142 offset:5120
	ds_read_b128 v[206:209], v142 offset:6144
	ds_read_b128 v[210:213], v142 offset:7168
	global_load_lds_dwordx4 v[214:215], off
	v_lshl_add_u64 v[214:215], v[230:231], 0, s[36:37]
	s_mov_b32 m0, s7
	s_nop 0
	global_load_lds_dwordx4 v[214:215], off
	s_waitcnt lgkmcnt(8)
	s_barrier
	s_waitcnt lgkmcnt(0)
	v_mfma_f32_16x16x32_bf16 v[126:129], v[160:163], v[144:147], v[126:129]
	v_mfma_f32_16x16x32_bf16 v[122:125], v[160:163], v[152:155], v[122:125]
	v_mfma_f32_16x16x32_bf16 v[118:121], v[190:193], v[144:147], v[118:121]
	v_mfma_f32_16x16x32_bf16 v[114:117], v[190:193], v[152:155], v[114:117]
	v_mfma_f32_16x16x32_bf16 v[110:113], v[198:201], v[144:147], v[110:113]
	v_mfma_f32_16x16x32_bf16 v[106:109], v[198:201], v[152:155], v[106:109]
	v_mfma_f32_16x16x32_bf16 v[102:105], v[206:209], v[144:147], v[102:105]
	v_mfma_f32_16x16x32_bf16 v[98:101], v[206:209], v[152:155], v[98:101]
	v_mfma_f32_16x16x32_bf16 v[126:129], v[164:167], v[148:151], v[126:129]
	v_mfma_f32_16x16x32_bf16 v[122:125], v[164:167], v[156:159], v[122:125]
	v_mfma_f32_16x16x32_bf16 v[118:121], v[194:197], v[148:151], v[118:121]
	v_mfma_f32_16x16x32_bf16 v[114:117], v[194:197], v[156:159], v[114:117]
	v_mfma_f32_16x16x32_bf16 v[110:113], v[202:205], v[148:151], v[110:113]
	v_mfma_f32_16x16x32_bf16 v[106:109], v[202:205], v[156:159], v[106:109]
	v_mfma_f32_16x16x32_bf16 v[102:105], v[210:213], v[148:151], v[102:105]
	v_mfma_f32_16x16x32_bf16 v[98:101], v[210:213], v[156:159], v[98:101]
	s_barrier
	s_add_i32 s16, 0, 0x14000
	v_lshl_add_u64 v[232:233], s[4:5], 0, v[132:133]
	s_add_i32 s9, s9, s11
	v_add_u32_e32 v226, s16, v143
	v_lshl_add_u64 v[234:235], v[232:233], 0, s[38:39]
	s_mov_b32 m0, s9
	ds_read_b128 v[214:217], v226
	ds_read_b128 v[218:221], v226 offset:1024
	ds_read_b128 v[222:225], v226 offset:2048
	ds_read_b128 v[226:229], v226 offset:3072
	global_load_lds_dwordx4 v[234:235], off
	v_lshl_add_u64 v[234:235], s[4:5], 0, v[134:135]
	v_lshl_add_u64 v[236:237], v[234:235], 0, s[38:39]
	s_add_i32 m0, s9, 0x2000
	s_nop 0
	global_load_lds_dwordx4 v[236:237], off
	s_barrier
	s_waitcnt lgkmcnt(0)
	v_mfma_f32_16x16x32_bf16 v[94:97], v[160:163], v[214:217], v[94:97]
	v_mfma_f32_16x16x32_bf16 v[90:93], v[160:163], v[222:225], v[90:93]
	v_mfma_f32_16x16x32_bf16 v[86:89], v[190:193], v[214:217], v[86:89]
	v_mfma_f32_16x16x32_bf16 v[82:85], v[190:193], v[222:225], v[82:85]
	v_mfma_f32_16x16x32_bf16 v[78:81], v[198:201], v[214:217], v[78:81]
	v_mfma_f32_16x16x32_bf16 v[74:77], v[198:201], v[222:225], v[74:77]
	v_mfma_f32_16x16x32_bf16 v[70:73], v[206:209], v[214:217], v[70:73]
	v_mfma_f32_16x16x32_bf16 v[66:69], v[206:209], v[222:225], v[66:69]
	v_mfma_f32_16x16x32_bf16 v[94:97], v[164:167], v[218:221], v[94:97]
	v_mfma_f32_16x16x32_bf16 v[90:93], v[164:167], v[226:229], v[90:93]
	v_mfma_f32_16x16x32_bf16 v[86:89], v[194:197], v[218:221], v[86:89]
	v_mfma_f32_16x16x32_bf16 v[82:85], v[194:197], v[226:229], v[82:85]
	v_mfma_f32_16x16x32_bf16 v[78:81], v[202:205], v[218:221], v[78:81]
	v_mfma_f32_16x16x32_bf16 v[74:77], v[202:205], v[226:229], v[74:77]
	v_mfma_f32_16x16x32_bf16 v[70:73], v[210:213], v[218:221], v[70:73]
	v_mfma_f32_16x16x32_bf16 v[66:69], v[210:213], v[226:229], v[66:69]
	s_barrier
	s_mov_b32 m0, s12
	v_lshl_add_u64 v[236:237], v[138:139], 0, s[40:41]
	ds_read_b128 v[160:163], v142 offset:16384
	ds_read_b128 v[164:167], v142 offset:17408
	ds_read_b128 v[190:193], v142 offset:18432
	ds_read_b128 v[194:197], v142 offset:19456
	ds_read_b128 v[198:201], v142 offset:20480
	ds_read_b128 v[202:205], v142 offset:21504
	ds_read_b128 v[206:209], v142 offset:22528
	ds_read_b128 v[210:213], v142 offset:23552
	global_load_lds_dwordx4 v[236:237], off
	v_lshl_add_u64 v[236:237], v[230:231], 0, s[40:41]
	s_mov_b32 m0, s13
	s_nop 0
	global_load_lds_dwordx4 v[236:237], off
	s_barrier
	s_waitcnt lgkmcnt(0)
	v_mfma_f32_16x16x32_bf16 v[62:65], v[160:163], v[144:147], v[62:65]
	v_mfma_f32_16x16x32_bf16 v[58:61], v[160:163], v[152:155], v[58:61]
	v_mfma_f32_16x16x32_bf16 v[54:57], v[190:193], v[144:147], v[54:57]
	v_mfma_f32_16x16x32_bf16 v[50:53], v[190:193], v[152:155], v[50:53]
	v_mfma_f32_16x16x32_bf16 v[46:49], v[198:201], v[144:147], v[46:49]
	v_mfma_f32_16x16x32_bf16 v[42:45], v[198:201], v[152:155], v[42:45]
	v_mfma_f32_16x16x32_bf16 v[38:41], v[206:209], v[144:147], v[38:41]
	v_mfma_f32_16x16x32_bf16 v[34:37], v[206:209], v[152:155], v[34:37]
	v_mfma_f32_16x16x32_bf16 v[62:65], v[164:167], v[148:151], v[62:65]
	v_mfma_f32_16x16x32_bf16 v[58:61], v[164:167], v[156:159], v[58:61]
	v_mfma_f32_16x16x32_bf16 v[54:57], v[194:197], v[148:151], v[54:57]
	v_mfma_f32_16x16x32_bf16 v[50:53], v[194:197], v[156:159], v[50:53]
	v_mfma_f32_16x16x32_bf16 v[46:49], v[202:205], v[148:151], v[46:49]
	v_mfma_f32_16x16x32_bf16 v[42:45], v[202:205], v[156:159], v[42:45]
	v_mfma_f32_16x16x32_bf16 v[38:41], v[210:213], v[148:151], v[38:41]
	v_mfma_f32_16x16x32_bf16 v[34:37], v[210:213], v[156:159], v[34:37]
	s_barrier
;     __device__ __forceinline__ unsigned* BAR() const { return (unsigned*)(ws + OFF_BAR); }
; #define STAGE(bufoff, gbase, voff) do { _Pragma("unroll") for (int _i = 0; _i < 2; ++_i) \
;         __builtin_amdgcn_global_load_lds((const unsigned*)((const char*)(gbase) + voff[_i]), (LAS unsigned*)(lds + (bufoff) + ldsw + _i * 8192), 16, 0, 0); } while (0)
; #define LDA(dst, b, h) do { _Pragma("unroll") for (int m = 0; m < 4; ++m) _Pragma("unroll") for (int k = 0; k < 2; ++k) dst[m][k] = *(const LAS bf16x8*)(lds + SA(b, h) + aoff + m * 2048 + k * 1024); } while (0)
; #define LDB(dst, b, h) do { _Pragma("unroll") for (int n = 0; n < 2; ++n) _Pragma("unroll") for (int k = 0; k < 2; ++k) dst[n][k] = *(const LAS bf16x8*)(lds + SB(b, h) + boff + n * 2048 + k * 1024); } while (0)
; #define MMA(ai, bj, At, Bx) do { __builtin_amdgcn_s_setprio(1); _Pragma("unroll") for (int m = 0; m < 4; ++m) _Pragma("unroll") for (int n = 0; n < 2; ++n) _Pragma("unroll") for (int k = 0; k < 2; ++k) \
;       acc[ai][bj][m][n] = __builtin_amdgcn_mfma_f32_16x16x32_bf16(At[m][k], Bx[n][k], acc[ai][bj][m][n], 0, 0, 0); \
;     __builtin_amdgcn_s_setprio(0); } while (0)
; #define WAIT_V(n) asm volatile("s_waitcnt vmcnt(" #n ")" ::: "memory")
; #define WAIT_L(n) asm volatile("s_waitcnt lgkmcnt(" #n ")" ::: "memory")
; #define BAR __builtin_amdgcn_s_barrier()
; #define SCHED __builtin_amdgcn_sched_barrier(0)
;     ...
;         BAR; WAIT_L(0); MMA(1, 0, At, B0); BAR; SCHED;
;         STAGE(SB(0, 1), b2 + hstepB, voffB);
;         WAIT_V(6); BAR; MMA(1, 1, At, B1); BAR;
;         LDB(B0, 1, 0); SCHED; LDA(At, 1, 0); STAGE(SA(0, 1), a2 + hstepA, voffA);
;         WAIT_L(8); BAR; WAIT_L(0); MMA(0, 0, At, B0); BAR; SCHED;
;         LDB(B1, 1, 1); STAGE(SB(1, 0), b3, voffB);
	s_add_i32 s9, s16, s11
	v_lshl_add_u64 v[144:145], v[232:233], 0, s[44:45]
	s_mov_b32 m0, s9
	s_nop 0
	global_load_lds_dwordx4 v[144:145], off
	v_lshl_add_u64 v[144:145], v[234:235], 0, s[44:45]
	s_add_i32 m0, s9, 0x2000
	s_nop 0
	global_load_lds_dwordx4 v[144:145], off
	s_waitcnt vmcnt(6)
	s_barrier
	v_mfma_f32_16x16x32_bf16 v[30:33], v[160:163], v[214:217], v[30:33]
	v_mfma_f32_16x16x32_bf16 v[26:29], v[160:163], v[222:225], v[26:29]
	v_mfma_f32_16x16x32_bf16 v[22:25], v[190:193], v[214:217], v[22:25]
	v_mfma_f32_16x16x32_bf16 v[18:21], v[190:193], v[222:225], v[18:21]
	v_mfma_f32_16x16x32_bf16 v[14:17], v[198:201], v[214:217], v[14:17]
	v_mfma_f32_16x16x32_bf16 v[10:13], v[198:201], v[222:225], v[10:13]
	v_mfma_f32_16x16x32_bf16 v[6:9], v[206:209], v[214:217], v[6:9]
	v_mfma_f32_16x16x32_bf16 v[2:5], v[206:209], v[222:225], v[2:5]
	v_mfma_f32_16x16x32_bf16 v[30:33], v[164:167], v[218:221], v[30:33]
	v_mfma_f32_16x16x32_bf16 v[26:29], v[164:167], v[226:229], v[26:29]
	v_mfma_f32_16x16x32_bf16 v[22:25], v[194:197], v[218:221], v[22:25]
	v_mfma_f32_16x16x32_bf16 v[18:21], v[194:197], v[226:229], v[18:21]
	v_mfma_f32_16x16x32_bf16 v[14:17], v[202:205], v[218:221], v[14:17]
	v_mfma_f32_16x16x32_bf16 v[10:13], v[202:205], v[226:229], v[10:13]
	v_mfma_f32_16x16x32_bf16 v[6:9], v[210:213], v[218:221], v[6:9]
	v_mfma_f32_16x16x32_bf16 v[2:5], v[210:213], v[226:229], v[2:5]
	s_barrier
	s_add_i32 s9, 0, 0x18000
	v_add_u32_e32 v156, s9, v143
	ds_read_b128 v[144:147], v156
	ds_read_b128 v[148:151], v156 offset:1024
	ds_read_b128 v[152:155], v156 offset:2048
	ds_read_b128 v[156:159], v156 offset:3072
	s_mov_b32 m0, s14
	v_lshl_add_u64 v[214:215], v[138:139], 0, s[46:47]
	ds_read_b128 v[160:163], v142 offset:32768
	ds_read_b128 v[164:167], v142 offset:33792
	ds_read_b128 v[190:193], v142 offset:34816
	ds_read_b128 v[194:197], v142 offset:35840
	ds_read_b128 v[198:201], v142 offset:36864
	ds_read_b128 v[202:205], v142 offset:37888
	ds_read_b128 v[206:209], v142 offset:38912
	ds_read_b128 v[210:213], v142 offset:39936
	global_load_lds_dwordx4 v[214:215], off
	v_lshl_add_u64 v[214:215], v[230:231], 0, s[46:47]
	s_mov_b32 m0, s15
	s_nop 0
	global_load_lds_dwordx4 v[214:215], off
	s_waitcnt lgkmcnt(8)
	s_barrier
	s_waitcnt lgkmcnt(0)
	v_mfma_f32_16x16x32_bf16 v[126:129], v[160:163], v[144:147], v[126:129]
	v_mfma_f32_16x16x32_bf16 v[122:125], v[160:163], v[152:155], v[122:125]
	v_mfma_f32_16x16x32_bf16 v[118:121], v[190:193], v[144:147], v[118:121]
	v_mfma_f32_16x16x32_bf16 v[114:117], v[190:193], v[152:155], v[114:117]
	v_mfma_f32_16x16x32_bf16 v[110:113], v[198:201], v[144:147], v[110:113]
	v_mfma_f32_16x16x32_bf16 v[106:109], v[198:201], v[152:155], v[106:109]
	v_mfma_f32_16x16x32_bf16 v[102:105], v[206:209], v[144:147], v[102:105]
	v_mfma_f32_16x16x32_bf16 v[98:101], v[206:209], v[152:155], v[98:101]
	v_mfma_f32_16x16x32_bf16 v[126:129], v[164:167], v[148:151], v[126:129]
	v_mfma_f32_16x16x32_bf16 v[122:125], v[164:167], v[156:159], v[122:125]
	v_mfma_f32_16x16x32_bf16 v[118:121], v[194:197], v[148:151], v[118:121]
	v_mfma_f32_16x16x32_bf16 v[114:117], v[194:197], v[156:159], v[114:117]
	v_mfma_f32_16x16x32_bf16 v[110:113], v[202:205], v[148:151], v[110:113]
	v_mfma_f32_16x16x32_bf16 v[106:109], v[202:205], v[156:159], v[106:109]
	v_mfma_f32_16x16x32_bf16 v[102:105], v[210:213], v[148:151], v[102:105]
	v_mfma_f32_16x16x32_bf16 v[98:101], v[210:213], v[156:159], v[98:101]
	s_barrier
	s_add_i32 s16, 0, 0x1c000
	s_add_i32 s9, s9, s11
	v_add_u32_e32 v226, s16, v143
	v_lshl_add_u64 v[236:237], v[232:233], 0, s[48:49]
	s_mov_b32 m0, s9
	ds_read_b128 v[214:217], v226
	ds_read_b128 v[218:221], v226 offset:1024
	ds_read_b128 v[222:225], v226 offset:2048
	ds_read_b128 v[226:229], v226 offset:3072
	global_load_lds_dwordx4 v[236:237], off
	v_lshl_add_u64 v[236:237], v[234:235], 0, s[48:49]
	s_add_i32 m0, s9, 0x2000
	s_nop 0
	global_load_lds_dwordx4 v[236:237], off
	s_barrier
	s_waitcnt lgkmcnt(0)
	v_mfma_f32_16x16x32_bf16 v[94:97], v[160:163], v[214:217], v[94:97]
	v_mfma_f32_16x16x32_bf16 v[90:93], v[160:163], v[222:225], v[90:93]
	v_mfma_f32_16x16x32_bf16 v[86:89], v[190:193], v[214:217], v[86:89]
	v_mfma_f32_16x16x32_bf16 v[82:85], v[190:193], v[222:225], v[82:85]
	v_mfma_f32_16x16x32_bf16 v[78:81], v[198:201], v[214:217], v[78:81]
	v_mfma_f32_16x16x32_bf16 v[74:77], v[198:201], v[222:225], v[74:77]
	v_mfma_f32_16x16x32_bf16 v[70:73], v[206:209], v[214:217], v[70:73]
	v_mfma_f32_16x16x32_bf16 v[66:69], v[206:209], v[222:225], v[66:69]
	v_mfma_f32_16x16x32_bf16 v[94:97], v[164:167], v[218:221], v[94:97]
	v_mfma_f32_16x16x32_bf16 v[90:93], v[164:167], v[226:229], v[90:93]
	v_mfma_f32_16x16x32_bf16 v[86:89], v[194:197], v[218:221], v[86:89]
	v_mfma_f32_16x16x32_bf16 v[82:85], v[194:197], v[226:229], v[82:85]
	v_mfma_f32_16x16x32_bf16 v[78:81], v[202:205], v[218:221], v[78:81]
	v_mfma_f32_16x16x32_bf16 v[74:77], v[202:205], v[226:229], v[74:77]
	v_mfma_f32_16x16x32_bf16 v[70:73], v[210:213], v[218:221], v[70:73]
	v_mfma_f32_16x16x32_bf16 v[66:69], v[210:213], v[226:229], v[66:69]
	s_barrier
	s_mov_b32 m0, s24
	v_lshl_add_u64 v[138:139], v[138:139], 0, s[42:43]
	ds_read_b128 v[160:163], v142 offset:49152
	ds_read_b128 v[164:167], v142 offset:50176
	ds_read_b128 v[190:193], v142 offset:51200
	ds_read_b128 v[194:197], v142 offset:52224
	ds_read_b128 v[198:201], v142 offset:53248
	ds_read_b128 v[202:205], v142 offset:54272
	ds_read_b128 v[206:209], v142 offset:55296
	ds_read_b128 v[210:213], v142 offset:56320
	global_load_lds_dwordx4 v[138:139], off
	v_lshl_add_u64 v[138:139], v[230:231], 0, s[42:43]
	s_mov_b32 m0, s30
	s_nop 0
	global_load_lds_dwordx4 v[138:139], off
	s_barrier
;     __device__ __forceinline__ unsigned* BAR() const { return (unsigned*)(ws + OFF_BAR); }
; #define STAGE(bufoff, gbase, voff) do { _Pragma("unroll") for (int _i = 0; _i < 2; ++_i) \
;         __builtin_amdgcn_global_load_lds((const unsigned*)((const char*)(gbase) + voff[_i]), (LAS unsigned*)(lds + (bufoff) + ldsw + _i * 8192), 16, 0, 0); } while (0)
; #define LDA(dst, b, h) do { _Pragma("unroll") for (int m = 0; m < 4; ++m) _Pragma("unroll") for (int k = 0; k < 2; ++k) dst[m][k] = *(const LAS bf16x8*)(lds + SA(b, h) + aoff + m * 2048 + k * 1024); } while (0)
; #define LDB(dst, b, h) do { _Pragma("unroll") for (int n = 0; n < 2; ++n) _Pragma("unroll") for (int k = 0; k < 2; ++k) dst[n][k] = *(const LAS bf16x8*)(lds + SB(b, h) + boff + n * 2048 + k * 1024); } while (0)
; #define MMA(ai, bj, At, Bx) do { __builtin_amdgcn_s_setprio(1); _Pragma("unroll") for (int m = 0; m < 4; ++m) _Pragma("unroll") for (int n = 0; n < 2; ++n) _Pragma("unroll") for (int k = 0; k < 2; ++k) \
;       acc[ai][bj][m][n] = __builtin_amdgcn_mfma_f32_16x16x32_bf16(At[m][k], Bx[n][k], acc[ai][bj][m][n], 0, 0, 0); \
;     __builtin_amdgcn_s_setprio(0); } while (0)
; #define WAIT_V(n) asm volatile("s_waitcnt vmcnt(" #n ")" ::: "memory")
; #define WAIT_L(n) asm volatile("s_waitcnt lgkmcnt(" #n ")" ::: "memory")
; #define BAR __builtin_amdgcn_s_barrier()
; #define SCHED __builtin_amdgcn_sched_barrier(0)
;     ...
;         LDB(B1, 1, 1); STAGE(SB(1, 0), b3, voffB);
;         BAR; WAIT_L(0); MMA(0, 1, At, B1); BAR;
;         LDA(At, 1, 1); STAGE(SA(1, 0), a3, voffA);
;         BAR; WAIT_L(0); MMA(1, 0, At, B0); BAR; SCHED;
;         STAGE(SB(1, 1), b3 + hstepB, voffB);
;         WAIT_V(6); BAR; MMA(1, 1, At, B1); BAR;
;     }
;     { LDB(B0, 0, 0); LDA(At, 0, 0); STAGE(SA(1, 1), pA(nt - 1) + hstepA, voffA);
;       BAR; WAIT_L(0); MMA(0, 0, At, B0); BAR;
;       LDB(B1, 0, 1); BAR; WAIT_L(0); MMA(0, 1, At, B1); BAR;
;       LDA(At, 0, 1); WAIT_V(4); BAR; WAIT_L(0); MMA(1, 0, At, B0); MMA(1, 1, At, B1); BAR; }
	s_waitcnt lgkmcnt(0)
	v_mfma_f32_16x16x32_bf16 v[62:65], v[160:163], v[144:147], v[62:65]
	v_mfma_f32_16x16x32_bf16 v[58:61], v[160:163], v[152:155], v[58:61]
	v_mfma_f32_16x16x32_bf16 v[54:57], v[190:193], v[144:147], v[54:57]
	v_mfma_f32_16x16x32_bf16 v[50:53], v[190:193], v[152:155], v[50:53]
	v_mfma_f32_16x16x32_bf16 v[46:49], v[198:201], v[144:147], v[46:49]
	v_mfma_f32_16x16x32_bf16 v[42:45], v[198:201], v[152:155], v[42:45]
	v_mfma_f32_16x16x32_bf16 v[38:41], v[206:209], v[144:147], v[38:41]
	v_mfma_f32_16x16x32_bf16 v[34:37], v[206:209], v[152:155], v[34:37]
	v_mfma_f32_16x16x32_bf16 v[62:65], v[164:167], v[148:151], v[62:65]
	v_mfma_f32_16x16x32_bf16 v[58:61], v[164:167], v[156:159], v[58:61]
	v_mfma_f32_16x16x32_bf16 v[54:57], v[194:197], v[148:151], v[54:57]
	v_mfma_f32_16x16x32_bf16 v[50:53], v[194:197], v[156:159], v[50:53]
	v_mfma_f32_16x16x32_bf16 v[46:49], v[202:205], v[148:151], v[46:49]
	v_mfma_f32_16x16x32_bf16 v[42:45], v[202:205], v[156:159], v[42:45]
	v_mfma_f32_16x16x32_bf16 v[38:41], v[210:213], v[148:151], v[38:41]
	v_mfma_f32_16x16x32_bf16 v[34:37], v[210:213], v[156:159], v[34:37]
	s_barrier
	s_add_i32 s9, s16, s11
	v_lshl_add_u64 v[138:139], v[232:233], 0, s[50:51]
	s_mov_b32 m0, s9
	s_nop 0
	global_load_lds_dwordx4 v[138:139], off
	v_lshl_add_u64 v[138:139], v[234:235], 0, s[50:51]
	s_add_i32 m0, s9, 0x2000
	s_nop 0
	global_load_lds_dwordx4 v[138:139], off
	s_waitcnt vmcnt(6)
	s_barrier
	v_mfma_f32_16x16x32_bf16 v[30:33], v[160:163], v[214:217], v[30:33]
	v_mfma_f32_16x16x32_bf16 v[26:29], v[160:163], v[222:225], v[26:29]
	v_mfma_f32_16x16x32_bf16 v[22:25], v[190:193], v[214:217], v[22:25]
	v_mfma_f32_16x16x32_bf16 v[18:21], v[190:193], v[222:225], v[18:21]
	v_mfma_f32_16x16x32_bf16 v[14:17], v[198:201], v[214:217], v[14:17]
	v_mfma_f32_16x16x32_bf16 v[10:13], v[198:201], v[222:225], v[10:13]
	v_mfma_f32_16x16x32_bf16 v[6:9], v[206:209], v[214:217], v[6:9]
	v_mfma_f32_16x16x32_bf16 v[2:5], v[206:209], v[222:225], v[2:5]
	v_mfma_f32_16x16x32_bf16 v[30:33], v[164:167], v[218:221], v[30:33]
	v_mfma_f32_16x16x32_bf16 v[26:29], v[164:167], v[226:229], v[26:29]
	v_mfma_f32_16x16x32_bf16 v[22:25], v[194:197], v[218:221], v[22:25]
	v_mfma_f32_16x16x32_bf16 v[18:21], v[194:197], v[226:229], v[18:21]
	v_mfma_f32_16x16x32_bf16 v[14:17], v[202:205], v[218:221], v[14:17]
	v_mfma_f32_16x16x32_bf16 v[10:13], v[202:205], v[226:229], v[10:13]
	v_mfma_f32_16x16x32_bf16 v[6:9], v[210:213], v[218:221], v[6:9]
	v_mfma_f32_16x16x32_bf16 v[2:5], v[210:213], v[226:229], v[2:5]
	s_barrier
	s_add_i32 s6, s6, 2
	s_add_u32 s4, s4, 0x100
	s_addc_u32 s5, s5, 0
	s_cmp_gt_u32 s6, 11
	s_cbranch_scc0 .LBB0_227
	v_add_u32_e32 v138, 0, v143
	s_add_u32 s0, s0, 0x40780
	v_add_u32_e32 v136, 0x10000, v138
	s_addc_u32 s1, s1, 0
	s_mov_b32 m0, s8
	ds_read_b128 v[132:135], v136
	ds_read_b128 v[144:147], v136 offset:1024
	ds_read_b128 v[148:151], v136 offset:2048
	ds_read_b128 v[152:155], v136 offset:3072
	ds_read_b128 v[156:159], v142
	ds_read_b128 v[160:163], v142 offset:1024
	ds_read_b128 v[164:167], v142 offset:2048
	ds_read_b128 v[190:193], v142 offset:3072
	ds_read_b128 v[194:197], v142 offset:4096
	ds_read_b128 v[198:201], v142 offset:5120
	ds_read_b128 v[202:205], v142 offset:6144
	ds_read_b128 v[206:209], v142 offset:7168
	v_lshl_add_u64 v[136:137], s[0:1], 0, v[0:1]
	global_load_lds_dwordx4 v[136:137], off
	v_lshl_add_u64 v[130:131], s[0:1], 0, v[130:131]
	s_mov_b32 m0, s7
	s_nop 0
	global_load_lds_dwordx4 v[130:131], off
	s_barrier
	s_waitcnt lgkmcnt(0)
	v_mfma_f32_16x16x32_bf16 v[126:129], v[156:159], v[132:135], v[126:129]
	v_mfma_f32_16x16x32_bf16 v[122:125], v[156:159], v[148:151], v[122:125]
	v_mfma_f32_16x16x32_bf16 v[118:121], v[164:167], v[132:135], v[118:121]
	v_mfma_f32_16x16x32_bf16 v[114:117], v[164:167], v[148:151], v[114:117]
	v_mfma_f32_16x16x32_bf16 v[98:101], v[202:205], v[148:151], v[98:101]
	v_mfma_f32_16x16x32_bf16 v[126:129], v[160:163], v[144:147], v[126:129]
	v_mfma_f32_16x16x32_bf16 v[122:125], v[160:163], v[152:155], v[122:125]
	v_mfma_f32_16x16x32_bf16 v[118:121], v[190:193], v[144:147], v[118:121]
	v_mfma_f32_16x16x32_bf16 v[114:117], v[190:193], v[152:155], v[114:117]
	v_mfma_f32_16x16x32_bf16 v[110:113], v[194:197], v[132:135], v[110:113]
	v_mfma_f32_16x16x32_bf16 v[106:109], v[194:197], v[148:151], v[106:109]
	v_mfma_f32_16x16x32_bf16 v[102:105], v[202:205], v[132:135], v[102:105]
	v_mfma_f32_16x16x32_bf16 v[98:101], v[206:209], v[152:155], v[98:101]
	v_mfma_f32_16x16x32_bf16 v[210:213], v[198:201], v[144:147], v[110:113]
	v_mfma_f32_16x16x32_bf16 v[214:217], v[198:201], v[152:155], v[106:109]
	v_mfma_f32_16x16x32_bf16 v[218:221], v[206:209], v[144:147], v[102:105]
	v_add_u32_e32 v0, 0x14000, v138
	s_barrier
	s_nop 0
	ds_read_b128 v[102:105], v0
	ds_read_b128 v[106:109], v0 offset:1024
	ds_read_b128 v[110:113], v0 offset:2048
	ds_read_b128 v[222:225], v0 offset:3072
	s_barrier
	s_waitcnt lgkmcnt(0)
	v_mfma_f32_16x16x32_bf16 v[94:97], v[156:159], v[102:105], v[94:97]
	v_mfma_f32_16x16x32_bf16 v[90:93], v[156:159], v[110:113], v[90:93]
	v_mfma_f32_16x16x32_bf16 v[86:89], v[164:167], v[102:105], v[86:89]
	v_mfma_f32_16x16x32_bf16 v[82:85], v[164:167], v[110:113], v[82:85]
	v_mfma_f32_16x16x32_bf16 v[66:69], v[202:205], v[110:113], v[66:69]
	v_mfma_f32_16x16x32_bf16 v[94:97], v[160:163], v[106:109], v[94:97]
	v_mfma_f32_16x16x32_bf16 v[90:93], v[160:163], v[222:225], v[90:93]
	v_mfma_f32_16x16x32_bf16 v[86:89], v[190:193], v[106:109], v[86:89]
	v_mfma_f32_16x16x32_bf16 v[82:85], v[190:193], v[222:225], v[82:85]
	v_mfma_f32_16x16x32_bf16 v[78:81], v[194:197], v[102:105], v[78:81]
	v_mfma_f32_16x16x32_bf16 v[74:77], v[194:197], v[110:113], v[74:77]
	v_mfma_f32_16x16x32_bf16 v[70:73], v[202:205], v[102:105], v[70:73]
	v_mfma_f32_16x16x32_bf16 v[66:69], v[206:209], v[222:225], v[66:69]
	v_mfma_f32_16x16x32_bf16 v[156:159], v[198:201], v[106:109], v[78:81]
	v_mfma_f32_16x16x32_bf16 v[160:163], v[198:201], v[222:225], v[74:77]
	v_mfma_f32_16x16x32_bf16 v[164:167], v[206:209], v[106:109], v[70:73]
	s_barrier
;     __device__ __forceinline__ unsigned* BAR() const { return (unsigned*)(ws + OFF_BAR); }
; #define LDA(dst, b, h) do { _Pragma("unroll") for (int m = 0; m < 4; ++m) _Pragma("unroll") for (int k = 0; k < 2; ++k) dst[m][k] = *(const LAS bf16x8*)(lds + SA(b, h) + aoff + m * 2048 + k * 1024); } while (0)
; #define LDB(dst, b, h) do { _Pragma("unroll") for (int n = 0; n < 2; ++n) _Pragma("unroll") for (int k = 0; k < 2; ++k) dst[n][k] = *(const LAS bf16x8*)(lds + SB(b, h) + boff + n * 2048 + k * 1024); } while (0)
; #define MMA(ai, bj, At, Bx) do { __builtin_amdgcn_s_setprio(1); _Pragma("unroll") for (int m = 0; m < 4; ++m) _Pragma("unroll") for (int n = 0; n < 2; ++n) _Pragma("unroll") for (int k = 0; k < 2; ++k) \
;       acc[ai][bj][m][n] = __builtin_amdgcn_mfma_f32_16x16x32_bf16(At[m][k], Bx[n][k], acc[ai][bj][m][n], 0, 0, 0); \
;     __builtin_amdgcn_s_setprio(0); } while (0)
; #define WAIT_V(n) asm volatile("s_waitcnt vmcnt(" #n ")" ::: "memory")
; #define WAIT_L(n) asm volatile("s_waitcnt lgkmcnt(" #n ")" ::: "memory")
; #define BAR __builtin_amdgcn_s_barrier()
;     ...
;       LDA(At, 0, 1); WAIT_V(4); BAR; WAIT_L(0); MMA(1, 0, At, B0); MMA(1, 1, At, B1); BAR; }
;     { LDB(B0, 1, 0); LDA(At, 1, 0); WAIT_V(2); BAR; WAIT_L(0); MMA(0, 0, At, B0); BAR;
;       LDB(B1, 1, 1); WAIT_V(0); BAR; WAIT_L(0); MMA(0, 1, At, B1); BAR;
;       LDA(At, 1, 1); BAR; WAIT_L(0); MMA(1, 0, At, B0); MMA(1, 1, At, B1); BAR; }
	s_nop 1
	ds_read_b128 v[70:73], v142 offset:16384
	ds_read_b128 v[74:77], v142 offset:17408
	ds_read_b128 v[78:81], v142 offset:18432
	ds_read_b128 v[190:193], v142 offset:19456
	ds_read_b128 v[194:197], v142 offset:20480
	ds_read_b128 v[198:201], v142 offset:21504
	ds_read_b128 v[202:205], v142 offset:22528
	ds_read_b128 v[206:209], v142 offset:23552
	s_waitcnt vmcnt(4)
	s_barrier
	s_waitcnt lgkmcnt(0)
	v_mfma_f32_16x16x32_bf16 v[62:65], v[70:73], v[132:135], v[62:65]
	v_mfma_f32_16x16x32_bf16 v[58:61], v[70:73], v[148:151], v[58:61]
	v_mfma_f32_16x16x32_bf16 v[54:57], v[78:81], v[132:135], v[54:57]
	v_mfma_f32_16x16x32_bf16 v[50:53], v[78:81], v[148:151], v[50:53]
	v_mfma_f32_16x16x32_bf16 v[34:37], v[202:205], v[148:151], v[34:37]
	v_mfma_f32_16x16x32_bf16 v[62:65], v[74:77], v[144:147], v[62:65]
	v_mfma_f32_16x16x32_bf16 v[58:61], v[74:77], v[152:155], v[58:61]
	v_mfma_f32_16x16x32_bf16 v[54:57], v[190:193], v[144:147], v[54:57]
	v_mfma_f32_16x16x32_bf16 v[50:53], v[190:193], v[152:155], v[50:53]
	v_mfma_f32_16x16x32_bf16 v[46:49], v[194:197], v[132:135], v[46:49]
	v_mfma_f32_16x16x32_bf16 v[42:45], v[194:197], v[148:151], v[42:45]
	v_mfma_f32_16x16x32_bf16 v[38:41], v[202:205], v[132:135], v[38:41]
	v_mfma_f32_16x16x32_bf16 v[34:37], v[206:209], v[152:155], v[34:37]
	v_mfma_f32_16x16x32_bf16 v[226:229], v[198:201], v[144:147], v[46:49]
	v_mfma_f32_16x16x32_bf16 v[230:233], v[198:201], v[152:155], v[42:45]
	v_mfma_f32_16x16x32_bf16 v[130:133], v[206:209], v[144:147], v[38:41]
	v_mfma_f32_16x16x32_bf16 v[30:33], v[70:73], v[102:105], v[30:33]
	v_mfma_f32_16x16x32_bf16 v[26:29], v[70:73], v[110:113], v[26:29]
	v_mfma_f32_16x16x32_bf16 v[22:25], v[78:81], v[102:105], v[22:25]
	v_mfma_f32_16x16x32_bf16 v[18:21], v[78:81], v[110:113], v[18:21]
	v_mfma_f32_16x16x32_bf16 v[2:5], v[202:205], v[110:113], v[2:5]
	v_mfma_f32_16x16x32_bf16 v[30:33], v[74:77], v[106:109], v[30:33]
	v_mfma_f32_16x16x32_bf16 v[26:29], v[74:77], v[222:225], v[26:29]
	v_mfma_f32_16x16x32_bf16 v[22:25], v[190:193], v[106:109], v[22:25]
	v_mfma_f32_16x16x32_bf16 v[18:21], v[190:193], v[222:225], v[18:21]
	v_mfma_f32_16x16x32_bf16 v[14:17], v[194:197], v[102:105], v[14:17]
	v_mfma_f32_16x16x32_bf16 v[10:13], v[194:197], v[110:113], v[10:13]
	v_mfma_f32_16x16x32_bf16 v[6:9], v[202:205], v[102:105], v[6:9]
	v_mfma_f32_16x16x32_bf16 v[2:5], v[206:209], v[222:225], v[2:5]
	v_mfma_f32_16x16x32_bf16 v[134:137], v[198:201], v[106:109], v[14:17]
	v_mfma_f32_16x16x32_bf16 v[144:147], v[198:201], v[222:225], v[10:13]
	v_mfma_f32_16x16x32_bf16 v[148:151], v[206:209], v[106:109], v[6:9]
	v_add_u32_e32 v0, 0x18000, v138
	s_barrier
	s_nop 0
	ds_read_b128 v[6:9], v0
	ds_read_b128 v[10:13], v0 offset:1024
	ds_read_b128 v[14:17], v0 offset:2048
	ds_read_b128 v[152:155], v0 offset:3072
	ds_read_b128 v[38:41], v142 offset:32768
	ds_read_b128 v[42:45], v142 offset:33792
	ds_read_b128 v[46:49], v142 offset:34816
	ds_read_b128 v[70:73], v142 offset:35840
	ds_read_b128 v[190:193], v142 offset:36864
	ds_read_b128 v[194:197], v142 offset:37888
	ds_read_b128 v[198:201], v142 offset:38912
	ds_read_b128 v[202:205], v142 offset:39936
	s_waitcnt vmcnt(2)
	s_barrier
	s_waitcnt lgkmcnt(0)
	v_mfma_f32_16x16x32_bf16 v[74:77], v[38:41], v[6:9], v[126:129]
	v_mfma_f32_16x16x32_bf16 v[126:129], v[42:45], v[10:13], v[74:77]
	v_mfma_f32_16x16x32_bf16 v[74:77], v[38:41], v[14:17], v[122:125]
	v_mfma_f32_16x16x32_bf16 v[110:113], v[42:45], v[152:155], v[74:77]
	v_mfma_f32_16x16x32_bf16 v[74:77], v[46:49], v[6:9], v[118:121]
	v_mfma_f32_16x16x32_bf16 v[122:125], v[70:73], v[10:13], v[74:77]
	v_mfma_f32_16x16x32_bf16 v[74:77], v[46:49], v[14:17], v[114:117]
	v_mfma_f32_16x16x32_bf16 v[106:109], v[70:73], v[152:155], v[74:77]
	v_mfma_f32_16x16x32_bf16 v[74:77], v[190:193], v[6:9], v[210:213]
	v_mfma_f32_16x16x32_bf16 v[118:121], v[194:197], v[10:13], v[74:77]
	v_mfma_f32_16x16x32_bf16 v[74:77], v[190:193], v[14:17], v[214:217]
	v_mfma_f32_16x16x32_bf16 v[102:105], v[194:197], v[152:155], v[74:77]
	v_mfma_f32_16x16x32_bf16 v[74:77], v[198:201], v[6:9], v[218:221]
	v_mfma_f32_16x16x32_bf16 v[114:117], v[202:205], v[10:13], v[74:77]
	v_mfma_f32_16x16x32_bf16 v[74:77], v[198:201], v[14:17], v[98:101]
	v_mfma_f32_16x16x32_bf16 v[98:101], v[202:205], v[152:155], v[74:77]
	v_add_u32_e32 v0, 0x1c000, v138
	s_barrier
;     __device__ __forceinline__ unsigned* BAR() const { return (unsigned*)(ws + OFF_BAR); }
; #define LDA(dst, b, h) do { _Pragma("unroll") for (int m = 0; m < 4; ++m) _Pragma("unroll") for (int k = 0; k < 2; ++k) dst[m][k] = *(const LAS bf16x8*)(lds + SA(b, h) + aoff + m * 2048 + k * 1024); } while (0)
; #define LDB(dst, b, h) do { _Pragma("unroll") for (int n = 0; n < 2; ++n) _Pragma("unroll") for (int k = 0; k < 2; ++k) dst[n][k] = *(const LAS bf16x8*)(lds + SB(b, h) + boff + n * 2048 + k * 1024); } while (0)
; #define MMA(ai, bj, At, Bx) do { __builtin_amdgcn_s_setprio(1); _Pragma("unroll") for (int m = 0; m < 4; ++m) _Pragma("unroll") for (int n = 0; n < 2; ++n) _Pragma("unroll") for (int k = 0; k < 2; ++k) \
;       acc[ai][bj][m][n] = __builtin_amdgcn_mfma_f32_16x16x32_bf16(At[m][k], Bx[n][k], acc[ai][bj][m][n], 0, 0, 0); \
;     __builtin_amdgcn_s_setprio(0); } while (0)
; #define WAIT_V(n) asm volatile("s_waitcnt vmcnt(" #n ")" ::: "memory")
; #define WAIT_L(n) asm volatile("s_waitcnt lgkmcnt(" #n ")" ::: "memory")
; #define BAR __builtin_amdgcn_s_barrier()
;     ...
;     { LDB(B0, 1, 0); LDA(At, 1, 0); WAIT_V(2); BAR; WAIT_L(0); MMA(0, 0, At, B0); BAR;
;       LDB(B1, 1, 1); WAIT_V(0); BAR; WAIT_L(0); MMA(0, 1, At, B1); BAR;
;       LDA(At, 1, 1); BAR; WAIT_L(0); MMA(1, 0, At, B0); MMA(1, 1, At, B1); BAR; }
;     if (wr == 0) BAR;
	ds_read_b128 v[206:209], v0
	ds_read_b128 v[210:213], v0 offset:1024
	ds_read_b128 v[214:217], v0 offset:2048
	ds_read_b128 v[218:221], v0 offset:3072
	s_waitcnt vmcnt(0)
	s_barrier
	s_waitcnt lgkmcnt(0)
	v_mfma_f32_16x16x32_bf16 v[74:77], v[38:41], v[206:209], v[94:97]
	v_mfma_f32_16x16x32_bf16 v[38:41], v[38:41], v[214:217], v[90:93]
	v_mfma_f32_16x16x32_bf16 v[78:81], v[42:45], v[218:221], v[38:41]
	v_mfma_f32_16x16x32_bf16 v[38:41], v[46:49], v[206:209], v[86:89]
	v_mfma_f32_16x16x32_bf16 v[90:93], v[70:73], v[210:213], v[38:41]
	v_mfma_f32_16x16x32_bf16 v[38:41], v[46:49], v[214:217], v[82:85]
	v_mfma_f32_16x16x32_bf16 v[94:97], v[42:45], v[210:213], v[74:77]
	v_mfma_f32_16x16x32_bf16 v[74:77], v[70:73], v[218:221], v[38:41]
	v_mfma_f32_16x16x32_bf16 v[38:41], v[190:193], v[206:209], v[156:159]
	v_mfma_f32_16x16x32_bf16 v[86:89], v[194:197], v[210:213], v[38:41]
	v_mfma_f32_16x16x32_bf16 v[38:41], v[190:193], v[214:217], v[160:163]
	v_mfma_f32_16x16x32_bf16 v[70:73], v[194:197], v[218:221], v[38:41]
	v_mfma_f32_16x16x32_bf16 v[38:41], v[198:201], v[206:209], v[164:167]
	v_mfma_f32_16x16x32_bf16 v[82:85], v[202:205], v[210:213], v[38:41]
	v_mfma_f32_16x16x32_bf16 v[38:41], v[198:201], v[214:217], v[66:69]
	v_mfma_f32_16x16x32_bf16 v[66:69], v[202:205], v[218:221], v[38:41]
	s_barrier
	ds_read_b128 v[156:159], v142 offset:49152
	ds_read_b128 v[160:163], v142 offset:50176
	ds_read_b128 v[164:167], v142 offset:51200
	ds_read_b128 v[190:193], v142 offset:52224
	ds_read_b128 v[194:197], v142 offset:53248
	ds_read_b128 v[198:201], v142 offset:54272
	ds_read_b128 v[202:205], v142 offset:55296
	ds_read_b128 v[140:143], v142 offset:56320
	s_barrier
	s_waitcnt lgkmcnt(0)
	v_mfma_f32_16x16x32_bf16 v[38:41], v[156:159], v[6:9], v[62:65]
	v_mfma_f32_16x16x32_bf16 v[62:65], v[160:163], v[10:13], v[38:41]
	v_mfma_f32_16x16x32_bf16 v[38:41], v[156:159], v[14:17], v[58:61]
	v_mfma_f32_16x16x32_bf16 v[46:49], v[160:163], v[152:155], v[38:41]
	v_mfma_f32_16x16x32_bf16 v[38:41], v[164:167], v[6:9], v[54:57]
	v_mfma_f32_16x16x32_bf16 v[58:61], v[190:193], v[10:13], v[38:41]
	v_mfma_f32_16x16x32_bf16 v[38:41], v[164:167], v[14:17], v[50:53]
	v_mfma_f32_16x16x32_bf16 v[42:45], v[190:193], v[152:155], v[38:41]
	v_mfma_f32_16x16x32_bf16 v[38:41], v[194:197], v[6:9], v[226:229]
	v_mfma_f32_16x16x32_bf16 v[6:9], v[202:205], v[6:9], v[130:133]
	v_mfma_f32_16x16x32_bf16 v[54:57], v[198:201], v[10:13], v[38:41]
	v_mfma_f32_16x16x32_bf16 v[38:41], v[194:197], v[14:17], v[230:233]
	v_mfma_f32_16x16x32_bf16 v[50:53], v[140:143], v[10:13], v[6:9]
	v_mfma_f32_16x16x32_bf16 v[6:9], v[202:205], v[14:17], v[34:37]
	v_mfma_f32_16x16x32_bf16 v[38:41], v[198:201], v[152:155], v[38:41]
	v_mfma_f32_16x16x32_bf16 v[34:37], v[140:143], v[152:155], v[6:9]
	v_mfma_f32_16x16x32_bf16 v[6:9], v[156:159], v[206:209], v[30:33]
	v_mfma_f32_16x16x32_bf16 v[30:33], v[160:163], v[210:213], v[6:9]
	v_mfma_f32_16x16x32_bf16 v[6:9], v[156:159], v[214:217], v[26:29]
	v_mfma_f32_16x16x32_bf16 v[14:17], v[160:163], v[218:221], v[6:9]
	v_mfma_f32_16x16x32_bf16 v[6:9], v[164:167], v[206:209], v[22:25]
	v_mfma_f32_16x16x32_bf16 v[26:29], v[190:193], v[210:213], v[6:9]
	v_mfma_f32_16x16x32_bf16 v[6:9], v[164:167], v[214:217], v[18:21]
	v_mfma_f32_16x16x32_bf16 v[10:13], v[190:193], v[218:221], v[6:9]
	v_mfma_f32_16x16x32_bf16 v[6:9], v[194:197], v[206:209], v[134:137]
	v_mfma_f32_16x16x32_bf16 v[22:25], v[198:201], v[210:213], v[6:9]
	v_mfma_f32_16x16x32_bf16 v[6:9], v[194:197], v[214:217], v[144:147]
	v_mfma_f32_16x16x32_bf16 v[18:21], v[202:205], v[206:209], v[148:151]
	v_mfma_f32_16x16x32_bf16 v[2:5], v[202:205], v[214:217], v[2:5]
	v_mfma_f32_16x16x32_bf16 v[6:9], v[198:201], v[218:221], v[6:9]
	v_mfma_f32_16x16x32_bf16 v[18:21], v[140:143], v[210:213], v[18:21]
	v_mfma_f32_16x16x32_bf16 v[2:5], v[140:143], v[218:221], v[2:5]
	s_cmpk_lt_u32 s10, 0x100
	s_barrier
	s_cbranch_scc0 .LBB0_230
	s_barrier

;     __device__ __forceinline__ unsigned* BAR() const { return (unsigned*)(ws + OFF_BAR); }
; #define STAGE(bufoff, gbase, voff) do { _Pragma("unroll") for (int _i = 0; _i < 2; ++_i) \
;         __builtin_amdgcn_global_load_lds((const unsigned*)((const char*)(gbase) + voff[_i]), (LAS unsigned*)(lds + (bufoff) + ldsw + _i * 8192), 16, 0, 0); } while (0)
; #define LDA(dst, b, h) do { _Pragma("unroll") for (int m = 0; m < 4; ++m) _Pragma("unroll") for (int k = 0; k < 2; ++k) dst[m][k] = *(const LAS bf16x8*)(lds + SA(b, h) + aoff + m * 2048 + k * 1024); } while (0)
; #define LDB(dst, b, h) do { _Pragma("unroll") for (int n = 0; n < 2; ++n) _Pragma("unroll") for (int k = 0; k < 2; ++k) dst[n][k] = *(const LAS bf16x8*)(lds + SB(b, h) + boff + n * 2048 + k * 1024); } while (0)
; #define MMA(ai, bj, At, Bx) do { __builtin_amdgcn_s_setprio(1); _Pragma("unroll") for (int m = 0; m < 4; ++m) _Pragma("unroll") for (int n = 0; n < 2; ++n) _Pragma("unroll") for (int k = 0; k < 2; ++k) \
;       acc[ai][bj][m][n] = __builtin_amdgcn_mfma_f32_16x16x32_bf16(At[m][k], Bx[n][k], acc[ai][bj][m][n], 0, 0, 0); \
;     __builtin_amdgcn_s_setprio(0); } while (0)
; #define WAIT_L(n) asm volatile("s_waitcnt lgkmcnt(" #n ")" ::: "memory")
; #define BAR __builtin_amdgcn_s_barrier()
; #define SCHED __builtin_amdgcn_sched_barrier(0)
;     ...
;     for (int t = 0; t < nt - 2; t += 2) {
;         if (KSEG && t > 0 && (t % (KSEG ? KSEG : 1)) == 0) hook(t / (KSEG ? KSEG : 1), acc);
;         const char* a1 = pA(t + 1); const char* a2 = pA(t + 2); const char* a3 = pA(t + 3);
;         const char* b2 = pB(t + 2); const char* b3 = pB(t + 3);
;         LDB(B0, 0, 0); SCHED; LDA(At, 0, 0); STAGE(SA(1, 1), a1 + hstepA, voffA);
;         WAIT_L(8); BAR; WAIT_L(0); MMA(0, 0, At, B0); BAR; SCHED;
;         LDB(B1, 0, 1); STAGE(SB(0, 0), b2, voffB);
;         BAR; WAIT_L(0); MMA(0, 1, At, B1); BAR;
;         LDA(At, 0, 1); STAGE(SA(0, 0), a2, voffA);
.LBB0_377:
	s_add_i32 s9, 0, 0x10000
	v_add_u32_e32 v138, s9, v143
	ds_read_b128 v[144:147], v138
	ds_read_b128 v[148:151], v138 offset:1024
	ds_read_b128 v[152:155], v138 offset:2048
	ds_read_b128 v[156:159], v138 offset:3072
	v_lshl_add_u64 v[138:139], s[20:21], 0, v[136:137]
	s_add_i32 s8, s13, 0xc000
	v_lshl_add_u64 v[214:215], v[138:139], 0, s[54:55]
	s_mov_b32 m0, s8
	v_lshl_add_u64 v[230:231], s[20:21], 0, v[140:141]
	s_add_i32 s7, s13, 0xe000
	ds_read_b128 v[160:163], v142
	ds_read_b128 v[164:167], v142 offset:1024
	ds_read_b128 v[190:193], v142 offset:2048
	ds_read_b128 v[194:197], v142 offset:3072
	ds_read_b128 v[198:201], v142 offset:4096
	ds_read_b128 v[202:205], v142 offset:5120
	ds_read_b128 v[206:209], v142 offset:6144
	ds_read_b128 v[210:213], v142 offset:7168
	global_load_lds_dwordx4 v[214:215], off
	v_lshl_add_u64 v[214:215], v[230:231], 0, s[54:55]
	s_mov_b32 m0, s7
	s_nop 0
	global_load_lds_dwordx4 v[214:215], off
	s_waitcnt lgkmcnt(8)
	s_barrier
	s_waitcnt lgkmcnt(0)
	v_mfma_f32_16x16x32_bf16 v[126:129], v[160:163], v[144:147], v[126:129]
	v_mfma_f32_16x16x32_bf16 v[122:125], v[160:163], v[152:155], v[122:125]
	v_mfma_f32_16x16x32_bf16 v[118:121], v[190:193], v[144:147], v[118:121]
	v_mfma_f32_16x16x32_bf16 v[114:117], v[190:193], v[152:155], v[114:117]
	v_mfma_f32_16x16x32_bf16 v[110:113], v[198:201], v[144:147], v[110:113]
	v_mfma_f32_16x16x32_bf16 v[106:109], v[198:201], v[152:155], v[106:109]
	v_mfma_f32_16x16x32_bf16 v[102:105], v[206:209], v[144:147], v[102:105]
	v_mfma_f32_16x16x32_bf16 v[98:101], v[206:209], v[152:155], v[98:101]
	v_mfma_f32_16x16x32_bf16 v[126:129], v[164:167], v[148:151], v[126:129]
	v_mfma_f32_16x16x32_bf16 v[122:125], v[164:167], v[156:159], v[122:125]
	v_mfma_f32_16x16x32_bf16 v[118:121], v[194:197], v[148:151], v[118:121]
	v_mfma_f32_16x16x32_bf16 v[114:117], v[194:197], v[156:159], v[114:117]
	v_mfma_f32_16x16x32_bf16 v[110:113], v[202:205], v[148:151], v[110:113]
	v_mfma_f32_16x16x32_bf16 v[106:109], v[202:205], v[156:159], v[106:109]
	v_mfma_f32_16x16x32_bf16 v[102:105], v[210:213], v[148:151], v[102:105]
	v_mfma_f32_16x16x32_bf16 v[98:101], v[210:213], v[156:159], v[98:101]
	s_barrier
	s_add_i32 s10, 0, 0x14000
	v_lshl_add_u64 v[232:233], s[20:21], 0, v[132:133]
	s_add_i32 s9, s9, s1
	v_add_u32_e32 v226, s10, v143
	v_lshl_add_u64 v[234:235], v[232:233], 0, s[40:41]
	s_mov_b32 m0, s9
	ds_read_b128 v[214:217], v226
	ds_read_b128 v[218:221], v226 offset:1024
	ds_read_b128 v[222:225], v226 offset:2048
	ds_read_b128 v[226:229], v226 offset:3072
	global_load_lds_dwordx4 v[234:235], off
	v_lshl_add_u64 v[234:235], s[20:21], 0, v[134:135]
	v_lshl_add_u64 v[236:237], v[234:235], 0, s[40:41]
	s_add_i32 m0, s9, 0x2000
	s_nop 0
	global_load_lds_dwordx4 v[236:237], off
	s_barrier
	s_waitcnt lgkmcnt(0)
	v_mfma_f32_16x16x32_bf16 v[94:97], v[160:163], v[214:217], v[94:97]
	v_mfma_f32_16x16x32_bf16 v[90:93], v[160:163], v[222:225], v[90:93]
	v_mfma_f32_16x16x32_bf16 v[86:89], v[190:193], v[214:217], v[86:89]
	v_mfma_f32_16x16x32_bf16 v[82:85], v[190:193], v[222:225], v[82:85]
	v_mfma_f32_16x16x32_bf16 v[78:81], v[198:201], v[214:217], v[78:81]
	v_mfma_f32_16x16x32_bf16 v[74:77], v[198:201], v[222:225], v[74:77]
	v_mfma_f32_16x16x32_bf16 v[70:73], v[206:209], v[214:217], v[70:73]
	v_mfma_f32_16x16x32_bf16 v[66:69], v[206:209], v[222:225], v[66:69]
	v_mfma_f32_16x16x32_bf16 v[94:97], v[164:167], v[218:221], v[94:97]
	v_mfma_f32_16x16x32_bf16 v[90:93], v[164:167], v[226:229], v[90:93]
	v_mfma_f32_16x16x32_bf16 v[86:89], v[194:197], v[218:221], v[86:89]
	v_mfma_f32_16x16x32_bf16 v[82:85], v[194:197], v[226:229], v[82:85]
	v_mfma_f32_16x16x32_bf16 v[78:81], v[202:205], v[218:221], v[78:81]
	v_mfma_f32_16x16x32_bf16 v[74:77], v[202:205], v[226:229], v[74:77]
	v_mfma_f32_16x16x32_bf16 v[70:73], v[210:213], v[218:221], v[70:73]
	v_mfma_f32_16x16x32_bf16 v[66:69], v[210:213], v[226:229], v[66:69]
	s_barrier
	s_mov_b32 m0, s13
	v_lshl_add_u64 v[236:237], v[138:139], 0, s[38:39]
	ds_read_b128 v[160:163], v142 offset:16384
	ds_read_b128 v[164:167], v142 offset:17408
	ds_read_b128 v[190:193], v142 offset:18432
	ds_read_b128 v[194:197], v142 offset:19456
	ds_read_b128 v[198:201], v142 offset:20480
	ds_read_b128 v[202:205], v142 offset:21504
	ds_read_b128 v[206:209], v142 offset:22528
	ds_read_b128 v[210:213], v142 offset:23552
	global_load_lds_dwordx4 v[236:237], off
	v_lshl_add_u64 v[236:237], v[230:231], 0, s[38:39]
	s_mov_b32 m0, s14
	s_nop 0
	global_load_lds_dwordx4 v[236:237], off
	s_barrier
	s_waitcnt lgkmcnt(0)
	v_mfma_f32_16x16x32_bf16 v[62:65], v[160:163], v[144:147], v[62:65]
	v_mfma_f32_16x16x32_bf16 v[58:61], v[160:163], v[152:155], v[58:61]
	v_mfma_f32_16x16x32_bf16 v[54:57], v[190:193], v[144:147], v[54:57]
	v_mfma_f32_16x16x32_bf16 v[50:53], v[190:193], v[152:155], v[50:53]
	v_mfma_f32_16x16x32_bf16 v[46:49], v[198:201], v[144:147], v[46:49]
	v_mfma_f32_16x16x32_bf16 v[42:45], v[198:201], v[152:155], v[42:45]
	v_mfma_f32_16x16x32_bf16 v[38:41], v[206:209], v[144:147], v[38:41]
	v_mfma_f32_16x16x32_bf16 v[34:37], v[206:209], v[152:155], v[34:37]
	v_mfma_f32_16x16x32_bf16 v[62:65], v[164:167], v[148:151], v[62:65]
	v_mfma_f32_16x16x32_bf16 v[58:61], v[164:167], v[156:159], v[58:61]
	v_mfma_f32_16x16x32_bf16 v[54:57], v[194:197], v[148:151], v[54:57]
	v_mfma_f32_16x16x32_bf16 v[50:53], v[194:197], v[156:159], v[50:53]
	v_mfma_f32_16x16x32_bf16 v[46:49], v[202:205], v[148:151], v[46:49]
	v_mfma_f32_16x16x32_bf16 v[42:45], v[202:205], v[156:159], v[42:45]
	v_mfma_f32_16x16x32_bf16 v[38:41], v[210:213], v[148:151], v[38:41]
	v_mfma_f32_16x16x32_bf16 v[34:37], v[210:213], v[156:159], v[34:37]
	s_barrier
;     __device__ __forceinline__ unsigned* BAR() const { return (unsigned*)(ws + OFF_BAR); }
; #define STAGE(bufoff, gbase, voff) do { _Pragma("unroll") for (int _i = 0; _i < 2; ++_i) \
;         __builtin_amdgcn_global_load_lds((const unsigned*)((const char*)(gbase) + voff[_i]), (LAS unsigned*)(lds + (bufoff) + ldsw + _i * 8192), 16, 0, 0); } while (0)
; #define LDA(dst, b, h) do { _Pragma("unroll") for (int m = 0; m < 4; ++m) _Pragma("unroll") for (int k = 0; k < 2; ++k) dst[m][k] = *(const LAS bf16x8*)(lds + SA(b, h) + aoff + m * 2048 + k * 1024); } while (0)
; #define LDB(dst, b, h) do { _Pragma("unroll") for (int n = 0; n < 2; ++n) _Pragma("unroll") for (int k = 0; k < 2; ++k) dst[n][k] = *(const LAS bf16x8*)(lds + SB(b, h) + boff + n * 2048 + k * 1024); } while (0)
; #define MMA(ai, bj, At, Bx) do { __builtin_amdgcn_s_setprio(1); _Pragma("unroll") for (int m = 0; m < 4; ++m) _Pragma("unroll") for (int n = 0; n < 2; ++n) _Pragma("unroll") for (int k = 0; k < 2; ++k) \
;       acc[ai][bj][m][n] = __builtin_amdgcn_mfma_f32_16x16x32_bf16(At[m][k], Bx[n][k], acc[ai][bj][m][n], 0, 0, 0); \
;     __builtin_amdgcn_s_setprio(0); } while (0)
; #define WAIT_V(n) asm volatile("s_waitcnt vmcnt(" #n ")" ::: "memory")
; #define WAIT_L(n) asm volatile("s_waitcnt lgkmcnt(" #n ")" ::: "memory")
; #define BAR __builtin_amdgcn_s_barrier()
; #define SCHED __builtin_amdgcn_sched_barrier(0)
;     ...
;         BAR; WAIT_L(0); MMA(1, 0, At, B0); BAR; SCHED;
;         STAGE(SB(0, 1), b2 + hstepB, voffB);
;         WAIT_V(6); BAR; MMA(1, 1, At, B1); BAR;
;         LDB(B0, 1, 0); SCHED; LDA(At, 1, 0); STAGE(SA(0, 1), a2 + hstepA, voffA);
;         WAIT_L(8); BAR; WAIT_L(0); MMA(0, 0, At, B0); BAR; SCHED;
;         LDB(B1, 1, 1); STAGE(SB(1, 0), b3, voffB);
	s_add_i32 s9, s10, s1
	v_lshl_add_u64 v[144:145], v[232:233], 0, s[46:47]
	s_mov_b32 m0, s9
	s_nop 0
	global_load_lds_dwordx4 v[144:145], off
	v_lshl_add_u64 v[144:145], v[234:235], 0, s[46:47]
	s_add_i32 m0, s9, 0x2000
	s_nop 0
	global_load_lds_dwordx4 v[144:145], off
	s_waitcnt vmcnt(6)
	s_barrier
	v_mfma_f32_16x16x32_bf16 v[30:33], v[160:163], v[214:217], v[30:33]
	v_mfma_f32_16x16x32_bf16 v[26:29], v[160:163], v[222:225], v[26:29]
	v_mfma_f32_16x16x32_bf16 v[22:25], v[190:193], v[214:217], v[22:25]
	v_mfma_f32_16x16x32_bf16 v[18:21], v[190:193], v[222:225], v[18:21]
	v_mfma_f32_16x16x32_bf16 v[14:17], v[198:201], v[214:217], v[14:17]
	v_mfma_f32_16x16x32_bf16 v[10:13], v[198:201], v[222:225], v[10:13]
	v_mfma_f32_16x16x32_bf16 v[6:9], v[206:209], v[214:217], v[6:9]
	v_mfma_f32_16x16x32_bf16 v[2:5], v[206:209], v[222:225], v[2:5]
	v_mfma_f32_16x16x32_bf16 v[30:33], v[164:167], v[218:221], v[30:33]
	v_mfma_f32_16x16x32_bf16 v[26:29], v[164:167], v[226:229], v[26:29]
	v_mfma_f32_16x16x32_bf16 v[22:25], v[194:197], v[218:221], v[22:25]
	v_mfma_f32_16x16x32_bf16 v[18:21], v[194:197], v[226:229], v[18:21]
	v_mfma_f32_16x16x32_bf16 v[14:17], v[202:205], v[218:221], v[14:17]
	v_mfma_f32_16x16x32_bf16 v[10:13], v[202:205], v[226:229], v[10:13]
	v_mfma_f32_16x16x32_bf16 v[6:9], v[210:213], v[218:221], v[6:9]
	v_mfma_f32_16x16x32_bf16 v[2:5], v[210:213], v[226:229], v[2:5]
	s_barrier
	s_add_i32 s9, 0, 0x18000
	v_add_u32_e32 v156, s9, v143
	ds_read_b128 v[144:147], v156
	ds_read_b128 v[148:151], v156 offset:1024
	ds_read_b128 v[152:155], v156 offset:2048
	ds_read_b128 v[156:159], v156 offset:3072
	s_mov_b32 m0, s15
	v_lshl_add_u64 v[214:215], v[138:139], 0, s[44:45]
	ds_read_b128 v[160:163], v142 offset:32768
	ds_read_b128 v[164:167], v142 offset:33792
	ds_read_b128 v[190:193], v142 offset:34816
	ds_read_b128 v[194:197], v142 offset:35840
	ds_read_b128 v[198:201], v142 offset:36864
	ds_read_b128 v[202:205], v142 offset:37888
	ds_read_b128 v[206:209], v142 offset:38912
	ds_read_b128 v[210:213], v142 offset:39936
	global_load_lds_dwordx4 v[214:215], off
	v_lshl_add_u64 v[214:215], v[230:231], 0, s[44:45]
	s_mov_b32 m0, s30
	s_nop 0
	global_load_lds_dwordx4 v[214:215], off
	s_waitcnt lgkmcnt(8)
	s_barrier
	s_waitcnt lgkmcnt(0)
	v_mfma_f32_16x16x32_bf16 v[126:129], v[160:163], v[144:147], v[126:129]
	v_mfma_f32_16x16x32_bf16 v[122:125], v[160:163], v[152:155], v[122:125]
	v_mfma_f32_16x16x32_bf16 v[118:121], v[190:193], v[144:147], v[118:121]
	v_mfma_f32_16x16x32_bf16 v[114:117], v[190:193], v[152:155], v[114:117]
	v_mfma_f32_16x16x32_bf16 v[110:113], v[198:201], v[144:147], v[110:113]
	v_mfma_f32_16x16x32_bf16 v[106:109], v[198:201], v[152:155], v[106:109]
	v_mfma_f32_16x16x32_bf16 v[102:105], v[206:209], v[144:147], v[102:105]
	v_mfma_f32_16x16x32_bf16 v[98:101], v[206:209], v[152:155], v[98:101]
	v_mfma_f32_16x16x32_bf16 v[126:129], v[164:167], v[148:151], v[126:129]
	v_mfma_f32_16x16x32_bf16 v[122:125], v[164:167], v[156:159], v[122:125]
	v_mfma_f32_16x16x32_bf16 v[118:121], v[194:197], v[148:151], v[118:121]
	v_mfma_f32_16x16x32_bf16 v[114:117], v[194:197], v[156:159], v[114:117]
	v_mfma_f32_16x16x32_bf16 v[110:113], v[202:205], v[148:151], v[110:113]
	v_mfma_f32_16x16x32_bf16 v[106:109], v[202:205], v[156:159], v[106:109]
	v_mfma_f32_16x16x32_bf16 v[102:105], v[210:213], v[148:151], v[102:105]
	v_mfma_f32_16x16x32_bf16 v[98:101], v[210:213], v[156:159], v[98:101]
	s_barrier
	s_add_i32 s10, 0, 0x1c000
	s_add_i32 s9, s9, s1
	v_add_u32_e32 v226, s10, v143
	v_lshl_add_u64 v[236:237], v[232:233], 0, s[64:65]
	s_mov_b32 m0, s9
	ds_read_b128 v[214:217], v226
	ds_read_b128 v[218:221], v226 offset:1024
	ds_read_b128 v[222:225], v226 offset:2048
	ds_read_b128 v[226:229], v226 offset:3072
	global_load_lds_dwordx4 v[236:237], off
	v_lshl_add_u64 v[236:237], v[234:235], 0, s[64:65]
	s_add_i32 m0, s9, 0x2000
	s_nop 0
	global_load_lds_dwordx4 v[236:237], off
	s_barrier
	s_waitcnt lgkmcnt(0)
	v_mfma_f32_16x16x32_bf16 v[94:97], v[160:163], v[214:217], v[94:97]
	v_mfma_f32_16x16x32_bf16 v[90:93], v[160:163], v[222:225], v[90:93]
	v_mfma_f32_16x16x32_bf16 v[86:89], v[190:193], v[214:217], v[86:89]
	v_mfma_f32_16x16x32_bf16 v[82:85], v[190:193], v[222:225], v[82:85]
	v_mfma_f32_16x16x32_bf16 v[78:81], v[198:201], v[214:217], v[78:81]
	v_mfma_f32_16x16x32_bf16 v[74:77], v[198:201], v[222:225], v[74:77]
	v_mfma_f32_16x16x32_bf16 v[70:73], v[206:209], v[214:217], v[70:73]
	v_mfma_f32_16x16x32_bf16 v[66:69], v[206:209], v[222:225], v[66:69]
	v_mfma_f32_16x16x32_bf16 v[94:97], v[164:167], v[218:221], v[94:97]
	v_mfma_f32_16x16x32_bf16 v[90:93], v[164:167], v[226:229], v[90:93]
	v_mfma_f32_16x16x32_bf16 v[86:89], v[194:197], v[218:221], v[86:89]
	v_mfma_f32_16x16x32_bf16 v[82:85], v[194:197], v[226:229], v[82:85]
	v_mfma_f32_16x16x32_bf16 v[78:81], v[202:205], v[218:221], v[78:81]
	v_mfma_f32_16x16x32_bf16 v[74:77], v[202:205], v[226:229], v[74:77]
	v_mfma_f32_16x16x32_bf16 v[70:73], v[210:213], v[218:221], v[70:73]
	v_mfma_f32_16x16x32_bf16 v[66:69], v[210:213], v[226:229], v[66:69]
	s_barrier
	s_mov_b32 m0, s31
	v_lshl_add_u64 v[138:139], v[138:139], 0, s[48:49]
	ds_read_b128 v[160:163], v142 offset:49152
	ds_read_b128 v[164:167], v142 offset:50176
	ds_read_b128 v[190:193], v142 offset:51200
	ds_read_b128 v[194:197], v142 offset:52224
	ds_read_b128 v[198:201], v142 offset:53248
	ds_read_b128 v[202:205], v142 offset:54272
	ds_read_b128 v[206:209], v142 offset:55296
	ds_read_b128 v[210:213], v142 offset:56320
	global_load_lds_dwordx4 v[138:139], off
	v_lshl_add_u64 v[138:139], v[230:231], 0, s[48:49]
	s_mov_b32 m0, s42
	s_nop 0
	global_load_lds_dwordx4 v[138:139], off
	s_barrier
;     __device__ __forceinline__ unsigned* BAR() const { return (unsigned*)(ws + OFF_BAR); }
; #define STAGE(bufoff, gbase, voff) do { _Pragma("unroll") for (int _i = 0; _i < 2; ++_i) \
;         __builtin_amdgcn_global_load_lds((const unsigned*)((const char*)(gbase) + voff[_i]), (LAS unsigned*)(lds + (bufoff) + ldsw + _i * 8192), 16, 0, 0); } while (0)
; #define LDA(dst, b, h) do { _Pragma("unroll") for (int m = 0; m < 4; ++m) _Pragma("unroll") for (int k = 0; k < 2; ++k) dst[m][k] = *(const LAS bf16x8*)(lds + SA(b, h) + aoff + m * 2048 + k * 1024); } while (0)
; #define LDB(dst, b, h) do { _Pragma("unroll") for (int n = 0; n < 2; ++n) _Pragma("unroll") for (int k = 0; k < 2; ++k) dst[n][k] = *(const LAS bf16x8*)(lds + SB(b, h) + boff + n * 2048 + k * 1024); } while (0)
; #define MMA(ai, bj, At, Bx) do { __builtin_amdgcn_s_setprio(1); _Pragma("unroll") for (int m = 0; m < 4; ++m) _Pragma("unroll") for (int n = 0; n < 2; ++n) _Pragma("unroll") for (int k = 0; k < 2; ++k) \
;       acc[ai][bj][m][n] = __builtin_amdgcn_mfma_f32_16x16x32_bf16(At[m][k], Bx[n][k], acc[ai][bj][m][n], 0, 0, 0); \
;     __builtin_amdgcn_s_setprio(0); } while (0)
; #define WAIT_V(n) asm volatile("s_waitcnt vmcnt(" #n ")" ::: "memory")
; #define WAIT_L(n) asm volatile("s_waitcnt lgkmcnt(" #n ")" ::: "memory")
; #define BAR __builtin_amdgcn_s_barrier()
; #define SCHED __builtin_amdgcn_sched_barrier(0)
;     ...
;         LDB(B1, 1, 1); STAGE(SB(1, 0), b3, voffB);
;         BAR; WAIT_L(0); MMA(0, 1, At, B1); BAR;
;         LDA(At, 1, 1); STAGE(SA(1, 0), a3, voffA);
;         BAR; WAIT_L(0); MMA(1, 0, At, B0); BAR; SCHED;
;         STAGE(SB(1, 1), b3 + hstepB, voffB);
;         WAIT_V(6); BAR; MMA(1, 1, At, B1); BAR;
;     }
;     { LDB(B0, 0, 0); LDA(At, 0, 0); STAGE(SA(1, 1), pA(nt - 1) + hstepA, voffA);
;       BAR; WAIT_L(0); MMA(0, 0, At, B0); BAR;
;       LDB(B1, 0, 1); BAR; WAIT_L(0); MMA(0, 1, At, B1); BAR;
;       LDA(At, 0, 1); WAIT_V(4); BAR; WAIT_L(0); MMA(1, 0, At, B0); MMA(1, 1, At, B1); BAR; }
	s_waitcnt lgkmcnt(0)
	v_mfma_f32_16x16x32_bf16 v[62:65], v[160:163], v[144:147], v[62:65]
	v_mfma_f32_16x16x32_bf16 v[58:61], v[160:163], v[152:155], v[58:61]
	v_mfma_f32_16x16x32_bf16 v[54:57], v[190:193], v[144:147], v[54:57]
	v_mfma_f32_16x16x32_bf16 v[50:53], v[190:193], v[152:155], v[50:53]
	v_mfma_f32_16x16x32_bf16 v[46:49], v[198:201], v[144:147], v[46:49]
	v_mfma_f32_16x16x32_bf16 v[42:45], v[198:201], v[152:155], v[42:45]
	v_mfma_f32_16x16x32_bf16 v[38:41], v[206:209], v[144:147], v[38:41]
	v_mfma_f32_16x16x32_bf16 v[34:37], v[206:209], v[152:155], v[34:37]
	v_mfma_f32_16x16x32_bf16 v[62:65], v[164:167], v[148:151], v[62:65]
	v_mfma_f32_16x16x32_bf16 v[58:61], v[164:167], v[156:159], v[58:61]
	v_mfma_f32_16x16x32_bf16 v[54:57], v[194:197], v[148:151], v[54:57]
	v_mfma_f32_16x16x32_bf16 v[50:53], v[194:197], v[156:159], v[50:53]
	v_mfma_f32_16x16x32_bf16 v[46:49], v[202:205], v[148:151], v[46:49]
	v_mfma_f32_16x16x32_bf16 v[42:45], v[202:205], v[156:159], v[42:45]
	v_mfma_f32_16x16x32_bf16 v[38:41], v[210:213], v[148:151], v[38:41]
	v_mfma_f32_16x16x32_bf16 v[34:37], v[210:213], v[156:159], v[34:37]
	s_barrier
	s_add_i32 s9, s10, s1
	v_lshl_add_u64 v[138:139], v[232:233], 0, s[56:57]
	s_mov_b32 m0, s9
	s_nop 0
	global_load_lds_dwordx4 v[138:139], off
	v_lshl_add_u64 v[138:139], v[234:235], 0, s[56:57]
	s_add_i32 m0, s9, 0x2000
	s_nop 0
	global_load_lds_dwordx4 v[138:139], off
	s_waitcnt vmcnt(6)
	s_barrier
	v_mfma_f32_16x16x32_bf16 v[30:33], v[160:163], v[214:217], v[30:33]
	v_mfma_f32_16x16x32_bf16 v[26:29], v[160:163], v[222:225], v[26:29]
	v_mfma_f32_16x16x32_bf16 v[22:25], v[190:193], v[214:217], v[22:25]
	v_mfma_f32_16x16x32_bf16 v[18:21], v[190:193], v[222:225], v[18:21]
	v_mfma_f32_16x16x32_bf16 v[14:17], v[198:201], v[214:217], v[14:17]
	v_mfma_f32_16x16x32_bf16 v[10:13], v[198:201], v[222:225], v[10:13]
	v_mfma_f32_16x16x32_bf16 v[6:9], v[206:209], v[214:217], v[6:9]
	v_mfma_f32_16x16x32_bf16 v[2:5], v[206:209], v[222:225], v[2:5]
	v_mfma_f32_16x16x32_bf16 v[30:33], v[164:167], v[218:221], v[30:33]
	v_mfma_f32_16x16x32_bf16 v[26:29], v[164:167], v[226:229], v[26:29]
	v_mfma_f32_16x16x32_bf16 v[22:25], v[194:197], v[218:221], v[22:25]
	v_mfma_f32_16x16x32_bf16 v[18:21], v[194:197], v[226:229], v[18:21]
	v_mfma_f32_16x16x32_bf16 v[14:17], v[202:205], v[218:221], v[14:17]
	v_mfma_f32_16x16x32_bf16 v[10:13], v[202:205], v[226:229], v[10:13]
	v_mfma_f32_16x16x32_bf16 v[6:9], v[210:213], v[218:221], v[6:9]
	v_mfma_f32_16x16x32_bf16 v[2:5], v[210:213], v[226:229], v[2:5]
	s_barrier
	s_add_i32 s6, s6, 2
	v_lshl_add_u64 v[132:133], v[132:133], 0, s[40:41]
	v_lshl_add_u64 v[134:135], v[134:135], 0, s[40:41]
	v_lshl_add_u64 v[136:137], v[136:137], 0, s[40:41]
	s_cmp_gt_u32 s6, 11
	v_lshl_add_u64 v[140:141], v[140:141], 0, s[40:41]
	s_cbranch_scc0 .LBB0_377
	v_add_u32_e32 v138, 0, v143
	s_add_u32 s4, s4, 0x40780
	v_add_u32_e32 v136, 0x10000, v138
	s_addc_u32 s5, s5, 0
	s_mov_b32 m0, s8
	ds_read_b128 v[132:135], v136
	ds_read_b128 v[144:147], v136 offset:1024
	ds_read_b128 v[148:151], v136 offset:2048
	ds_read_b128 v[152:155], v136 offset:3072
	ds_read_b128 v[156:159], v142
	ds_read_b128 v[160:163], v142 offset:1024
	ds_read_b128 v[164:167], v142 offset:2048
	ds_read_b128 v[190:193], v142 offset:3072
	ds_read_b128 v[194:197], v142 offset:4096
	ds_read_b128 v[198:201], v142 offset:5120
	ds_read_b128 v[202:205], v142 offset:6144
	ds_read_b128 v[206:209], v142 offset:7168
	v_lshl_add_u64 v[136:137], s[4:5], 0, v[0:1]
	global_load_lds_dwordx4 v[136:137], off
	v_lshl_add_u64 v[130:131], s[4:5], 0, v[130:131]
	s_mov_b32 m0, s7
	s_nop 0
	global_load_lds_dwordx4 v[130:131], off
	s_barrier
	s_waitcnt lgkmcnt(0)
	v_mfma_f32_16x16x32_bf16 v[126:129], v[156:159], v[132:135], v[126:129]
	v_mfma_f32_16x16x32_bf16 v[122:125], v[156:159], v[148:151], v[122:125]
	v_mfma_f32_16x16x32_bf16 v[118:121], v[164:167], v[132:135], v[118:121]
	v_mfma_f32_16x16x32_bf16 v[110:113], v[194:197], v[132:135], v[110:113]
	v_mfma_f32_16x16x32_bf16 v[106:109], v[194:197], v[148:151], v[106:109]
	v_mfma_f32_16x16x32_bf16 v[102:105], v[202:205], v[132:135], v[102:105]
	v_mfma_f32_16x16x32_bf16 v[98:101], v[202:205], v[148:151], v[98:101]
	v_mfma_f32_16x16x32_bf16 v[126:129], v[160:163], v[144:147], v[126:129]
	v_mfma_f32_16x16x32_bf16 v[122:125], v[160:163], v[152:155], v[122:125]
	v_mfma_f32_16x16x32_bf16 v[118:121], v[190:193], v[144:147], v[118:121]
	v_mfma_f32_16x16x32_bf16 v[114:117], v[164:167], v[148:151], v[114:117]
	v_mfma_f32_16x16x32_bf16 v[110:113], v[198:201], v[144:147], v[110:113]
	v_mfma_f32_16x16x32_bf16 v[106:109], v[198:201], v[152:155], v[106:109]
	v_mfma_f32_16x16x32_bf16 v[102:105], v[206:209], v[144:147], v[102:105]
	v_mfma_f32_16x16x32_bf16 v[98:101], v[206:209], v[152:155], v[98:101]
	v_mfma_f32_16x16x32_bf16 v[210:213], v[190:193], v[152:155], v[114:117]
	v_add_u32_e32 v0, 0x14000, v138
	s_barrier
	ds_read_b128 v[114:117], v0
	ds_read_b128 v[214:217], v0 offset:1024
	ds_read_b128 v[218:221], v0 offset:2048
	ds_read_b128 v[222:225], v0 offset:3072
	s_barrier
	s_waitcnt lgkmcnt(0)
	v_mfma_f32_16x16x32_bf16 v[78:81], v[194:197], v[114:117], v[78:81]
	v_mfma_f32_16x16x32_bf16 v[74:77], v[194:197], v[218:221], v[74:77]
	v_mfma_f32_16x16x32_bf16 v[70:73], v[202:205], v[114:117], v[70:73]
	v_mfma_f32_16x16x32_bf16 v[66:69], v[202:205], v[218:221], v[66:69]
	v_mfma_f32_16x16x32_bf16 v[94:97], v[156:159], v[114:117], v[94:97]
	v_mfma_f32_16x16x32_bf16 v[90:93], v[156:159], v[218:221], v[90:93]
	v_mfma_f32_16x16x32_bf16 v[86:89], v[164:167], v[114:117], v[86:89]
	v_mfma_f32_16x16x32_bf16 v[82:85], v[164:167], v[218:221], v[82:85]
	v_mfma_f32_16x16x32_bf16 v[78:81], v[198:201], v[214:217], v[78:81]
	v_mfma_f32_16x16x32_bf16 v[74:77], v[198:201], v[222:225], v[74:77]
	v_mfma_f32_16x16x32_bf16 v[70:73], v[206:209], v[214:217], v[70:73]
	v_mfma_f32_16x16x32_bf16 v[66:69], v[206:209], v[222:225], v[66:69]
	v_mfma_f32_16x16x32_bf16 v[226:229], v[160:163], v[214:217], v[94:97]
	v_mfma_f32_16x16x32_bf16 v[156:159], v[160:163], v[222:225], v[90:93]
	v_mfma_f32_16x16x32_bf16 v[160:163], v[190:193], v[214:217], v[86:89]
	v_mfma_f32_16x16x32_bf16 v[164:167], v[190:193], v[222:225], v[82:85]
	s_barrier
;     __device__ __forceinline__ unsigned* BAR() const { return (unsigned*)(ws + OFF_BAR); }
; #define LDA(dst, b, h) do { _Pragma("unroll") for (int m = 0; m < 4; ++m) _Pragma("unroll") for (int k = 0; k < 2; ++k) dst[m][k] = *(const LAS bf16x8*)(lds + SA(b, h) + aoff + m * 2048 + k * 1024); } while (0)
; #define LDB(dst, b, h) do { _Pragma("unroll") for (int n = 0; n < 2; ++n) _Pragma("unroll") for (int k = 0; k < 2; ++k) dst[n][k] = *(const LAS bf16x8*)(lds + SB(b, h) + boff + n * 2048 + k * 1024); } while (0)
; #define MMA(ai, bj, At, Bx) do { __builtin_amdgcn_s_setprio(1); _Pragma("unroll") for (int m = 0; m < 4; ++m) _Pragma("unroll") for (int n = 0; n < 2; ++n) _Pragma("unroll") for (int k = 0; k < 2; ++k) \
;       acc[ai][bj][m][n] = __builtin_amdgcn_mfma_f32_16x16x32_bf16(At[m][k], Bx[n][k], acc[ai][bj][m][n], 0, 0, 0); \
;     __builtin_amdgcn_s_setprio(0); } while (0)
; #define WAIT_V(n) asm volatile("s_waitcnt vmcnt(" #n ")" ::: "memory")
; #define WAIT_L(n) asm volatile("s_waitcnt lgkmcnt(" #n ")" ::: "memory")
; #define BAR __builtin_amdgcn_s_barrier()
;     ...
;       LDA(At, 0, 1); WAIT_V(4); BAR; WAIT_L(0); MMA(1, 0, At, B0); MMA(1, 1, At, B1); BAR; }
;     { LDB(B0, 1, 0); LDA(At, 1, 0); WAIT_V(2); BAR; WAIT_L(0); MMA(0, 0, At, B0); BAR;
;       LDB(B1, 1, 1); WAIT_V(0); BAR; WAIT_L(0); MMA(0, 1, At, B1); BAR;
;       LDA(At, 1, 1); BAR; WAIT_L(0); MMA(1, 0, At, B0); MMA(1, 1, At, B1); BAR; }
	s_nop 0
	ds_read_b128 v[82:85], v142 offset:16384
	ds_read_b128 v[86:89], v142 offset:17408
	ds_read_b128 v[90:93], v142 offset:18432
	ds_read_b128 v[94:97], v142 offset:19456
	ds_read_b128 v[190:193], v142 offset:20480
	ds_read_b128 v[194:197], v142 offset:21504
	ds_read_b128 v[198:201], v142 offset:22528
	ds_read_b128 v[202:205], v142 offset:23552
	s_waitcnt vmcnt(4)
	s_barrier
	s_waitcnt lgkmcnt(0)
	v_mfma_f32_16x16x32_bf16 v[46:49], v[190:193], v[132:135], v[46:49]
	v_mfma_f32_16x16x32_bf16 v[42:45], v[190:193], v[148:151], v[42:45]
	v_mfma_f32_16x16x32_bf16 v[38:41], v[198:201], v[132:135], v[38:41]
	v_mfma_f32_16x16x32_bf16 v[34:37], v[198:201], v[148:151], v[34:37]
	v_mfma_f32_16x16x32_bf16 v[62:65], v[82:85], v[132:135], v[62:65]
	v_mfma_f32_16x16x32_bf16 v[58:61], v[82:85], v[148:151], v[58:61]
	v_mfma_f32_16x16x32_bf16 v[54:57], v[90:93], v[132:135], v[54:57]
	v_mfma_f32_16x16x32_bf16 v[50:53], v[90:93], v[148:151], v[50:53]
	v_mfma_f32_16x16x32_bf16 v[46:49], v[194:197], v[144:147], v[46:49]
	v_mfma_f32_16x16x32_bf16 v[42:45], v[194:197], v[152:155], v[42:45]
	v_mfma_f32_16x16x32_bf16 v[38:41], v[202:205], v[144:147], v[38:41]
	v_mfma_f32_16x16x32_bf16 v[34:37], v[202:205], v[152:155], v[34:37]
	v_mfma_f32_16x16x32_bf16 v[206:209], v[86:89], v[144:147], v[62:65]
	v_mfma_f32_16x16x32_bf16 v[230:233], v[86:89], v[152:155], v[58:61]
	v_mfma_f32_16x16x32_bf16 v[234:237], v[94:97], v[144:147], v[54:57]
	v_mfma_f32_16x16x32_bf16 v[238:241], v[94:97], v[152:155], v[50:53]
	v_mfma_f32_16x16x32_bf16 v[2:5], v[198:201], v[218:221], v[2:5]
	v_mfma_f32_16x16x32_bf16 v[30:33], v[82:85], v[114:117], v[30:33]
	v_mfma_f32_16x16x32_bf16 v[26:29], v[82:85], v[218:221], v[26:29]
	v_mfma_f32_16x16x32_bf16 v[22:25], v[90:93], v[114:117], v[22:25]
	v_mfma_f32_16x16x32_bf16 v[18:21], v[90:93], v[218:221], v[18:21]
	v_mfma_f32_16x16x32_bf16 v[14:17], v[190:193], v[114:117], v[14:17]
	v_mfma_f32_16x16x32_bf16 v[10:13], v[190:193], v[218:221], v[10:13]
	v_mfma_f32_16x16x32_bf16 v[6:9], v[198:201], v[114:117], v[6:9]
	v_mfma_f32_16x16x32_bf16 v[2:5], v[202:205], v[222:225], v[2:5]
	v_mfma_f32_16x16x32_bf16 v[130:133], v[86:89], v[214:217], v[30:33]
	v_mfma_f32_16x16x32_bf16 v[134:137], v[86:89], v[222:225], v[26:29]
	v_mfma_f32_16x16x32_bf16 v[144:147], v[94:97], v[214:217], v[22:25]
	v_mfma_f32_16x16x32_bf16 v[148:151], v[94:97], v[222:225], v[18:21]
	v_mfma_f32_16x16x32_bf16 v[152:155], v[194:197], v[214:217], v[14:17]
	v_mfma_f32_16x16x32_bf16 v[190:193], v[194:197], v[222:225], v[10:13]
	v_mfma_f32_16x16x32_bf16 v[194:197], v[202:205], v[214:217], v[6:9]
	v_add_u32_e32 v0, 0x18000, v138
	s_barrier
	ds_read_b128 v[6:9], v0
	ds_read_b128 v[10:13], v0 offset:1024
	ds_read_b128 v[14:17], v0 offset:2048
	ds_read_b128 v[198:201], v0 offset:3072
	ds_read_b128 v[18:21], v142 offset:32768
	ds_read_b128 v[22:25], v142 offset:33792
	ds_read_b128 v[26:29], v142 offset:34816
	ds_read_b128 v[50:53], v142 offset:35840
	ds_read_b128 v[202:205], v142 offset:36864
	ds_read_b128 v[214:217], v142 offset:37888
	ds_read_b128 v[218:221], v142 offset:38912
	ds_read_b128 v[222:225], v142 offset:39936
	s_waitcnt vmcnt(2)
	s_barrier
	s_waitcnt lgkmcnt(0)
	v_mfma_f32_16x16x32_bf16 v[30:33], v[18:21], v[6:9], v[126:129]
	v_mfma_f32_16x16x32_bf16 v[114:117], v[22:25], v[10:13], v[30:33]
	v_mfma_f32_16x16x32_bf16 v[30:33], v[18:21], v[14:17], v[122:125]
	v_mfma_f32_16x16x32_bf16 v[94:97], v[22:25], v[198:201], v[30:33]
	v_mfma_f32_16x16x32_bf16 v[30:33], v[26:29], v[6:9], v[118:121]
	v_mfma_f32_16x16x32_bf16 v[118:121], v[50:53], v[10:13], v[30:33]
	v_mfma_f32_16x16x32_bf16 v[30:33], v[26:29], v[14:17], v[210:213]
	v_mfma_f32_16x16x32_bf16 v[90:93], v[50:53], v[198:201], v[30:33]
	v_mfma_f32_16x16x32_bf16 v[30:33], v[202:205], v[6:9], v[110:113]
	v_mfma_f32_16x16x32_bf16 v[122:125], v[214:217], v[10:13], v[30:33]
	v_mfma_f32_16x16x32_bf16 v[30:33], v[202:205], v[14:17], v[106:109]
	v_mfma_f32_16x16x32_bf16 v[86:89], v[214:217], v[198:201], v[30:33]
	v_mfma_f32_16x16x32_bf16 v[30:33], v[218:221], v[6:9], v[102:105]
	v_mfma_f32_16x16x32_bf16 v[126:129], v[222:225], v[10:13], v[30:33]
	v_mfma_f32_16x16x32_bf16 v[30:33], v[218:221], v[14:17], v[98:101]
	v_mfma_f32_16x16x32_bf16 v[82:85], v[222:225], v[198:201], v[30:33]
	v_add_u32_e32 v0, 0x1c000, v138
	s_barrier
;     __device__ __forceinline__ unsigned* BAR() const { return (unsigned*)(ws + OFF_BAR); }
; #define LDA(dst, b, h) do { _Pragma("unroll") for (int m = 0; m < 4; ++m) _Pragma("unroll") for (int k = 0; k < 2; ++k) dst[m][k] = *(const LAS bf16x8*)(lds + SA(b, h) + aoff + m * 2048 + k * 1024); } while (0)
; #define LDB(dst, b, h) do { _Pragma("unroll") for (int n = 0; n < 2; ++n) _Pragma("unroll") for (int k = 0; k < 2; ++k) dst[n][k] = *(const LAS bf16x8*)(lds + SB(b, h) + boff + n * 2048 + k * 1024); } while (0)
; #define MMA(ai, bj, At, Bx) do { __builtin_amdgcn_s_setprio(1); _Pragma("unroll") for (int m = 0; m < 4; ++m) _Pragma("unroll") for (int n = 0; n < 2; ++n) _Pragma("unroll") for (int k = 0; k < 2; ++k) \
;       acc[ai][bj][m][n] = __builtin_amdgcn_mfma_f32_16x16x32_bf16(At[m][k], Bx[n][k], acc[ai][bj][m][n], 0, 0, 0); \
;     __builtin_amdgcn_s_setprio(0); } while (0)
; #define WAIT_V(n) asm volatile("s_waitcnt vmcnt(" #n ")" ::: "memory")
; #define WAIT_L(n) asm volatile("s_waitcnt lgkmcnt(" #n ")" ::: "memory")
; #define BAR __builtin_amdgcn_s_barrier()
;     ...
;     { LDB(B0, 1, 0); LDA(At, 1, 0); WAIT_V(2); BAR; WAIT_L(0); MMA(0, 0, At, B0); BAR;
;       LDB(B1, 1, 1); WAIT_V(0); BAR; WAIT_L(0); MMA(0, 1, At, B1); BAR;
;       LDA(At, 1, 1); BAR; WAIT_L(0); MMA(1, 0, At, B0); MMA(1, 1, At, B1); BAR; }
;     if (wr == 0) BAR;
	ds_read_b128 v[210:213], v0
	ds_read_b128 v[242:245], v0 offset:1024
	ds_read_b128 v[246:249], v0 offset:2048
	ds_read_b128 v[138:141], v0 offset:3072
	s_waitcnt vmcnt(0)
	s_barrier
	s_waitcnt lgkmcnt(0)
	v_mfma_f32_16x16x32_bf16 v[30:33], v[18:21], v[210:213], v[226:229]
	v_mfma_f32_16x16x32_bf16 v[18:21], v[18:21], v[246:249], v[156:159]
	v_mfma_f32_16x16x32_bf16 v[62:65], v[22:25], v[242:245], v[30:33]
	v_mfma_f32_16x16x32_bf16 v[30:33], v[22:25], v[138:141], v[18:21]
	v_mfma_f32_16x16x32_bf16 v[18:21], v[26:29], v[210:213], v[160:163]
	v_mfma_f32_16x16x32_bf16 v[58:61], v[50:53], v[242:245], v[18:21]
	v_mfma_f32_16x16x32_bf16 v[18:21], v[26:29], v[246:249], v[164:167]
	v_mfma_f32_16x16x32_bf16 v[26:29], v[50:53], v[138:141], v[18:21]
	v_mfma_f32_16x16x32_bf16 v[18:21], v[202:205], v[210:213], v[78:81]
	v_mfma_f32_16x16x32_bf16 v[54:57], v[214:217], v[242:245], v[18:21]
	v_mfma_f32_16x16x32_bf16 v[18:21], v[202:205], v[246:249], v[74:77]
	v_mfma_f32_16x16x32_bf16 v[22:25], v[214:217], v[138:141], v[18:21]
	v_mfma_f32_16x16x32_bf16 v[18:21], v[218:221], v[210:213], v[70:73]
	v_mfma_f32_16x16x32_bf16 v[50:53], v[222:225], v[242:245], v[18:21]
	v_mfma_f32_16x16x32_bf16 v[18:21], v[218:221], v[246:249], v[66:69]
	v_mfma_f32_16x16x32_bf16 v[18:21], v[222:225], v[138:141], v[18:21]
	s_barrier
	ds_read_b128 v[156:159], v142 offset:49152
	ds_read_b128 v[160:163], v142 offset:50176
	ds_read_b128 v[164:167], v142 offset:51200
	ds_read_b128 v[202:205], v142 offset:52224
	ds_read_b128 v[214:217], v142 offset:53248
	ds_read_b128 v[218:221], v142 offset:54272
	ds_read_b128 v[222:225], v142 offset:55296
	ds_read_b128 v[226:229], v142 offset:56320
	s_barrier
	s_waitcnt lgkmcnt(0)
	v_mfma_f32_16x16x32_bf16 v[66:69], v[156:159], v[6:9], v[206:209]
	v_mfma_f32_16x16x32_bf16 v[110:113], v[160:163], v[10:13], v[66:69]
	v_mfma_f32_16x16x32_bf16 v[66:69], v[156:159], v[14:17], v[230:233]
	v_mfma_f32_16x16x32_bf16 v[78:81], v[160:163], v[198:201], v[66:69]
	v_mfma_f32_16x16x32_bf16 v[66:69], v[164:167], v[6:9], v[234:237]
	v_mfma_f32_16x16x32_bf16 v[46:49], v[214:217], v[6:9], v[46:49]
	v_mfma_f32_16x16x32_bf16 v[6:9], v[222:225], v[6:9], v[38:41]
	v_mfma_f32_16x16x32_bf16 v[106:109], v[202:205], v[10:13], v[66:69]
	v_mfma_f32_16x16x32_bf16 v[66:69], v[164:167], v[14:17], v[238:241]
	v_mfma_f32_16x16x32_bf16 v[42:45], v[214:217], v[14:17], v[42:45]
	v_mfma_f32_16x16x32_bf16 v[98:101], v[226:229], v[10:13], v[6:9]
	v_mfma_f32_16x16x32_bf16 v[6:9], v[222:225], v[14:17], v[34:37]
	v_mfma_f32_16x16x32_bf16 v[74:77], v[202:205], v[198:201], v[66:69]
	v_mfma_f32_16x16x32_bf16 v[102:105], v[218:221], v[10:13], v[46:49]
	v_mfma_f32_16x16x32_bf16 v[70:73], v[218:221], v[198:201], v[42:45]
	v_mfma_f32_16x16x32_bf16 v[66:69], v[226:229], v[198:201], v[6:9]
	v_mfma_f32_16x16x32_bf16 v[6:9], v[156:159], v[210:213], v[130:133]
	v_mfma_f32_16x16x32_bf16 v[46:49], v[160:163], v[242:245], v[6:9]
	v_mfma_f32_16x16x32_bf16 v[6:9], v[156:159], v[246:249], v[134:137]
	v_mfma_f32_16x16x32_bf16 v[14:17], v[160:163], v[138:141], v[6:9]
	v_mfma_f32_16x16x32_bf16 v[6:9], v[164:167], v[210:213], v[144:147]
	v_mfma_f32_16x16x32_bf16 v[42:45], v[202:205], v[242:245], v[6:9]
	v_mfma_f32_16x16x32_bf16 v[6:9], v[164:167], v[246:249], v[148:151]
	v_mfma_f32_16x16x32_bf16 v[10:13], v[202:205], v[138:141], v[6:9]
	v_mfma_f32_16x16x32_bf16 v[6:9], v[214:217], v[210:213], v[152:155]
	v_mfma_f32_16x16x32_bf16 v[38:41], v[218:221], v[242:245], v[6:9]
	v_mfma_f32_16x16x32_bf16 v[6:9], v[214:217], v[246:249], v[190:193]
	v_mfma_f32_16x16x32_bf16 v[34:37], v[222:225], v[210:213], v[194:197]
	v_mfma_f32_16x16x32_bf16 v[2:5], v[222:225], v[246:249], v[2:5]
	v_mfma_f32_16x16x32_bf16 v[6:9], v[218:221], v[138:141], v[6:9]
	v_mfma_f32_16x16x32_bf16 v[34:37], v[226:229], v[242:245], v[34:37]
	v_mfma_f32_16x16x32_bf16 v[2:5], v[226:229], v[138:141], v[2:5]
	s_cmpk_lt_u32 s12, 0x100
	s_barrier
	s_cbranch_scc0 .LBB0_206
	s_barrier
	s_branch .LBB0_206

; #define MFMA(a, b, c) __builtin_amdgcn_mfma_f32_32x32x16_bf16((a), (b), (c), 0, 0, 0)
; __device__ __forceinline__ unsigned pk2(float lo, float hi) { const f32x2_t f = {lo, hi}; const bf16x2_t b = __builtin_convertvector(f, bf16x2_t); return __builtin_bit_cast(unsigned, b); }
; template <int DV> ...
;     ...
;     float ps = 0.f;
; #pragma unroll
;     for (int sub = 0; sub < 2; sub++)
; #pragma unroll
;         for (int r = 0; r < 16; r++) { S[sub][r] = __builtin_amdgcn_exp2f(S[sub][r]); ps += S[sub][r]; }
;     l += ps;
; #pragma unroll
;     for (int sub = 0; sub < 2; sub++)
; #pragma unroll
;         for (int s = 0; s < 2; s++) {
;             u32x4 cv;
;             cv[0] = pk2(S[sub][8 * s + 0], S[sub][8 * s + 1]); cv[1] = pk2(S[sub][8 * s + 2], S[sub][8 * s + 3]);
;             cv[2] = pk2(S[sub][8 * s + 4], S[sub][8 * s + 5]); cv[3] = pk2(S[sub][8 * s + 6], S[sub][8 * s + 7]);
;             const bf16x8 pb = __builtin_bit_cast(bf16x8, cv);
; #pragma unroll
;             for (int dt = 0; dt < DV / 32; dt++) {
;                 const bf16x8 vf = *(const bf16x8*)(Vl + (dt * 32 + l31) * LROW + (sub * 4 + s * 2 + hh) * 16);
;                 O[dt] = MFMA(vf, pb, O[dt]);
;             }
; template <bool DIFF>
; __device__ __forceinline__ void attn_unit(const Params& p, int layer, int mode, int bl, int hidx, int qblk, bool isctx, unsigned char* lds) {
;     ...
;         if (more) {
;             unsigned char* wb = lds + ((it + 1) & 1) * BUFB + lr * LROW + lc * 16;
; #pragma unroll
;             for (int i = 0; i < NKM; i++) *(u32x4*)(wb + i * 9216) = kr[i];
; #pragma unroll
;             for (int i = 0; i < DV / 64; i++) *(u32x4*)(wb + KBYTES + i * 64 * LROW) = vr[i];
;         }
.LBB0_488:
	v_exp_f32_e32 v66, v66
	v_exp_f32_e32 v67, v67
	v_exp_f32_e32 v68, v68
	v_exp_f32_e32 v69, v69
	v_exp_f32_e32 v70, v70
	v_exp_f32_e32 v71, v71
	v_exp_f32_e32 v72, v72
	v_exp_f32_e32 v73, v73
	v_cvt_pk_bf16_f32 v142, v66, v67
	v_cvt_pk_bf16_f32 v143, v68, v69
	v_add_f32_e32 v150, v67, v66
	v_cvt_pk_bf16_f32 v144, v70, v71
	v_add_f32_e32 v150, v68, v150
	v_cvt_pk_bf16_f32 v145, v72, v73
	v_add_f32_e32 v150, v69, v150
	v_add_f32_e32 v150, v70, v150
	s_waitcnt lgkmcnt(0)
	v_mfma_f32_32x32x16_bf16 v[18:33], v[224:227], v[142:145], v[18:33]
	v_exp_f32_e32 v74, v74
	v_exp_f32_e32 v75, v75
	v_exp_f32_e32 v76, v76
	v_exp_f32_e32 v77, v77
	v_add_f32_e32 v150, v71, v150
	v_mfma_f32_32x32x16_bf16 v[2:17], v[228:231], v[142:145], v[2:17]
	v_exp_f32_e32 v78, v78
	v_exp_f32_e32 v79, v79
	v_exp_f32_e32 v80, v80
	v_exp_f32_e32 v81, v81
	v_add_f32_e32 v150, v72, v150
	v_add_f32_e32 v150, v73, v150
	v_cvt_pk_bf16_f32 v146, v74, v75
	v_cvt_pk_bf16_f32 v147, v76, v77
	v_cvt_pk_bf16_f32 v148, v78, v79
	v_cvt_pk_bf16_f32 v149, v80, v81
	v_add_f32_e32 v150, v74, v150
	v_add_f32_e32 v150, v75, v150
	v_mfma_f32_32x32x16_bf16 v[2:17], v[232:235], v[146:149], v[2:17]
	v_exp_f32_e32 v50, v50
	v_exp_f32_e32 v51, v51
	v_exp_f32_e32 v52, v52
	v_exp_f32_e32 v53, v53
	v_add_f32_e32 v150, v76, v150
	v_add_f32_e32 v150, v77, v150
	v_mfma_f32_32x32x16_bf16 v[18:33], v[236:239], v[146:149], v[18:33]
	v_exp_f32_e32 v54, v54
	v_exp_f32_e32 v55, v55
	v_exp_f32_e32 v56, v56
	v_exp_f32_e32 v57, v57
	v_add_f32_e32 v150, v78, v150
	v_add_f32_e32 v150, v79, v150
	v_add_f32_e32 v150, v80, v150
	v_add_f32_e32 v150, v81, v150
	v_cvt_pk_bf16_f32 v142, v50, v51
	v_cvt_pk_bf16_f32 v143, v52, v53
	v_cvt_pk_bf16_f32 v144, v54, v55
	v_cvt_pk_bf16_f32 v145, v56, v57
	v_add_f32_e32 v150, v50, v150
	v_add_f32_e32 v150, v51, v150
	v_mfma_f32_32x32x16_bf16 v[18:33], v[240:243], v[142:145], v[18:33]
	v_exp_f32_e32 v58, v58
	v_exp_f32_e32 v59, v59
	v_exp_f32_e32 v60, v60
	v_exp_f32_e32 v61, v61
	v_add_f32_e32 v150, v52, v150
	v_add_f32_e32 v150, v53, v150
	v_mfma_f32_32x32x16_bf16 v[2:17], v[244:247], v[142:145], v[2:17]
	v_exp_f32_e32 v62, v62
	v_exp_f32_e32 v63, v63
	v_exp_f32_e32 v64, v64
	v_exp_f32_e32 v65, v65
	v_add_f32_e32 v150, v54, v150
	v_add_f32_e32 v150, v55, v150
	v_add_f32_e32 v150, v56, v150
	v_add_f32_e32 v150, v57, v150
	v_cvt_pk_bf16_f32 v146, v58, v59
	v_cvt_pk_bf16_f32 v147, v60, v61
	v_cvt_pk_bf16_f32 v148, v62, v63
	v_cvt_pk_bf16_f32 v149, v64, v65
	v_add_f32_e32 v150, v58, v150
	v_add_f32_e32 v150, v59, v150
	v_mfma_f32_32x32x16_bf16 v[18:33], v[134:137], v[146:149], v[18:33]
	v_add_f32_e32 v150, v60, v150
	v_add_f32_e32 v150, v61, v150
	v_add_f32_e32 v150, v62, v150
	v_mfma_f32_32x32x16_bf16 v[2:17], v[138:141], v[146:149], v[2:17]
	v_add_f32_e32 v150, v63, v150
	v_add_f32_e32 v150, v64, v150
	v_add_f32_e32 v150, v65, v150
	s_andn2_b64 vcc, exec, s[42:43]
	s_cbranch_vccnz .LBB0_490
	s_bitcmp1_b32 s31, 0
	s_cselect_b32 s16, 0x4800, 0
	v_add_u32_e32 v120, s16, v115
	s_waitcnt vmcnt(1)
	ds_write_b128 v120, v[98:101]
	s_waitcnt vmcnt(0)
	ds_write_b128 v120, v[102:105] offset:9216

; #define MFMA(a, b, c) __builtin_amdgcn_mfma_f32_32x32x16_bf16((a), (b), (c), 0, 0, 0)
; __device__ __forceinline__ unsigned pk2(float lo, float hi) { const f32x2_t f = {lo, hi}; const bf16x2_t b = __builtin_convertvector(f, bf16x2_t); return __builtin_bit_cast(unsigned, b); }
; template <int DV>
; __device__ __forceinline__ void attn_tile(const unsigned char* Kl, const unsigned char* Vl, const bf16x8 (&qf)[4], f32x16 (&O)[DV / 32], float& m, float& l,
;                                           int l31, int hh, bool domask, int qpos, int kpos0) {
;     ...
;     float ps = 0.f;
; #pragma unroll
;     for (int sub = 0; sub < 2; sub++)
; #pragma unroll
;         for (int r = 0; r < 16; r++) { S[sub][r] = __builtin_amdgcn_exp2f(__builtin_fmaf(S[sub][r], SL2, -m)); ps += S[sub][r]; }
;     l += ps;
;     bf16x8 pb[2][2];
; #pragma unroll
;     for (int sub = 0; sub < 2; sub++)
; #pragma unroll
;         for (int s = 0; s < 2; s++) {
;             u32x4 cv;
;             cv[0] = pk2(S[sub][8 * s + 0], S[sub][8 * s + 1]); cv[1] = pk2(S[sub][8 * s + 2], S[sub][8 * s + 3]);
;             cv[2] = pk2(S[sub][8 * s + 4], S[sub][8 * s + 5]); cv[3] = pk2(S[sub][8 * s + 6], S[sub][8 * s + 7]);
;             pb[sub][s] = __builtin_bit_cast(bf16x8, cv);
;         }
; #pragma unroll
;     for (int sub = 0; sub < 2; sub++)
; #pragma unroll
;         for (int s = 0; s < 2; s++)
; #pragma unroll
;             for (int dt = 0; dt < DV / 32; dt++) {
;                 const bf16x8 vf = *(const bf16x8*)(Vl + (dt * 32 + l31) * LROW + (sub * 4 + s * 2 + hh) * 16);
;                 O[dt] = MFMA(vf, pb[sub][s], O[dt]);
;             }
; template <bool DIFF>
; __device__ __forceinline__ void attn_unit(const Params& p, int layer, int mode, int bl, int hidx, int qblk, bool isctx, unsigned char* lds) {
;     ...
;         if (more) {
;             unsigned char* wb = lds + ((it + 1) & 1) * BUFB + lr * LROW + lc * 16;
; #pragma unroll
;             for (int i = 0; i < NKM; i++) *(u32x4*)(wb + i * 9216) = kr[i];
; #pragma unroll
;             for (int i = 0; i < DV / 64; i++) *(u32x4*)(wb + KBYTES + i * 64 * LROW) = vr[i];
;         }
;         __syncthreads();
.LBB0_498:
	v_exp_f32_e32 v96, v96
	v_exp_f32_e32 v97, v97
	v_exp_f32_e32 v98, v98
	v_exp_f32_e32 v99, v99
	v_exp_f32_e32 v100, v100
	v_exp_f32_e32 v101, v101
	v_exp_f32_e32 v102, v102
	v_exp_f32_e32 v103, v103
	v_cvt_pk_bf16_f32 v164, v96, v97
	v_cvt_pk_bf16_f32 v165, v98, v99
	v_add_f32_e32 v14, v97, v96
	v_cvt_pk_bf16_f32 v166, v100, v101
	v_add_f32_e32 v14, v98, v14
	v_add_f32_e32 v14, v99, v14
	v_cvt_pk_bf16_f32 v167, v102, v103
	v_add_f32_e32 v14, v100, v14
	v_add_f32_e32 v14, v101, v14
	s_waitcnt lgkmcnt(0)
	v_mfma_f32_32x32x16_bf16 v[64:79], v[226:229], v[164:167], v[64:79]
	ds_read_b128 v[226:229], v193 offset:18528
	v_exp_f32_e32 v104, v104
	v_exp_f32_e32 v105, v105
	v_exp_f32_e32 v106, v106
	v_exp_f32_e32 v107, v107
	v_mfma_f32_32x32x16_bf16 v[48:63], v[230:233], v[164:167], v[48:63]
	ds_read_b128 v[230:233], v193 offset:23136
	v_exp_f32_e32 v108, v108
	v_exp_f32_e32 v109, v109
	v_exp_f32_e32 v110, v110
	v_exp_f32_e32 v111, v111
	v_add_f32_e32 v14, v102, v14
	v_mfma_f32_32x32x16_bf16 v[32:47], v[156:159], v[164:167], v[32:47]
	ds_read_b128 v[156:159], v193 offset:27744
	v_add_f32_e32 v14, v103, v14
	v_cvt_pk_bf16_f32 v96, v104, v105
	v_cvt_pk_bf16_f32 v97, v106, v107
	v_add_f32_e32 v14, v104, v14
	v_mfma_f32_32x32x16_bf16 v[16:31], v[160:163], v[164:167], v[16:31]
	ds_read_b128 v[160:163], v193 offset:32352
	v_add_f32_e32 v14, v105, v14
	v_cvt_pk_bf16_f32 v98, v108, v109
	v_add_f32_e32 v14, v106, v14
	v_cvt_pk_bf16_f32 v99, v110, v111
	v_add_f32_e32 v14, v107, v14
	v_add_f32_e32 v14, v108, v14
	v_add_f32_e32 v14, v109, v14
	v_mfma_f32_32x32x16_bf16 v[64:79], v[194:197], v[96:99], v[64:79]
	v_exp_f32_e32 v80, v80
	v_exp_f32_e32 v81, v81
	v_exp_f32_e32 v82, v82
	v_exp_f32_e32 v83, v83
	v_mfma_f32_32x32x16_bf16 v[48:63], v[198:201], v[96:99], v[48:63]
	v_exp_f32_e32 v84, v84
	v_exp_f32_e32 v85, v85
	v_exp_f32_e32 v86, v86
	v_exp_f32_e32 v87, v87
	v_add_f32_e32 v14, v110, v14
	v_mfma_f32_32x32x16_bf16 v[32:47], v[202:205], v[96:99], v[32:47]
	v_add_f32_e32 v14, v111, v14
	v_cvt_pk_bf16_f32 v100, v80, v81
	v_cvt_pk_bf16_f32 v101, v82, v83
	v_add_f32_e32 v14, v80, v14
	v_mfma_f32_32x32x16_bf16 v[16:31], v[206:209], v[96:99], v[16:31]
	v_add_f32_e32 v14, v81, v14
	v_cvt_pk_bf16_f32 v102, v84, v85
	v_add_f32_e32 v14, v82, v14
	v_cvt_pk_bf16_f32 v103, v86, v87
	v_add_f32_e32 v14, v83, v14
	v_add_f32_e32 v14, v84, v14
	v_add_f32_e32 v14, v85, v14
	v_mfma_f32_32x32x16_bf16 v[64:79], v[210:213], v[100:103], v[64:79]
	v_exp_f32_e32 v88, v88
	v_exp_f32_e32 v89, v89
	v_exp_f32_e32 v90, v90
	v_exp_f32_e32 v91, v91
	v_mfma_f32_32x32x16_bf16 v[48:63], v[214:217], v[100:103], v[48:63]
	v_exp_f32_e32 v92, v92
	v_exp_f32_e32 v93, v93
	v_exp_f32_e32 v94, v94
	v_exp_f32_e32 v95, v95
	v_add_f32_e32 v14, v86, v14
	v_mfma_f32_32x32x16_bf16 v[32:47], v[218:221], v[100:103], v[32:47]
	v_add_f32_e32 v14, v87, v14
	v_cvt_pk_bf16_f32 v104, v88, v89
	v_cvt_pk_bf16_f32 v105, v90, v91
	v_add_f32_e32 v14, v88, v14
	v_mfma_f32_32x32x16_bf16 v[16:31], v[222:225], v[100:103], v[16:31]
	v_add_f32_e32 v14, v89, v14
	v_cvt_pk_bf16_f32 v106, v92, v93
	v_add_f32_e32 v14, v90, v14
	v_cvt_pk_bf16_f32 v107, v94, v95
	v_add_f32_e32 v14, v91, v14
	v_add_f32_e32 v14, v92, v14
	v_add_f32_e32 v14, v93, v14
	s_waitcnt lgkmcnt(3)
	v_mfma_f32_32x32x16_bf16 v[64:79], v[226:229], v[104:107], v[64:79]
	v_add_f32_e32 v14, v94, v14
	s_add_i32 s24, s24, 1
	v_add_f32_e32 v14, v95, v14
	s_bitcmp1_b32 s24, 0
	s_cselect_b32 s8, 0x9000, 0
	s_add_i32 s1, s1, 64
	s_waitcnt lgkmcnt(2)
	v_mfma_f32_32x32x16_bf16 v[48:63], v[230:233], v[104:107], v[48:63]
	v_add_f32_e32 v145, v145, v14
	v_add_u32_e32 v0, s8, v147
	s_waitcnt vmcnt(3)
	ds_write_b128 v0, v[2:5]
	s_waitcnt vmcnt(2)
	ds_write_b128 v0, v[6:9] offset:9216
	s_waitcnt vmcnt(1)
	ds_write_b128 v0, v[10:13] offset:18432
	s_waitcnt vmcnt(0)
	ds_write_b128 v0, v[128:131] offset:27648
	s_cmp_eq_u32 s0, s24
	s_waitcnt lgkmcnt(0)
	s_barrier
	v_mfma_f32_32x32x16_bf16 v[32:47], v[156:159], v[104:107], v[32:47]
	v_mfma_f32_32x32x16_bf16 v[16:31], v[160:163], v[104:107], v[16:31]
	s_cbranch_scc1 .LBB0_501

;     __device__ __forceinline__ unsigned* BAR() const { return (unsigned*)(ws + OFF_BAR); }
; #define STAGE(bufoff, gbase, voff) do { _Pragma("unroll") for (int _i = 0; _i < 2; ++_i) \
;         __builtin_amdgcn_global_load_lds((const unsigned*)((const char*)(gbase) + voff[_i]), (LAS unsigned*)(lds + (bufoff) + ldsw + _i * 8192), 16, 0, 0); } while (0)
; #define LDA(dst, b, h) do { _Pragma("unroll") for (int m = 0; m < 4; ++m) _Pragma("unroll") for (int k = 0; k < 2; ++k) dst[m][k] = *(const LAS bf16x8*)(lds + SA(b, h) + aoff + m * 2048 + k * 1024); } while (0)
; #define LDB(dst, b, h) do { _Pragma("unroll") for (int n = 0; n < 2; ++n) _Pragma("unroll") for (int k = 0; k < 2; ++k) dst[n][k] = *(const LAS bf16x8*)(lds + SB(b, h) + boff + n * 2048 + k * 1024); } while (0)
; #define MMA(ai, bj, At, Bx) do { __builtin_amdgcn_s_setprio(1); _Pragma("unroll") for (int m = 0; m < 4; ++m) _Pragma("unroll") for (int n = 0; n < 2; ++n) _Pragma("unroll") for (int k = 0; k < 2; ++k) \
;       acc[ai][bj][m][n] = __builtin_amdgcn_mfma_f32_16x16x32_bf16(At[m][k], Bx[n][k], acc[ai][bj][m][n], 0, 0, 0); \
;     __builtin_amdgcn_s_setprio(0); } while (0)
; #define WAIT_L(n) asm volatile("s_waitcnt lgkmcnt(" #n ")" ::: "memory")
; #define BAR __builtin_amdgcn_s_barrier()
; #define SCHED __builtin_amdgcn_sched_barrier(0)
;     ...
;     for (int t = 0; t < nt - 2; t += 2) {
;         if (KSEG && t > 0 && (t % (KSEG ? KSEG : 1)) == 0) hook(t / (KSEG ? KSEG : 1), acc);
;         const char* a1 = pA(t + 1); const char* a2 = pA(t + 2); const char* a3 = pA(t + 3);
;         const char* b2 = pB(t + 2); const char* b3 = pB(t + 3);
;         LDB(B0, 0, 0); SCHED; LDA(At, 0, 0); STAGE(SA(1, 1), a1 + hstepA, voffA);
;         WAIT_L(8); BAR; WAIT_L(0); MMA(0, 0, At, B0); BAR; SCHED;
;         LDB(B1, 0, 1); STAGE(SB(0, 0), b2, voffB);
;         BAR; WAIT_L(0); MMA(0, 1, At, B1); BAR;
;         LDA(At, 0, 1); STAGE(SA(0, 0), a2, voffA);
.LBB0_574:
	s_add_i32 s10, s12, 4
	s_lshr_b32 s24, s10, 3
	s_and_b32 s17, s43, 0x300000
	s_and_b32 vcc_lo, s8, 0x300
	s_lshl_b64 s[14:15], s[24:25], 20
	s_add_u32 s10, s8, 0x100
	s_addc_u32 s11, s9, 0
	s_add_i32 s9, s12, 5
	s_lshr_b32 s12, s9, 3
	s_mov_b32 s13, s25
	s_addk_i32 s8, 0x180
	s_and_b32 s94, s10, 0x300
	s_lshl_b64 s[92:93], s[12:13], 20
	s_and_b32 vcc_hi, s8, 0x380
	s_mul_i32 s9, s24, 0x1200000
	s_mul_hi_u32 s8, s24, 0x1200000
	s_add_u32 s9, s6, s9
	s_addc_u32 s8, s7, s8
	s_mul_hi_u32 s13, s12, 0x1200000
	s_mul_i32 s12, s12, 0x1200000
	s_add_u32 s55, s6, s12
	s_addc_u32 s16, s7, s13
	s_add_i32 s45, 0, 0x10000
	v_add_u32_e32 v138, s45, v143
	ds_read_b128 v[130:133], v138
	ds_read_b128 v[134:137], v138 offset:1024
	ds_read_b128 v[144:147], v138 offset:2048
	ds_read_b128 v[148:151], v138 offset:3072
	s_add_u32 s12, s4, s17
	s_addc_u32 s13, s5, 0
	s_add_u32 s17, s4, s14
	s_addc_u32 s23, s5, s15
	s_add_u32 s24, s4, s92
	s_addc_u32 s92, s5, s93
	s_add_u32 s14, s9, s94
	s_addc_u32 s15, s8, 0
	s_add_u32 s12, s12, vcc_lo
	s_addc_u32 s13, s13, 0
	s_add_u32 s8, s24, vcc_hi
	s_addc_u32 s9, s92, 0
	s_add_u32 s12, s12, 0x20080
	s_addc_u32 s13, s13, 0
	s_add_i32 vcc_lo, s75, 0xc000
	v_lshl_add_u64 v[138:139], s[12:13], 0, v[0:1]
	s_mov_b32 m0, vcc_lo
	s_add_i32 s24, s75, 0xe000
	ds_read_b128 v[152:155], v142
	ds_read_b128 v[156:159], v142 offset:1024
	ds_read_b128 v[160:163], v142 offset:2048
	ds_read_b128 v[164:167], v142 offset:3072
	ds_read_b128 v[190:193], v142 offset:4096
	ds_read_b128 v[194:197], v142 offset:5120
	ds_read_b128 v[198:201], v142 offset:6144
	ds_read_b128 v[202:205], v142 offset:7168
	global_load_lds_dwordx4 v[138:139], off
	v_lshl_add_u64 v[138:139], s[12:13], 0, v[140:141]
	s_mov_b32 m0, s24
	s_add_u32 s12, s17, s94
	global_load_lds_dwordx4 v[138:139], off
	s_waitcnt lgkmcnt(8)
	s_barrier
	s_waitcnt lgkmcnt(0)
	s_addc_u32 s13, s23, 0
	s_waitcnt lgkmcnt(0)
	v_mfma_f32_16x16x32_bf16 v[126:129], v[152:155], v[130:133], v[126:129]
	v_mfma_f32_16x16x32_bf16 v[122:125], v[152:155], v[144:147], v[122:125]
	v_mfma_f32_16x16x32_bf16 v[118:121], v[160:163], v[130:133], v[118:121]
	v_mfma_f32_16x16x32_bf16 v[114:117], v[160:163], v[144:147], v[114:117]
	v_mfma_f32_16x16x32_bf16 v[110:113], v[190:193], v[130:133], v[110:113]
	v_mfma_f32_16x16x32_bf16 v[106:109], v[190:193], v[144:147], v[106:109]
	v_mfma_f32_16x16x32_bf16 v[102:105], v[198:201], v[130:133], v[102:105]
	v_mfma_f32_16x16x32_bf16 v[98:101], v[198:201], v[144:147], v[98:101]
	v_mfma_f32_16x16x32_bf16 v[126:129], v[156:159], v[134:137], v[126:129]
	v_mfma_f32_16x16x32_bf16 v[122:125], v[156:159], v[148:151], v[122:125]
	v_mfma_f32_16x16x32_bf16 v[118:121], v[164:167], v[134:137], v[118:121]
	v_mfma_f32_16x16x32_bf16 v[114:117], v[164:167], v[148:151], v[114:117]
	v_mfma_f32_16x16x32_bf16 v[110:113], v[194:197], v[134:137], v[110:113]
	v_mfma_f32_16x16x32_bf16 v[106:109], v[194:197], v[148:151], v[106:109]
	v_mfma_f32_16x16x32_bf16 v[102:105], v[202:205], v[134:137], v[102:105]
	v_mfma_f32_16x16x32_bf16 v[98:101], v[202:205], v[148:151], v[98:101]
	s_barrier
	s_add_i32 s17, 0, 0x14000
	v_add_u32_e32 v138, s17, v143
	s_add_i32 s23, s45, s1
	ds_read_b128 v[206:209], v138
	ds_read_b128 v[210:213], v138 offset:1024
	ds_read_b128 v[214:217], v138 offset:2048
	ds_read_b128 v[218:221], v138 offset:3072
	v_lshl_add_u64 v[138:139], s[14:15], 0, v[0:1]
	s_mov_b32 m0, s23
	s_nop 0
	global_load_lds_dwordx4 v[138:139], off
	v_lshl_add_u64 v[138:139], s[14:15], 0, v[140:141]
	s_add_i32 m0, s23, 0x2000
	s_nop 0
	global_load_lds_dwordx4 v[138:139], off
	s_barrier
	s_waitcnt lgkmcnt(0)
	v_mfma_f32_16x16x32_bf16 v[94:97], v[152:155], v[206:209], v[94:97]
	v_mfma_f32_16x16x32_bf16 v[90:93], v[152:155], v[214:217], v[90:93]
	v_mfma_f32_16x16x32_bf16 v[86:89], v[160:163], v[206:209], v[86:89]
	v_mfma_f32_16x16x32_bf16 v[82:85], v[160:163], v[214:217], v[82:85]
	v_mfma_f32_16x16x32_bf16 v[78:81], v[190:193], v[206:209], v[78:81]
	v_mfma_f32_16x16x32_bf16 v[74:77], v[190:193], v[214:217], v[74:77]
	v_mfma_f32_16x16x32_bf16 v[70:73], v[198:201], v[206:209], v[70:73]
	v_mfma_f32_16x16x32_bf16 v[66:69], v[198:201], v[214:217], v[66:69]
	v_mfma_f32_16x16x32_bf16 v[94:97], v[156:159], v[210:213], v[94:97]
	v_mfma_f32_16x16x32_bf16 v[90:93], v[156:159], v[218:221], v[90:93]
	v_mfma_f32_16x16x32_bf16 v[86:89], v[164:167], v[210:213], v[86:89]
	v_mfma_f32_16x16x32_bf16 v[82:85], v[164:167], v[218:221], v[82:85]
	v_mfma_f32_16x16x32_bf16 v[78:81], v[194:197], v[210:213], v[78:81]
	v_mfma_f32_16x16x32_bf16 v[74:77], v[194:197], v[218:221], v[74:77]
	v_mfma_f32_16x16x32_bf16 v[70:73], v[202:205], v[210:213], v[70:73]
	v_mfma_f32_16x16x32_bf16 v[66:69], v[202:205], v[218:221], v[66:69]
	s_barrier
	s_mov_b32 m0, s75
	v_lshl_add_u64 v[138:139], s[12:13], 0, v[0:1]
	ds_read_b128 v[152:155], v142 offset:16384
	ds_read_b128 v[156:159], v142 offset:17408
	ds_read_b128 v[160:163], v142 offset:18432
	ds_read_b128 v[164:167], v142 offset:19456
	ds_read_b128 v[190:193], v142 offset:20480
	ds_read_b128 v[194:197], v142 offset:21504
	ds_read_b128 v[198:201], v142 offset:22528
	ds_read_b128 v[202:205], v142 offset:23552
	global_load_lds_dwordx4 v[138:139], off
	v_lshl_add_u64 v[138:139], s[12:13], 0, v[140:141]
	s_mov_b32 m0, s76
	s_nop 0
	global_load_lds_dwordx4 v[138:139], off
	s_barrier
;     __device__ __forceinline__ unsigned* BAR() const { return (unsigned*)(ws + OFF_BAR); }
; #define STAGE(bufoff, gbase, voff) do { _Pragma("unroll") for (int _i = 0; _i < 2; ++_i) \
;         __builtin_amdgcn_global_load_lds((const unsigned*)((const char*)(gbase) + voff[_i]), (LAS unsigned*)(lds + (bufoff) + ldsw + _i * 8192), 16, 0, 0); } while (0)
; #define LDA(dst, b, h) do { _Pragma("unroll") for (int m = 0; m < 4; ++m) _Pragma("unroll") for (int k = 0; k < 2; ++k) dst[m][k] = *(const LAS bf16x8*)(lds + SA(b, h) + aoff + m * 2048 + k * 1024); } while (0)
; #define LDB(dst, b, h) do { _Pragma("unroll") for (int n = 0; n < 2; ++n) _Pragma("unroll") for (int k = 0; k < 2; ++k) dst[n][k] = *(const LAS bf16x8*)(lds + SB(b, h) + boff + n * 2048 + k * 1024); } while (0)
; #define MMA(ai, bj, At, Bx) do { __builtin_amdgcn_s_setprio(1); _Pragma("unroll") for (int m = 0; m < 4; ++m) _Pragma("unroll") for (int n = 0; n < 2; ++n) _Pragma("unroll") for (int k = 0; k < 2; ++k) \
;       acc[ai][bj][m][n] = __builtin_amdgcn_mfma_f32_16x16x32_bf16(At[m][k], Bx[n][k], acc[ai][bj][m][n], 0, 0, 0); \
;     __builtin_amdgcn_s_setprio(0); } while (0)
; #define WAIT_V(n) asm volatile("s_waitcnt vmcnt(" #n ")" ::: "memory")
; #define WAIT_L(n) asm volatile("s_waitcnt lgkmcnt(" #n ")" ::: "memory")
; #define BAR __builtin_amdgcn_s_barrier()
; #define SCHED __builtin_amdgcn_sched_barrier(0)
;     ...
;         BAR; WAIT_L(0); MMA(1, 0, At, B0); BAR; SCHED;
;         STAGE(SB(0, 1), b2 + hstepB, voffB);
;         WAIT_V(6); BAR; MMA(1, 1, At, B1); BAR;
;         LDB(B0, 1, 0); SCHED; LDA(At, 1, 0); STAGE(SA(0, 1), a2 + hstepA, voffA);
;         WAIT_L(8); BAR; WAIT_L(0); MMA(0, 0, At, B0); BAR; SCHED;
;         LDB(B1, 1, 1); STAGE(SB(1, 0), b3, voffB);
	s_waitcnt lgkmcnt(0)
	v_mfma_f32_16x16x32_bf16 v[62:65], v[152:155], v[130:133], v[62:65]
	v_mfma_f32_16x16x32_bf16 v[58:61], v[152:155], v[144:147], v[58:61]
	v_mfma_f32_16x16x32_bf16 v[54:57], v[160:163], v[130:133], v[54:57]
	v_mfma_f32_16x16x32_bf16 v[50:53], v[160:163], v[144:147], v[50:53]
	v_mfma_f32_16x16x32_bf16 v[46:49], v[190:193], v[130:133], v[46:49]
	v_mfma_f32_16x16x32_bf16 v[42:45], v[190:193], v[144:147], v[42:45]
	v_mfma_f32_16x16x32_bf16 v[38:41], v[198:201], v[130:133], v[38:41]
	v_mfma_f32_16x16x32_bf16 v[34:37], v[198:201], v[144:147], v[34:37]
	v_mfma_f32_16x16x32_bf16 v[62:65], v[156:159], v[134:137], v[62:65]
	v_mfma_f32_16x16x32_bf16 v[58:61], v[156:159], v[148:151], v[58:61]
	v_mfma_f32_16x16x32_bf16 v[54:57], v[164:167], v[134:137], v[54:57]
	v_mfma_f32_16x16x32_bf16 v[50:53], v[164:167], v[148:151], v[50:53]
	v_mfma_f32_16x16x32_bf16 v[46:49], v[194:197], v[134:137], v[46:49]
	v_mfma_f32_16x16x32_bf16 v[42:45], v[194:197], v[148:151], v[42:45]
	v_mfma_f32_16x16x32_bf16 v[38:41], v[202:205], v[134:137], v[38:41]
	v_mfma_f32_16x16x32_bf16 v[34:37], v[202:205], v[148:151], v[34:37]
	s_barrier
	s_add_u32 s14, s14, 0x20000
	s_addc_u32 s15, s15, 0
	s_add_i32 s17, s17, s1
	v_lshl_add_u64 v[130:131], s[14:15], 0, v[0:1]
	s_mov_b32 m0, s17
	s_nop 0
	global_load_lds_dwordx4 v[130:131], off
	v_lshl_add_u64 v[130:131], s[14:15], 0, v[140:141]
	s_add_i32 m0, s17, 0x2000
	s_nop 0
	global_load_lds_dwordx4 v[130:131], off
	s_waitcnt vmcnt(6)
	s_barrier
	v_mfma_f32_16x16x32_bf16 v[30:33], v[152:155], v[206:209], v[30:33]
	v_mfma_f32_16x16x32_bf16 v[26:29], v[152:155], v[214:217], v[26:29]
	v_mfma_f32_16x16x32_bf16 v[22:25], v[160:163], v[206:209], v[22:25]
	v_mfma_f32_16x16x32_bf16 v[18:21], v[160:163], v[214:217], v[18:21]
	v_mfma_f32_16x16x32_bf16 v[14:17], v[190:193], v[206:209], v[14:17]
	v_mfma_f32_16x16x32_bf16 v[10:13], v[190:193], v[214:217], v[10:13]
	v_mfma_f32_16x16x32_bf16 v[6:9], v[198:201], v[206:209], v[6:9]
	v_mfma_f32_16x16x32_bf16 v[2:5], v[198:201], v[214:217], v[2:5]
	v_mfma_f32_16x16x32_bf16 v[30:33], v[156:159], v[210:213], v[30:33]
	v_mfma_f32_16x16x32_bf16 v[26:29], v[156:159], v[218:221], v[26:29]
	v_mfma_f32_16x16x32_bf16 v[22:25], v[164:167], v[210:213], v[22:25]
	v_mfma_f32_16x16x32_bf16 v[18:21], v[164:167], v[218:221], v[18:21]
	v_mfma_f32_16x16x32_bf16 v[14:17], v[194:197], v[210:213], v[14:17]
	v_mfma_f32_16x16x32_bf16 v[10:13], v[194:197], v[218:221], v[10:13]
	v_mfma_f32_16x16x32_bf16 v[6:9], v[202:205], v[210:213], v[6:9]
	v_mfma_f32_16x16x32_bf16 v[2:5], v[202:205], v[218:221], v[2:5]
	s_barrier
	s_add_i32 s14, 0, 0x18000
	v_add_u32_e32 v138, s14, v143
	ds_read_b128 v[130:133], v138
	ds_read_b128 v[134:137], v138 offset:1024
	ds_read_b128 v[144:147], v138 offset:2048
	ds_read_b128 v[148:151], v138 offset:3072
	s_add_u32 s12, s12, 0x20000
	s_addc_u32 s13, s13, 0
	s_mov_b32 m0, s77
	v_lshl_add_u64 v[138:139], s[12:13], 0, v[0:1]
	ds_read_b128 v[152:155], v142 offset:32768
	ds_read_b128 v[156:159], v142 offset:33792
	ds_read_b128 v[160:163], v142 offset:34816
	ds_read_b128 v[164:167], v142 offset:35840
	ds_read_b128 v[190:193], v142 offset:36864
	ds_read_b128 v[194:197], v142 offset:37888
	ds_read_b128 v[198:201], v142 offset:38912
	ds_read_b128 v[202:205], v142 offset:39936
	global_load_lds_dwordx4 v[138:139], off
	v_lshl_add_u64 v[138:139], s[12:13], 0, v[140:141]
	s_mov_b32 m0, s88
	s_nop 0
	global_load_lds_dwordx4 v[138:139], off
	s_waitcnt lgkmcnt(8)
	s_barrier
	s_waitcnt lgkmcnt(0)
	v_mfma_f32_16x16x32_bf16 v[126:129], v[152:155], v[130:133], v[126:129]
	v_mfma_f32_16x16x32_bf16 v[122:125], v[152:155], v[144:147], v[122:125]
	v_mfma_f32_16x16x32_bf16 v[118:121], v[160:163], v[130:133], v[118:121]
	v_mfma_f32_16x16x32_bf16 v[114:117], v[160:163], v[144:147], v[114:117]
	v_mfma_f32_16x16x32_bf16 v[110:113], v[190:193], v[130:133], v[110:113]
	v_mfma_f32_16x16x32_bf16 v[106:109], v[190:193], v[144:147], v[106:109]
	v_mfma_f32_16x16x32_bf16 v[102:105], v[198:201], v[130:133], v[102:105]
	v_mfma_f32_16x16x32_bf16 v[98:101], v[198:201], v[144:147], v[98:101]
	v_mfma_f32_16x16x32_bf16 v[126:129], v[156:159], v[134:137], v[126:129]
	v_mfma_f32_16x16x32_bf16 v[122:125], v[156:159], v[148:151], v[122:125]
	v_mfma_f32_16x16x32_bf16 v[118:121], v[164:167], v[134:137], v[118:121]
	v_mfma_f32_16x16x32_bf16 v[114:117], v[164:167], v[148:151], v[114:117]
	v_mfma_f32_16x16x32_bf16 v[110:113], v[194:197], v[134:137], v[110:113]
	v_mfma_f32_16x16x32_bf16 v[106:109], v[194:197], v[148:151], v[106:109]
	v_mfma_f32_16x16x32_bf16 v[102:105], v[202:205], v[134:137], v[102:105]
	v_mfma_f32_16x16x32_bf16 v[98:101], v[202:205], v[148:151], v[98:101]
	s_barrier
;     __device__ __forceinline__ unsigned* BAR() const { return (unsigned*)(ws + OFF_BAR); }
; #define STAGE(bufoff, gbase, voff) do { _Pragma("unroll") for (int _i = 0; _i < 2; ++_i) \
;         __builtin_amdgcn_global_load_lds((const unsigned*)((const char*)(gbase) + voff[_i]), (LAS unsigned*)(lds + (bufoff) + ldsw + _i * 8192), 16, 0, 0); } while (0)
; #define LDA(dst, b, h) do { _Pragma("unroll") for (int m = 0; m < 4; ++m) _Pragma("unroll") for (int k = 0; k < 2; ++k) dst[m][k] = *(const LAS bf16x8*)(lds + SA(b, h) + aoff + m * 2048 + k * 1024); } while (0)
; #define LDB(dst, b, h) do { _Pragma("unroll") for (int n = 0; n < 2; ++n) _Pragma("unroll") for (int k = 0; k < 2; ++k) dst[n][k] = *(const LAS bf16x8*)(lds + SB(b, h) + boff + n * 2048 + k * 1024); } while (0)
; #define MMA(ai, bj, At, Bx) do { __builtin_amdgcn_s_setprio(1); _Pragma("unroll") for (int m = 0; m < 4; ++m) _Pragma("unroll") for (int n = 0; n < 2; ++n) _Pragma("unroll") for (int k = 0; k < 2; ++k) \
;       acc[ai][bj][m][n] = __builtin_amdgcn_mfma_f32_16x16x32_bf16(At[m][k], Bx[n][k], acc[ai][bj][m][n], 0, 0, 0); \
;     __builtin_amdgcn_s_setprio(0); } while (0)
; #define WAIT_V(n) asm volatile("s_waitcnt vmcnt(" #n ")" ::: "memory")
; #define WAIT_L(n) asm volatile("s_waitcnt lgkmcnt(" #n ")" ::: "memory")
; #define BAR __builtin_amdgcn_s_barrier()
; #define SCHED __builtin_amdgcn_sched_barrier(0)
;     ...
;         LDB(B1, 1, 1); STAGE(SB(1, 0), b3, voffB);
;         BAR; WAIT_L(0); MMA(0, 1, At, B1); BAR;
;         LDA(At, 1, 1); STAGE(SA(1, 0), a3, voffA);
;         BAR; WAIT_L(0); MMA(1, 0, At, B0); BAR; SCHED;
;         STAGE(SB(1, 1), b3 + hstepB, voffB);
;         WAIT_V(6); BAR; MMA(1, 1, At, B1); BAR;
;     }
	s_add_i32 s15, 0, 0x1c000
	s_add_u32 s12, s55, vcc_hi
	v_add_u32_e32 v138, s15, v143
	s_addc_u32 s13, s16, 0
	s_add_i32 s14, s14, s1
	ds_read_b128 v[206:209], v138
	ds_read_b128 v[210:213], v138 offset:1024
	ds_read_b128 v[214:217], v138 offset:2048
	ds_read_b128 v[218:221], v138 offset:3072
	v_lshl_add_u64 v[138:139], s[12:13], 0, v[0:1]
	s_mov_b32 m0, s14
	s_nop 0
	global_load_lds_dwordx4 v[138:139], off
	v_lshl_add_u64 v[138:139], s[12:13], 0, v[140:141]
	s_add_i32 m0, s14, 0x2000
	s_nop 0
	global_load_lds_dwordx4 v[138:139], off
	s_barrier
	s_waitcnt lgkmcnt(0)
	v_mfma_f32_16x16x32_bf16 v[94:97], v[152:155], v[206:209], v[94:97]
	v_mfma_f32_16x16x32_bf16 v[90:93], v[152:155], v[214:217], v[90:93]
	v_mfma_f32_16x16x32_bf16 v[86:89], v[160:163], v[206:209], v[86:89]
	v_mfma_f32_16x16x32_bf16 v[82:85], v[160:163], v[214:217], v[82:85]
	v_mfma_f32_16x16x32_bf16 v[78:81], v[190:193], v[206:209], v[78:81]
	v_mfma_f32_16x16x32_bf16 v[74:77], v[190:193], v[214:217], v[74:77]
	v_mfma_f32_16x16x32_bf16 v[70:73], v[198:201], v[206:209], v[70:73]
	v_mfma_f32_16x16x32_bf16 v[66:69], v[198:201], v[214:217], v[66:69]
	v_mfma_f32_16x16x32_bf16 v[94:97], v[156:159], v[210:213], v[94:97]
	v_mfma_f32_16x16x32_bf16 v[90:93], v[156:159], v[218:221], v[90:93]
	v_mfma_f32_16x16x32_bf16 v[86:89], v[164:167], v[210:213], v[86:89]
	v_mfma_f32_16x16x32_bf16 v[82:85], v[164:167], v[218:221], v[82:85]
	v_mfma_f32_16x16x32_bf16 v[78:81], v[194:197], v[210:213], v[78:81]
	v_mfma_f32_16x16x32_bf16 v[74:77], v[194:197], v[218:221], v[74:77]
	v_mfma_f32_16x16x32_bf16 v[70:73], v[202:205], v[210:213], v[70:73]
	v_mfma_f32_16x16x32_bf16 v[66:69], v[202:205], v[218:221], v[66:69]
	s_barrier
	s_mov_b32 m0, s31
	v_lshl_add_u64 v[138:139], s[8:9], 0, v[0:1]
	ds_read_b128 v[152:155], v142 offset:49152
	ds_read_b128 v[156:159], v142 offset:50176
	ds_read_b128 v[160:163], v142 offset:51200
	ds_read_b128 v[164:167], v142 offset:52224
	ds_read_b128 v[190:193], v142 offset:53248
	ds_read_b128 v[194:197], v142 offset:54272
	ds_read_b128 v[198:201], v142 offset:55296
	ds_read_b128 v[202:205], v142 offset:56320
	global_load_lds_dwordx4 v[138:139], off
	v_lshl_add_u64 v[138:139], s[8:9], 0, v[140:141]
	s_mov_b32 m0, s27
	s_nop 0
	global_load_lds_dwordx4 v[138:139], off
	s_barrier
	s_waitcnt lgkmcnt(0)
	v_mfma_f32_16x16x32_bf16 v[62:65], v[152:155], v[130:133], v[62:65]
	v_mfma_f32_16x16x32_bf16 v[58:61], v[152:155], v[144:147], v[58:61]
	v_mfma_f32_16x16x32_bf16 v[54:57], v[160:163], v[130:133], v[54:57]
	v_mfma_f32_16x16x32_bf16 v[50:53], v[160:163], v[144:147], v[50:53]
	v_mfma_f32_16x16x32_bf16 v[46:49], v[190:193], v[130:133], v[46:49]
	v_mfma_f32_16x16x32_bf16 v[42:45], v[190:193], v[144:147], v[42:45]
	v_mfma_f32_16x16x32_bf16 v[38:41], v[198:201], v[130:133], v[38:41]
	v_mfma_f32_16x16x32_bf16 v[34:37], v[198:201], v[144:147], v[34:37]
	v_mfma_f32_16x16x32_bf16 v[62:65], v[156:159], v[134:137], v[62:65]
	v_mfma_f32_16x16x32_bf16 v[58:61], v[156:159], v[148:151], v[58:61]
	v_mfma_f32_16x16x32_bf16 v[54:57], v[164:167], v[134:137], v[54:57]
	v_mfma_f32_16x16x32_bf16 v[50:53], v[164:167], v[148:151], v[50:53]
	v_mfma_f32_16x16x32_bf16 v[46:49], v[194:197], v[134:137], v[46:49]
	v_mfma_f32_16x16x32_bf16 v[42:45], v[194:197], v[148:151], v[42:45]
	v_mfma_f32_16x16x32_bf16 v[38:41], v[202:205], v[134:137], v[38:41]
	v_mfma_f32_16x16x32_bf16 v[34:37], v[202:205], v[148:151], v[34:37]
	s_barrier
	s_add_u32 s8, s12, 0x20000
	s_addc_u32 s9, s13, 0
	s_add_i32 s12, s15, s1
	v_lshl_add_u64 v[130:131], s[8:9], 0, v[0:1]
	s_mov_b32 m0, s12
	s_nop 0
	global_load_lds_dwordx4 v[130:131], off
	v_lshl_add_u64 v[130:131], s[8:9], 0, v[140:141]
	s_add_i32 m0, s12, 0x2000
	s_nop 0
	global_load_lds_dwordx4 v[130:131], off
	s_waitcnt vmcnt(6)
	s_barrier
	v_mfma_f32_16x16x32_bf16 v[30:33], v[152:155], v[206:209], v[30:33]
	v_mfma_f32_16x16x32_bf16 v[26:29], v[152:155], v[214:217], v[26:29]
	v_mfma_f32_16x16x32_bf16 v[22:25], v[160:163], v[206:209], v[22:25]
	v_mfma_f32_16x16x32_bf16 v[18:21], v[160:163], v[214:217], v[18:21]
	v_mfma_f32_16x16x32_bf16 v[14:17], v[190:193], v[206:209], v[14:17]
	v_mfma_f32_16x16x32_bf16 v[10:13], v[190:193], v[214:217], v[10:13]
	v_mfma_f32_16x16x32_bf16 v[6:9], v[198:201], v[206:209], v[6:9]
	v_mfma_f32_16x16x32_bf16 v[2:5], v[198:201], v[214:217], v[2:5]
	v_mfma_f32_16x16x32_bf16 v[30:33], v[156:159], v[210:213], v[30:33]
	v_mfma_f32_16x16x32_bf16 v[26:29], v[156:159], v[218:221], v[26:29]
	v_mfma_f32_16x16x32_bf16 v[22:25], v[164:167], v[210:213], v[22:25]
	v_mfma_f32_16x16x32_bf16 v[18:21], v[164:167], v[218:221], v[18:21]
	v_mfma_f32_16x16x32_bf16 v[14:17], v[194:197], v[210:213], v[14:17]
	v_mfma_f32_16x16x32_bf16 v[10:13], v[194:197], v[218:221], v[10:13]
	v_mfma_f32_16x16x32_bf16 v[6:9], v[202:205], v[210:213], v[6:9]
	v_mfma_f32_16x16x32_bf16 v[2:5], v[202:205], v[218:221], v[2:5]
	s_barrier
	s_add_i32 s43, s43, 0x40000
	s_cmp_gt_u32 s54, 19
	s_cbranch_scc1 .LBB0_576
	s_mov_b32 s12, s54
	s_mov_b64 s[8:9], s[10:11]
	s_branch .LBB0_572

;     __device__ __forceinline__ unsigned* BAR() const { return (unsigned*)(ws + OFF_BAR); }
; #define STAGE(bufoff, gbase, voff) do { _Pragma("unroll") for (int _i = 0; _i < 2; ++_i) \
;         __builtin_amdgcn_global_load_lds((const unsigned*)((const char*)(gbase) + voff[_i]), (LAS unsigned*)(lds + (bufoff) + ldsw + _i * 8192), 16, 0, 0); } while (0)
; #define LDA(dst, b, h) do { _Pragma("unroll") for (int m = 0; m < 4; ++m) _Pragma("unroll") for (int k = 0; k < 2; ++k) dst[m][k] = *(const LAS bf16x8*)(lds + SA(b, h) + aoff + m * 2048 + k * 1024); } while (0)
; #define LDB(dst, b, h) do { _Pragma("unroll") for (int n = 0; n < 2; ++n) _Pragma("unroll") for (int k = 0; k < 2; ++k) dst[n][k] = *(const LAS bf16x8*)(lds + SB(b, h) + boff + n * 2048 + k * 1024); } while (0)
; #define MMA(ai, bj, At, Bx) do { __builtin_amdgcn_s_setprio(1); _Pragma("unroll") for (int m = 0; m < 4; ++m) _Pragma("unroll") for (int n = 0; n < 2; ++n) _Pragma("unroll") for (int k = 0; k < 2; ++k) \
;       acc[ai][bj][m][n] = __builtin_amdgcn_mfma_f32_16x16x32_bf16(At[m][k], Bx[n][k], acc[ai][bj][m][n], 0, 0, 0); \
;     __builtin_amdgcn_s_setprio(0); } while (0)
; #define WAIT_V(n) asm volatile("s_waitcnt vmcnt(" #n ")" ::: "memory")
; #define WAIT_L(n) asm volatile("s_waitcnt lgkmcnt(" #n ")" ::: "memory")
; #define BAR __builtin_amdgcn_s_barrier()
; #define SCHED __builtin_amdgcn_sched_barrier(0)
;     ...
;         const char* a1 = pA(t + 1); const char* a2 = pA(t + 2); const char* a3 = pA(t + 3);
;         const char* b2 = pB(t + 2); const char* b3 = pB(t + 3);
;         LDB(B0, 0, 0); SCHED; LDA(At, 0, 0); STAGE(SA(1, 1), a1 + hstepA, voffA);
;         WAIT_L(8); BAR; WAIT_L(0); MMA(0, 0, At, B0); BAR; SCHED;
;         LDB(B1, 0, 1); STAGE(SB(0, 0), b2, voffB);
;         BAR; WAIT_L(0); MMA(0, 1, At, B1); BAR;
;         LDA(At, 0, 1); STAGE(SA(0, 0), a2, voffA);
;         BAR; WAIT_L(0); MMA(1, 0, At, B0); BAR; SCHED;
;         STAGE(SB(0, 1), b2 + hstepB, voffB);
;         WAIT_V(6); BAR; MMA(1, 1, At, B1); BAR;
.LBB0_617:
	s_add_i32 s16, 0, 0x10000
	v_add_u32_e32 v138, s16, v143
	ds_read_b128 v[144:147], v138
	ds_read_b128 v[148:151], v138 offset:1024
	ds_read_b128 v[152:155], v138 offset:2048
	ds_read_b128 v[156:159], v138 offset:3072
	v_lshl_add_u64 v[138:139], s[8:9], 0, v[136:137]
	s_add_i32 s88, s42, 0xc000
	v_lshl_add_u64 v[214:215], v[138:139], 0, s[84:85]
	s_mov_b32 m0, s88
	v_lshl_add_u64 v[230:231], s[8:9], 0, v[140:141]
	s_add_i32 s11, s42, 0xe000
	ds_read_b128 v[160:163], v142
	ds_read_b128 v[164:167], v142 offset:1024
	ds_read_b128 v[190:193], v142 offset:2048
	ds_read_b128 v[194:197], v142 offset:3072
	ds_read_b128 v[198:201], v142 offset:4096
	ds_read_b128 v[202:205], v142 offset:5120
	ds_read_b128 v[206:209], v142 offset:6144
	ds_read_b128 v[210:213], v142 offset:7168
	global_load_lds_dwordx4 v[214:215], off
	v_lshl_add_u64 v[214:215], v[230:231], 0, s[84:85]
	s_mov_b32 m0, s11
	s_nop 0
	global_load_lds_dwordx4 v[214:215], off
	s_waitcnt lgkmcnt(8)
	s_barrier
	s_waitcnt lgkmcnt(0)
	v_mfma_f32_16x16x32_bf16 v[126:129], v[160:163], v[144:147], v[126:129]
	v_mfma_f32_16x16x32_bf16 v[122:125], v[160:163], v[152:155], v[122:125]
	v_mfma_f32_16x16x32_bf16 v[118:121], v[190:193], v[144:147], v[118:121]
	v_mfma_f32_16x16x32_bf16 v[114:117], v[190:193], v[152:155], v[114:117]
	v_mfma_f32_16x16x32_bf16 v[110:113], v[198:201], v[144:147], v[110:113]
	v_mfma_f32_16x16x32_bf16 v[106:109], v[198:201], v[152:155], v[106:109]
	v_mfma_f32_16x16x32_bf16 v[102:105], v[206:209], v[144:147], v[102:105]
	v_mfma_f32_16x16x32_bf16 v[98:101], v[206:209], v[152:155], v[98:101]
	v_mfma_f32_16x16x32_bf16 v[126:129], v[164:167], v[148:151], v[126:129]
	v_mfma_f32_16x16x32_bf16 v[122:125], v[164:167], v[156:159], v[122:125]
	v_mfma_f32_16x16x32_bf16 v[118:121], v[194:197], v[148:151], v[118:121]
	v_mfma_f32_16x16x32_bf16 v[114:117], v[194:197], v[156:159], v[114:117]
	v_mfma_f32_16x16x32_bf16 v[110:113], v[202:205], v[148:151], v[110:113]
	v_mfma_f32_16x16x32_bf16 v[106:109], v[202:205], v[156:159], v[106:109]
	v_mfma_f32_16x16x32_bf16 v[102:105], v[210:213], v[148:151], v[102:105]
	v_mfma_f32_16x16x32_bf16 v[98:101], v[210:213], v[156:159], v[98:101]
	s_barrier
	s_add_i32 s17, 0, 0x14000
	v_lshl_add_u64 v[232:233], s[8:9], 0, v[132:133]
	s_add_i32 s16, s16, s15
	v_add_u32_e32 v226, s17, v143
	v_lshl_add_u64 v[234:235], v[232:233], 0, s[52:53]
	s_mov_b32 m0, s16
	ds_read_b128 v[214:217], v226
	ds_read_b128 v[218:221], v226 offset:1024
	ds_read_b128 v[222:225], v226 offset:2048
	ds_read_b128 v[226:229], v226 offset:3072
	global_load_lds_dwordx4 v[234:235], off
	v_lshl_add_u64 v[234:235], s[8:9], 0, v[134:135]
	v_lshl_add_u64 v[236:237], v[234:235], 0, s[52:53]
	s_add_i32 m0, s16, 0x2000
	s_nop 0
	global_load_lds_dwordx4 v[236:237], off
	s_barrier
	s_waitcnt lgkmcnt(0)
	v_mfma_f32_16x16x32_bf16 v[94:97], v[160:163], v[214:217], v[94:97]
	v_mfma_f32_16x16x32_bf16 v[90:93], v[160:163], v[222:225], v[90:93]
	v_mfma_f32_16x16x32_bf16 v[86:89], v[190:193], v[214:217], v[86:89]
	v_mfma_f32_16x16x32_bf16 v[82:85], v[190:193], v[222:225], v[82:85]
	v_mfma_f32_16x16x32_bf16 v[78:81], v[198:201], v[214:217], v[78:81]
	v_mfma_f32_16x16x32_bf16 v[74:77], v[198:201], v[222:225], v[74:77]
	v_mfma_f32_16x16x32_bf16 v[70:73], v[206:209], v[214:217], v[70:73]
	v_mfma_f32_16x16x32_bf16 v[66:69], v[206:209], v[222:225], v[66:69]
	v_mfma_f32_16x16x32_bf16 v[94:97], v[164:167], v[218:221], v[94:97]
	v_mfma_f32_16x16x32_bf16 v[90:93], v[164:167], v[226:229], v[90:93]
	v_mfma_f32_16x16x32_bf16 v[86:89], v[194:197], v[218:221], v[86:89]
	v_mfma_f32_16x16x32_bf16 v[82:85], v[194:197], v[226:229], v[82:85]
	v_mfma_f32_16x16x32_bf16 v[78:81], v[202:205], v[218:221], v[78:81]
	v_mfma_f32_16x16x32_bf16 v[74:77], v[202:205], v[226:229], v[74:77]
	v_mfma_f32_16x16x32_bf16 v[70:73], v[210:213], v[218:221], v[70:73]
	v_mfma_f32_16x16x32_bf16 v[66:69], v[210:213], v[226:229], v[66:69]
	s_barrier
	s_mov_b32 m0, s42
	v_lshl_add_u64 v[236:237], v[138:139], 0, s[58:59]
	ds_read_b128 v[160:163], v142 offset:16384
	ds_read_b128 v[164:167], v142 offset:17408
	ds_read_b128 v[190:193], v142 offset:18432
	ds_read_b128 v[194:197], v142 offset:19456
	ds_read_b128 v[198:201], v142 offset:20480
	ds_read_b128 v[202:205], v142 offset:21504
	ds_read_b128 v[206:209], v142 offset:22528
	ds_read_b128 v[210:213], v142 offset:23552
	global_load_lds_dwordx4 v[236:237], off
	v_lshl_add_u64 v[236:237], v[230:231], 0, s[58:59]
	s_mov_b32 m0, s43
	s_nop 0
	global_load_lds_dwordx4 v[236:237], off
	s_barrier
	s_waitcnt lgkmcnt(0)
	v_mfma_f32_16x16x32_bf16 v[62:65], v[160:163], v[144:147], v[62:65]
	v_mfma_f32_16x16x32_bf16 v[58:61], v[160:163], v[152:155], v[58:61]
	v_mfma_f32_16x16x32_bf16 v[54:57], v[190:193], v[144:147], v[54:57]
	v_mfma_f32_16x16x32_bf16 v[50:53], v[190:193], v[152:155], v[50:53]
	v_mfma_f32_16x16x32_bf16 v[46:49], v[198:201], v[144:147], v[46:49]
	v_mfma_f32_16x16x32_bf16 v[42:45], v[198:201], v[152:155], v[42:45]
	v_mfma_f32_16x16x32_bf16 v[38:41], v[206:209], v[144:147], v[38:41]
	v_mfma_f32_16x16x32_bf16 v[34:37], v[206:209], v[152:155], v[34:37]
	v_mfma_f32_16x16x32_bf16 v[62:65], v[164:167], v[148:151], v[62:65]
	v_mfma_f32_16x16x32_bf16 v[58:61], v[164:167], v[156:159], v[58:61]
	v_mfma_f32_16x16x32_bf16 v[54:57], v[194:197], v[148:151], v[54:57]
	v_mfma_f32_16x16x32_bf16 v[50:53], v[194:197], v[156:159], v[50:53]
	v_mfma_f32_16x16x32_bf16 v[46:49], v[202:205], v[148:151], v[46:49]
	v_mfma_f32_16x16x32_bf16 v[42:45], v[202:205], v[156:159], v[42:45]
	v_mfma_f32_16x16x32_bf16 v[38:41], v[210:213], v[148:151], v[38:41]
	v_mfma_f32_16x16x32_bf16 v[34:37], v[210:213], v[156:159], v[34:37]
	s_barrier
;     __device__ __forceinline__ unsigned* BAR() const { return (unsigned*)(ws + OFF_BAR); }
; #define STAGE(bufoff, gbase, voff) do { _Pragma("unroll") for (int _i = 0; _i < 2; ++_i) \
;         __builtin_amdgcn_global_load_lds((const unsigned*)((const char*)(gbase) + voff[_i]), (LAS unsigned*)(lds + (bufoff) + ldsw + _i * 8192), 16, 0, 0); } while (0)
; #define LDA(dst, b, h) do { _Pragma("unroll") for (int m = 0; m < 4; ++m) _Pragma("unroll") for (int k = 0; k < 2; ++k) dst[m][k] = *(const LAS bf16x8*)(lds + SA(b, h) + aoff + m * 2048 + k * 1024); } while (0)
; #define LDB(dst, b, h) do { _Pragma("unroll") for (int n = 0; n < 2; ++n) _Pragma("unroll") for (int k = 0; k < 2; ++k) dst[n][k] = *(const LAS bf16x8*)(lds + SB(b, h) + boff + n * 2048 + k * 1024); } while (0)
; #define MMA(ai, bj, At, Bx) do { __builtin_amdgcn_s_setprio(1); _Pragma("unroll") for (int m = 0; m < 4; ++m) _Pragma("unroll") for (int n = 0; n < 2; ++n) _Pragma("unroll") for (int k = 0; k < 2; ++k) \
;       acc[ai][bj][m][n] = __builtin_amdgcn_mfma_f32_16x16x32_bf16(At[m][k], Bx[n][k], acc[ai][bj][m][n], 0, 0, 0); \
;     __builtin_amdgcn_s_setprio(0); } while (0)
; #define WAIT_V(n) asm volatile("s_waitcnt vmcnt(" #n ")" ::: "memory")
; #define WAIT_L(n) asm volatile("s_waitcnt lgkmcnt(" #n ")" ::: "memory")
; #define BAR __builtin_amdgcn_s_barrier()
; #define SCHED __builtin_amdgcn_sched_barrier(0)
;     ...
;         STAGE(SB(0, 1), b2 + hstepB, voffB);
;         WAIT_V(6); BAR; MMA(1, 1, At, B1); BAR;
;         LDB(B0, 1, 0); SCHED; LDA(At, 1, 0); STAGE(SA(0, 1), a2 + hstepA, voffA);
;         WAIT_L(8); BAR; WAIT_L(0); MMA(0, 0, At, B0); BAR; SCHED;
;         LDB(B1, 1, 1); STAGE(SB(1, 0), b3, voffB);
;         BAR; WAIT_L(0); MMA(0, 1, At, B1); BAR;
;         LDA(At, 1, 1); STAGE(SA(1, 0), a3, voffA);
;         BAR; WAIT_L(0); MMA(1, 0, At, B0); BAR; SCHED;
	s_add_i32 s16, s17, s15
	v_lshl_add_u64 v[144:145], v[232:233], 0, s[82:83]
	s_mov_b32 m0, s16
	s_nop 0
	global_load_lds_dwordx4 v[144:145], off
	v_lshl_add_u64 v[144:145], v[234:235], 0, s[82:83]
	s_add_i32 m0, s16, 0x2000
	s_nop 0
	global_load_lds_dwordx4 v[144:145], off
	s_waitcnt vmcnt(6)
	s_barrier
	v_mfma_f32_16x16x32_bf16 v[30:33], v[160:163], v[214:217], v[30:33]
	v_mfma_f32_16x16x32_bf16 v[26:29], v[160:163], v[222:225], v[26:29]
	v_mfma_f32_16x16x32_bf16 v[22:25], v[190:193], v[214:217], v[22:25]
	v_mfma_f32_16x16x32_bf16 v[18:21], v[190:193], v[222:225], v[18:21]
	v_mfma_f32_16x16x32_bf16 v[14:17], v[198:201], v[214:217], v[14:17]
	v_mfma_f32_16x16x32_bf16 v[10:13], v[198:201], v[222:225], v[10:13]
	v_mfma_f32_16x16x32_bf16 v[6:9], v[206:209], v[214:217], v[6:9]
	v_mfma_f32_16x16x32_bf16 v[2:5], v[206:209], v[222:225], v[2:5]
	v_mfma_f32_16x16x32_bf16 v[30:33], v[164:167], v[218:221], v[30:33]
	v_mfma_f32_16x16x32_bf16 v[26:29], v[164:167], v[226:229], v[26:29]
	v_mfma_f32_16x16x32_bf16 v[22:25], v[194:197], v[218:221], v[22:25]
	v_mfma_f32_16x16x32_bf16 v[18:21], v[194:197], v[226:229], v[18:21]
	v_mfma_f32_16x16x32_bf16 v[14:17], v[202:205], v[218:221], v[14:17]
	v_mfma_f32_16x16x32_bf16 v[10:13], v[202:205], v[226:229], v[10:13]
	v_mfma_f32_16x16x32_bf16 v[6:9], v[210:213], v[218:221], v[6:9]
	v_mfma_f32_16x16x32_bf16 v[2:5], v[210:213], v[226:229], v[2:5]
	s_barrier
	s_add_i32 s16, 0, 0x18000
	v_add_u32_e32 v156, s16, v143
	ds_read_b128 v[144:147], v156
	ds_read_b128 v[148:151], v156 offset:1024
	ds_read_b128 v[152:155], v156 offset:2048
	ds_read_b128 v[156:159], v156 offset:3072
	s_mov_b32 m0, s54
	v_lshl_add_u64 v[214:215], v[138:139], 0, s[96:97]
	ds_read_b128 v[160:163], v142 offset:32768
	ds_read_b128 v[164:167], v142 offset:33792
	ds_read_b128 v[190:193], v142 offset:34816
	ds_read_b128 v[194:197], v142 offset:35840
	ds_read_b128 v[198:201], v142 offset:36864
	ds_read_b128 v[202:205], v142 offset:37888
	ds_read_b128 v[206:209], v142 offset:38912
	ds_read_b128 v[210:213], v142 offset:39936
	global_load_lds_dwordx4 v[214:215], off
	v_lshl_add_u64 v[214:215], v[230:231], 0, s[96:97]
	s_mov_b32 m0, s55
	s_nop 0
	global_load_lds_dwordx4 v[214:215], off
	s_waitcnt lgkmcnt(8)
	s_barrier
	s_waitcnt lgkmcnt(0)
	v_mfma_f32_16x16x32_bf16 v[126:129], v[160:163], v[144:147], v[126:129]
	v_mfma_f32_16x16x32_bf16 v[122:125], v[160:163], v[152:155], v[122:125]
	v_mfma_f32_16x16x32_bf16 v[118:121], v[190:193], v[144:147], v[118:121]
	v_mfma_f32_16x16x32_bf16 v[114:117], v[190:193], v[152:155], v[114:117]
	v_mfma_f32_16x16x32_bf16 v[110:113], v[198:201], v[144:147], v[110:113]
	v_mfma_f32_16x16x32_bf16 v[106:109], v[198:201], v[152:155], v[106:109]
	v_mfma_f32_16x16x32_bf16 v[102:105], v[206:209], v[144:147], v[102:105]
	v_mfma_f32_16x16x32_bf16 v[98:101], v[206:209], v[152:155], v[98:101]
	v_mfma_f32_16x16x32_bf16 v[126:129], v[164:167], v[148:151], v[126:129]
	v_mfma_f32_16x16x32_bf16 v[122:125], v[164:167], v[156:159], v[122:125]
	v_mfma_f32_16x16x32_bf16 v[118:121], v[194:197], v[148:151], v[118:121]
	v_mfma_f32_16x16x32_bf16 v[114:117], v[194:197], v[156:159], v[114:117]
	v_mfma_f32_16x16x32_bf16 v[110:113], v[202:205], v[148:151], v[110:113]
	v_mfma_f32_16x16x32_bf16 v[106:109], v[202:205], v[156:159], v[106:109]
	v_mfma_f32_16x16x32_bf16 v[102:105], v[210:213], v[148:151], v[102:105]
	v_mfma_f32_16x16x32_bf16 v[98:101], v[210:213], v[156:159], v[98:101]
	s_barrier
	s_add_i32 s17, 0, 0x1c000
	s_add_i32 s16, s16, s15
	v_add_u32_e32 v226, s17, v143
	v_lshl_add_u64 v[236:237], v[232:233], 0, s[18:19]
	s_mov_b32 m0, s16
	ds_read_b128 v[214:217], v226
	ds_read_b128 v[218:221], v226 offset:1024
	ds_read_b128 v[222:225], v226 offset:2048
	ds_read_b128 v[226:229], v226 offset:3072
	global_load_lds_dwordx4 v[236:237], off
	v_lshl_add_u64 v[236:237], v[234:235], 0, s[18:19]
	s_add_i32 m0, s16, 0x2000
	s_nop 0
	global_load_lds_dwordx4 v[236:237], off
	s_barrier
	s_waitcnt lgkmcnt(0)
	v_mfma_f32_16x16x32_bf16 v[94:97], v[160:163], v[214:217], v[94:97]
	v_mfma_f32_16x16x32_bf16 v[90:93], v[160:163], v[222:225], v[90:93]
	v_mfma_f32_16x16x32_bf16 v[86:89], v[190:193], v[214:217], v[86:89]
	v_mfma_f32_16x16x32_bf16 v[82:85], v[190:193], v[222:225], v[82:85]
	v_mfma_f32_16x16x32_bf16 v[78:81], v[198:201], v[214:217], v[78:81]
	v_mfma_f32_16x16x32_bf16 v[74:77], v[198:201], v[222:225], v[74:77]
	v_mfma_f32_16x16x32_bf16 v[70:73], v[206:209], v[214:217], v[70:73]
	v_mfma_f32_16x16x32_bf16 v[66:69], v[206:209], v[222:225], v[66:69]
	v_mfma_f32_16x16x32_bf16 v[94:97], v[164:167], v[218:221], v[94:97]
	v_mfma_f32_16x16x32_bf16 v[90:93], v[164:167], v[226:229], v[90:93]
	v_mfma_f32_16x16x32_bf16 v[86:89], v[194:197], v[218:221], v[86:89]
	v_mfma_f32_16x16x32_bf16 v[82:85], v[194:197], v[226:229], v[82:85]
	v_mfma_f32_16x16x32_bf16 v[78:81], v[202:205], v[218:221], v[78:81]
	v_mfma_f32_16x16x32_bf16 v[74:77], v[202:205], v[226:229], v[74:77]
	v_mfma_f32_16x16x32_bf16 v[70:73], v[210:213], v[218:221], v[70:73]
	v_mfma_f32_16x16x32_bf16 v[66:69], v[210:213], v[226:229], v[66:69]
	s_barrier
	s_mov_b32 m0, s56
	v_lshl_add_u64 v[138:139], v[138:139], 0, s[34:35]
	ds_read_b128 v[160:163], v142 offset:49152
	ds_read_b128 v[164:167], v142 offset:50176
	ds_read_b128 v[190:193], v142 offset:51200
	ds_read_b128 v[194:197], v142 offset:52224
	ds_read_b128 v[198:201], v142 offset:53248
	ds_read_b128 v[202:205], v142 offset:54272
	ds_read_b128 v[206:209], v142 offset:55296
	ds_read_b128 v[210:213], v142 offset:56320
	global_load_lds_dwordx4 v[138:139], off
	v_lshl_add_u64 v[138:139], v[230:231], 0, s[34:35]
	s_mov_b32 m0, s57
	s_nop 0
	global_load_lds_dwordx4 v[138:139], off
	s_barrier
;     __device__ __forceinline__ unsigned* BAR() const { return (unsigned*)(ws + OFF_BAR); }
; #define STAGE(bufoff, gbase, voff) do { _Pragma("unroll") for (int _i = 0; _i < 2; ++_i) \
;         __builtin_amdgcn_global_load_lds((const unsigned*)((const char*)(gbase) + voff[_i]), (LAS unsigned*)(lds + (bufoff) + ldsw + _i * 8192), 16, 0, 0); } while (0)
; #define LDA(dst, b, h) do { _Pragma("unroll") for (int m = 0; m < 4; ++m) _Pragma("unroll") for (int k = 0; k < 2; ++k) dst[m][k] = *(const LAS bf16x8*)(lds + SA(b, h) + aoff + m * 2048 + k * 1024); } while (0)
; #define LDB(dst, b, h) do { _Pragma("unroll") for (int n = 0; n < 2; ++n) _Pragma("unroll") for (int k = 0; k < 2; ++k) dst[n][k] = *(const LAS bf16x8*)(lds + SB(b, h) + boff + n * 2048 + k * 1024); } while (0)
; #define MMA(ai, bj, At, Bx) do { __builtin_amdgcn_s_setprio(1); _Pragma("unroll") for (int m = 0; m < 4; ++m) _Pragma("unroll") for (int n = 0; n < 2; ++n) _Pragma("unroll") for (int k = 0; k < 2; ++k) \
;       acc[ai][bj][m][n] = __builtin_amdgcn_mfma_f32_16x16x32_bf16(At[m][k], Bx[n][k], acc[ai][bj][m][n], 0, 0, 0); \
;     __builtin_amdgcn_s_setprio(0); } while (0)
; #define WAIT_V(n) asm volatile("s_waitcnt vmcnt(" #n ")" ::: "memory")
; #define WAIT_L(n) asm volatile("s_waitcnt lgkmcnt(" #n ")" ::: "memory")
; #define BAR __builtin_amdgcn_s_barrier()
;     ...
;         STAGE(SB(1, 1), b3 + hstepB, voffB);
;         WAIT_V(6); BAR; MMA(1, 1, At, B1); BAR;
;     }
;     { LDB(B0, 0, 0); LDA(At, 0, 0); STAGE(SA(1, 1), pA(nt - 1) + hstepA, voffA);
;       BAR; WAIT_L(0); MMA(0, 0, At, B0); BAR;
;       LDB(B1, 0, 1); BAR; WAIT_L(0); MMA(0, 1, At, B1); BAR;
;       LDA(At, 0, 1); WAIT_V(4); BAR; WAIT_L(0); MMA(1, 0, At, B0); MMA(1, 1, At, B1); BAR; }
;     { LDB(B0, 1, 0); LDA(At, 1, 0); WAIT_V(2); BAR; WAIT_L(0); MMA(0, 0, At, B0); BAR;
	s_waitcnt lgkmcnt(0)
	v_mfma_f32_16x16x32_bf16 v[62:65], v[160:163], v[144:147], v[62:65]
	v_mfma_f32_16x16x32_bf16 v[58:61], v[160:163], v[152:155], v[58:61]
	v_mfma_f32_16x16x32_bf16 v[54:57], v[190:193], v[144:147], v[54:57]
	v_mfma_f32_16x16x32_bf16 v[50:53], v[190:193], v[152:155], v[50:53]
	v_mfma_f32_16x16x32_bf16 v[46:49], v[198:201], v[144:147], v[46:49]
	v_mfma_f32_16x16x32_bf16 v[42:45], v[198:201], v[152:155], v[42:45]
	v_mfma_f32_16x16x32_bf16 v[38:41], v[206:209], v[144:147], v[38:41]
	v_mfma_f32_16x16x32_bf16 v[34:37], v[206:209], v[152:155], v[34:37]
	v_mfma_f32_16x16x32_bf16 v[62:65], v[164:167], v[148:151], v[62:65]
	v_mfma_f32_16x16x32_bf16 v[58:61], v[164:167], v[156:159], v[58:61]
	v_mfma_f32_16x16x32_bf16 v[54:57], v[194:197], v[148:151], v[54:57]
	v_mfma_f32_16x16x32_bf16 v[50:53], v[194:197], v[156:159], v[50:53]
	v_mfma_f32_16x16x32_bf16 v[46:49], v[202:205], v[148:151], v[46:49]
	v_mfma_f32_16x16x32_bf16 v[42:45], v[202:205], v[156:159], v[42:45]
	v_mfma_f32_16x16x32_bf16 v[38:41], v[210:213], v[148:151], v[38:41]
	v_mfma_f32_16x16x32_bf16 v[34:37], v[210:213], v[156:159], v[34:37]
	s_barrier
	s_add_i32 s16, s17, s15
	v_lshl_add_u64 v[138:139], v[232:233], 0, s[86:87]
	s_mov_b32 m0, s16
	s_nop 0
	global_load_lds_dwordx4 v[138:139], off
	v_lshl_add_u64 v[138:139], v[234:235], 0, s[86:87]
	s_add_i32 m0, s16, 0x2000
	s_nop 0
	global_load_lds_dwordx4 v[138:139], off
	s_waitcnt vmcnt(6)
	s_barrier
	v_mfma_f32_16x16x32_bf16 v[30:33], v[160:163], v[214:217], v[30:33]
	v_mfma_f32_16x16x32_bf16 v[26:29], v[160:163], v[222:225], v[26:29]
	v_mfma_f32_16x16x32_bf16 v[22:25], v[190:193], v[214:217], v[22:25]
	v_mfma_f32_16x16x32_bf16 v[18:21], v[190:193], v[222:225], v[18:21]
	v_mfma_f32_16x16x32_bf16 v[14:17], v[198:201], v[214:217], v[14:17]
	v_mfma_f32_16x16x32_bf16 v[10:13], v[198:201], v[222:225], v[10:13]
	v_mfma_f32_16x16x32_bf16 v[6:9], v[206:209], v[214:217], v[6:9]
	v_mfma_f32_16x16x32_bf16 v[2:5], v[206:209], v[222:225], v[2:5]
	v_mfma_f32_16x16x32_bf16 v[30:33], v[164:167], v[218:221], v[30:33]
	v_mfma_f32_16x16x32_bf16 v[26:29], v[164:167], v[226:229], v[26:29]
	v_mfma_f32_16x16x32_bf16 v[22:25], v[194:197], v[218:221], v[22:25]
	v_mfma_f32_16x16x32_bf16 v[18:21], v[194:197], v[226:229], v[18:21]
	v_mfma_f32_16x16x32_bf16 v[14:17], v[202:205], v[218:221], v[14:17]
	v_mfma_f32_16x16x32_bf16 v[10:13], v[202:205], v[226:229], v[10:13]
	v_mfma_f32_16x16x32_bf16 v[6:9], v[210:213], v[218:221], v[6:9]
	v_mfma_f32_16x16x32_bf16 v[2:5], v[210:213], v[226:229], v[2:5]
	s_barrier
	s_add_i32 s10, s10, 2
	s_add_u32 s8, s8, 0x100
	s_addc_u32 s9, s9, 0
	s_cmp_gt_u32 s10, 11
	s_cbranch_scc0 .LBB0_617
	v_add_u32_e32 v143, 0, v143
	s_add_u32 s6, s6, 0x40780
	v_add_u32_e32 v140, 0x10000, v143
	s_addc_u32 s7, s7, 0
	s_mov_b32 m0, s88
	ds_read_b128 v[132:135], v140
	ds_read_b128 v[136:139], v140 offset:1024
	ds_read_b128 v[144:147], v140 offset:2048
	ds_read_b128 v[148:151], v140 offset:3072
	ds_read_b128 v[152:155], v142
	ds_read_b128 v[156:159], v142 offset:1024
	ds_read_b128 v[160:163], v142 offset:2048
	ds_read_b128 v[164:167], v142 offset:3072
	ds_read_b128 v[190:193], v142 offset:4096
	ds_read_b128 v[194:197], v142 offset:5120
	ds_read_b128 v[198:201], v142 offset:6144
	ds_read_b128 v[202:205], v142 offset:7168
	v_lshl_add_u64 v[140:141], s[6:7], 0, v[0:1]
	global_load_lds_dwordx4 v[140:141], off
	v_lshl_add_u64 v[130:131], s[6:7], 0, v[130:131]
	s_mov_b32 m0, s11
	s_nop 0
	global_load_lds_dwordx4 v[130:131], off
	s_barrier
	s_waitcnt lgkmcnt(0)
	v_mfma_f32_16x16x32_bf16 v[126:129], v[152:155], v[132:135], v[126:129]
	v_mfma_f32_16x16x32_bf16 v[122:125], v[152:155], v[144:147], v[122:125]
	v_mfma_f32_16x16x32_bf16 v[118:121], v[160:163], v[132:135], v[118:121]
	v_mfma_f32_16x16x32_bf16 v[114:117], v[160:163], v[144:147], v[114:117]
	v_mfma_f32_16x16x32_bf16 v[110:113], v[190:193], v[132:135], v[110:113]
	v_mfma_f32_16x16x32_bf16 v[106:109], v[190:193], v[144:147], v[106:109]
	v_mfma_f32_16x16x32_bf16 v[102:105], v[198:201], v[132:135], v[102:105]
	v_mfma_f32_16x16x32_bf16 v[98:101], v[198:201], v[144:147], v[98:101]
	v_mfma_f32_16x16x32_bf16 v[126:129], v[156:159], v[136:139], v[126:129]
	v_mfma_f32_16x16x32_bf16 v[122:125], v[156:159], v[148:151], v[122:125]
	v_mfma_f32_16x16x32_bf16 v[118:121], v[164:167], v[136:139], v[118:121]
	v_mfma_f32_16x16x32_bf16 v[114:117], v[164:167], v[148:151], v[114:117]
	v_mfma_f32_16x16x32_bf16 v[110:113], v[194:197], v[136:139], v[110:113]
	v_mfma_f32_16x16x32_bf16 v[106:109], v[194:197], v[148:151], v[106:109]
	v_mfma_f32_16x16x32_bf16 v[102:105], v[202:205], v[136:139], v[102:105]
	v_mfma_f32_16x16x32_bf16 v[98:101], v[202:205], v[148:151], v[98:101]
	v_add_u32_e32 v0, 0x14000, v143
	s_barrier
	ds_read_b128 v[206:209], v0
	ds_read_b128 v[210:213], v0 offset:1024
	ds_read_b128 v[214:217], v0 offset:2048
	ds_read_b128 v[218:221], v0 offset:3072
	s_barrier
	s_waitcnt lgkmcnt(0)
	v_mfma_f32_16x16x32_bf16 v[66:69], v[198:201], v[214:217], v[66:69]
	v_mfma_f32_16x16x32_bf16 v[94:97], v[152:155], v[206:209], v[94:97]
	v_mfma_f32_16x16x32_bf16 v[90:93], v[152:155], v[214:217], v[90:93]
	v_mfma_f32_16x16x32_bf16 v[86:89], v[160:163], v[206:209], v[86:89]
	v_mfma_f32_16x16x32_bf16 v[82:85], v[160:163], v[214:217], v[82:85]
	v_mfma_f32_16x16x32_bf16 v[78:81], v[190:193], v[206:209], v[78:81]
	v_mfma_f32_16x16x32_bf16 v[74:77], v[190:193], v[214:217], v[74:77]
	v_mfma_f32_16x16x32_bf16 v[70:73], v[198:201], v[206:209], v[70:73]
	v_mfma_f32_16x16x32_bf16 v[66:69], v[202:205], v[218:221], v[66:69]
	v_mfma_f32_16x16x32_bf16 v[222:225], v[156:159], v[210:213], v[94:97]
	v_mfma_f32_16x16x32_bf16 v[152:155], v[156:159], v[218:221], v[90:93]
	v_mfma_f32_16x16x32_bf16 v[156:159], v[164:167], v[210:213], v[86:89]
	v_mfma_f32_16x16x32_bf16 v[160:163], v[164:167], v[218:221], v[82:85]
	v_mfma_f32_16x16x32_bf16 v[164:167], v[194:197], v[210:213], v[78:81]
	v_mfma_f32_16x16x32_bf16 v[190:193], v[194:197], v[218:221], v[74:77]
	v_mfma_f32_16x16x32_bf16 v[194:197], v[202:205], v[210:213], v[70:73]
	s_barrier
;     __device__ __forceinline__ unsigned* BAR() const { return (unsigned*)(ws + OFF_BAR); }
; #define LDA(dst, b, h) do { _Pragma("unroll") for (int m = 0; m < 4; ++m) _Pragma("unroll") for (int k = 0; k < 2; ++k) dst[m][k] = *(const LAS bf16x8*)(lds + SA(b, h) + aoff + m * 2048 + k * 1024); } while (0)
; #define LDB(dst, b, h) do { _Pragma("unroll") for (int n = 0; n < 2; ++n) _Pragma("unroll") for (int k = 0; k < 2; ++k) dst[n][k] = *(const LAS bf16x8*)(lds + SB(b, h) + boff + n * 2048 + k * 1024); } while (0)
; #define MMA(ai, bj, At, Bx) do { __builtin_amdgcn_s_setprio(1); _Pragma("unroll") for (int m = 0; m < 4; ++m) _Pragma("unroll") for (int n = 0; n < 2; ++n) _Pragma("unroll") for (int k = 0; k < 2; ++k) \
;       acc[ai][bj][m][n] = __builtin_amdgcn_mfma_f32_16x16x32_bf16(At[m][k], Bx[n][k], acc[ai][bj][m][n], 0, 0, 0); \
;     __builtin_amdgcn_s_setprio(0); } while (0)
; #define WAIT_V(n) asm volatile("s_waitcnt vmcnt(" #n ")" ::: "memory")
; #define WAIT_L(n) asm volatile("s_waitcnt lgkmcnt(" #n ")" ::: "memory")
; #define BAR __builtin_amdgcn_s_barrier()
;     ...
;       LDA(At, 0, 1); WAIT_V(4); BAR; WAIT_L(0); MMA(1, 0, At, B0); MMA(1, 1, At, B1); BAR; }
;     { LDB(B0, 1, 0); LDA(At, 1, 0); WAIT_V(2); BAR; WAIT_L(0); MMA(0, 0, At, B0); BAR;
	s_nop 0
	ds_read_b128 v[70:73], v142 offset:16384
	ds_read_b128 v[74:77], v142 offset:17408
	ds_read_b128 v[78:81], v142 offset:18432
	ds_read_b128 v[82:85], v142 offset:19456
	ds_read_b128 v[86:89], v142 offset:20480
	ds_read_b128 v[90:93], v142 offset:21504
	ds_read_b128 v[94:97], v142 offset:22528
	ds_read_b128 v[198:201], v142 offset:23552
	s_waitcnt vmcnt(4)
	s_barrier
	s_waitcnt lgkmcnt(0)
	v_mfma_f32_16x16x32_bf16 v[62:65], v[70:73], v[132:135], v[62:65]
	v_mfma_f32_16x16x32_bf16 v[58:61], v[70:73], v[144:147], v[58:61]
	v_mfma_f32_16x16x32_bf16 v[54:57], v[78:81], v[132:135], v[54:57]
	v_mfma_f32_16x16x32_bf16 v[50:53], v[78:81], v[144:147], v[50:53]
	v_mfma_f32_16x16x32_bf16 v[34:37], v[94:97], v[144:147], v[34:37]
	v_mfma_f32_16x16x32_bf16 v[62:65], v[74:77], v[136:139], v[62:65]
	v_mfma_f32_16x16x32_bf16 v[58:61], v[74:77], v[148:151], v[58:61]
	v_mfma_f32_16x16x32_bf16 v[54:57], v[82:85], v[136:139], v[54:57]
	v_mfma_f32_16x16x32_bf16 v[50:53], v[82:85], v[148:151], v[50:53]
	v_mfma_f32_16x16x32_bf16 v[46:49], v[86:89], v[132:135], v[46:49]
	v_mfma_f32_16x16x32_bf16 v[42:45], v[86:89], v[144:147], v[42:45]
	v_mfma_f32_16x16x32_bf16 v[38:41], v[94:97], v[132:135], v[38:41]
	v_mfma_f32_16x16x32_bf16 v[34:37], v[198:201], v[148:151], v[34:37]
	v_mfma_f32_16x16x32_bf16 v[202:205], v[90:93], v[136:139], v[46:49]
	v_mfma_f32_16x16x32_bf16 v[226:229], v[90:93], v[148:151], v[42:45]
	v_mfma_f32_16x16x32_bf16 v[130:133], v[198:201], v[136:139], v[38:41]
	v_mfma_f32_16x16x32_bf16 v[30:33], v[70:73], v[206:209], v[30:33]
	v_mfma_f32_16x16x32_bf16 v[26:29], v[70:73], v[214:217], v[26:29]
	v_mfma_f32_16x16x32_bf16 v[22:25], v[78:81], v[206:209], v[22:25]
	v_mfma_f32_16x16x32_bf16 v[18:21], v[78:81], v[214:217], v[18:21]
	v_mfma_f32_16x16x32_bf16 v[2:5], v[94:97], v[214:217], v[2:5]
	v_mfma_f32_16x16x32_bf16 v[30:33], v[74:77], v[210:213], v[30:33]
	v_mfma_f32_16x16x32_bf16 v[26:29], v[74:77], v[218:221], v[26:29]
	v_mfma_f32_16x16x32_bf16 v[22:25], v[82:85], v[210:213], v[22:25]
	v_mfma_f32_16x16x32_bf16 v[18:21], v[82:85], v[218:221], v[18:21]
	v_mfma_f32_16x16x32_bf16 v[14:17], v[86:89], v[206:209], v[14:17]
	v_mfma_f32_16x16x32_bf16 v[10:13], v[86:89], v[214:217], v[10:13]
	v_mfma_f32_16x16x32_bf16 v[6:9], v[94:97], v[206:209], v[6:9]
	v_mfma_f32_16x16x32_bf16 v[2:5], v[198:201], v[218:221], v[2:5]
	v_mfma_f32_16x16x32_bf16 v[134:137], v[90:93], v[210:213], v[14:17]
	v_mfma_f32_16x16x32_bf16 v[138:141], v[90:93], v[218:221], v[10:13]
	v_mfma_f32_16x16x32_bf16 v[144:147], v[198:201], v[210:213], v[6:9]
	v_add_u32_e32 v0, 0x18000, v143
	s_barrier
	s_nop 0
	ds_read_b128 v[6:9], v0
	ds_read_b128 v[10:13], v0 offset:1024
	ds_read_b128 v[14:17], v0 offset:2048
	ds_read_b128 v[148:151], v0 offset:3072
	ds_read_b128 v[38:41], v142 offset:32768
	ds_read_b128 v[42:45], v142 offset:33792
	ds_read_b128 v[46:49], v142 offset:34816
	ds_read_b128 v[70:73], v142 offset:35840
	ds_read_b128 v[198:201], v142 offset:36864
	ds_read_b128 v[206:209], v142 offset:37888
	ds_read_b128 v[210:213], v142 offset:38912
	ds_read_b128 v[214:217], v142 offset:39936
	s_waitcnt vmcnt(2)
	s_barrier
	s_waitcnt lgkmcnt(0)
	v_mfma_f32_16x16x32_bf16 v[74:77], v[38:41], v[6:9], v[126:129]
	v_mfma_f32_16x16x32_bf16 v[126:129], v[42:45], v[10:13], v[74:77]
	v_mfma_f32_16x16x32_bf16 v[74:77], v[38:41], v[14:17], v[122:125]
	v_mfma_f32_16x16x32_bf16 v[94:97], v[42:45], v[148:151], v[74:77]
	v_mfma_f32_16x16x32_bf16 v[74:77], v[46:49], v[6:9], v[118:121]
	v_mfma_f32_16x16x32_bf16 v[122:125], v[70:73], v[10:13], v[74:77]
	v_mfma_f32_16x16x32_bf16 v[74:77], v[46:49], v[14:17], v[114:117]
	v_mfma_f32_16x16x32_bf16 v[90:93], v[70:73], v[148:151], v[74:77]
	v_mfma_f32_16x16x32_bf16 v[74:77], v[198:201], v[6:9], v[110:113]
	v_mfma_f32_16x16x32_bf16 v[118:121], v[206:209], v[10:13], v[74:77]
	v_mfma_f32_16x16x32_bf16 v[74:77], v[198:201], v[14:17], v[106:109]
	v_mfma_f32_16x16x32_bf16 v[86:89], v[206:209], v[148:151], v[74:77]
	v_mfma_f32_16x16x32_bf16 v[74:77], v[210:213], v[6:9], v[102:105]
	v_mfma_f32_16x16x32_bf16 v[114:117], v[214:217], v[10:13], v[74:77]
	v_mfma_f32_16x16x32_bf16 v[74:77], v[210:213], v[14:17], v[98:101]
	v_mfma_f32_16x16x32_bf16 v[82:85], v[214:217], v[148:151], v[74:77]
	v_add_u32_e32 v0, 0x1c000, v143
	s_barrier
;     __device__ __forceinline__ unsigned* BAR() const { return (unsigned*)(ws + OFF_BAR); }
; #define LDA(dst, b, h) do { _Pragma("unroll") for (int m = 0; m < 4; ++m) _Pragma("unroll") for (int k = 0; k < 2; ++k) dst[m][k] = *(const LAS bf16x8*)(lds + SA(b, h) + aoff + m * 2048 + k * 1024); } while (0)
; #define LDB(dst, b, h) do { _Pragma("unroll") for (int n = 0; n < 2; ++n) _Pragma("unroll") for (int k = 0; k < 2; ++k) dst[n][k] = *(const LAS bf16x8*)(lds + SB(b, h) + boff + n * 2048 + k * 1024); } while (0)
; #define MMA(ai, bj, At, Bx) do { __builtin_amdgcn_s_setprio(1); _Pragma("unroll") for (int m = 0; m < 4; ++m) _Pragma("unroll") for (int n = 0; n < 2; ++n) _Pragma("unroll") for (int k = 0; k < 2; ++k) \
;       acc[ai][bj][m][n] = __builtin_amdgcn_mfma_f32_16x16x32_bf16(At[m][k], Bx[n][k], acc[ai][bj][m][n], 0, 0, 0); \
;     __builtin_amdgcn_s_setprio(0); } while (0)
; #define WAIT_V(n) asm volatile("s_waitcnt vmcnt(" #n ")" ::: "memory")
; #define WAIT_L(n) asm volatile("s_waitcnt lgkmcnt(" #n ")" ::: "memory")
; #define BAR __builtin_amdgcn_s_barrier()
;     ...
;       LDB(B1, 1, 1); WAIT_V(0); BAR; WAIT_L(0); MMA(0, 1, At, B1); BAR;
;       LDA(At, 1, 1); BAR; WAIT_L(0); MMA(1, 0, At, B0); MMA(1, 1, At, B1); BAR; }
;     if (wr == 0) BAR;
	ds_read_b128 v[218:221], v0
	ds_read_b128 v[230:233], v0 offset:1024
	ds_read_b128 v[234:237], v0 offset:2048
	ds_read_b128 v[238:241], v0 offset:3072
	s_waitcnt vmcnt(0)
	s_barrier
	s_waitcnt lgkmcnt(0)
	v_mfma_f32_16x16x32_bf16 v[74:77], v[38:41], v[218:221], v[222:225]
	v_mfma_f32_16x16x32_bf16 v[38:41], v[38:41], v[234:237], v[152:155]
	v_mfma_f32_16x16x32_bf16 v[78:81], v[42:45], v[238:241], v[38:41]
	v_mfma_f32_16x16x32_bf16 v[38:41], v[46:49], v[218:221], v[156:159]
	v_mfma_f32_16x16x32_bf16 v[106:109], v[70:73], v[230:233], v[38:41]
	v_mfma_f32_16x16x32_bf16 v[38:41], v[46:49], v[234:237], v[160:163]
	v_mfma_f32_16x16x32_bf16 v[110:113], v[42:45], v[230:233], v[74:77]
	v_mfma_f32_16x16x32_bf16 v[74:77], v[70:73], v[238:241], v[38:41]
	v_mfma_f32_16x16x32_bf16 v[38:41], v[198:201], v[218:221], v[164:167]
	v_mfma_f32_16x16x32_bf16 v[102:105], v[206:209], v[230:233], v[38:41]
	v_mfma_f32_16x16x32_bf16 v[38:41], v[198:201], v[234:237], v[190:193]
	v_mfma_f32_16x16x32_bf16 v[70:73], v[206:209], v[238:241], v[38:41]
	v_mfma_f32_16x16x32_bf16 v[38:41], v[210:213], v[218:221], v[194:197]
	v_mfma_f32_16x16x32_bf16 v[98:101], v[214:217], v[230:233], v[38:41]
	v_mfma_f32_16x16x32_bf16 v[38:41], v[210:213], v[234:237], v[66:69]
	v_mfma_f32_16x16x32_bf16 v[66:69], v[214:217], v[238:241], v[38:41]
	s_barrier
	ds_read_b128 v[152:155], v142 offset:49152
	ds_read_b128 v[156:159], v142 offset:50176
	ds_read_b128 v[160:163], v142 offset:51200
	ds_read_b128 v[164:167], v142 offset:52224
	ds_read_b128 v[190:193], v142 offset:53248
	ds_read_b128 v[194:197], v142 offset:54272
	ds_read_b128 v[198:201], v142 offset:55296
	ds_read_b128 v[206:209], v142 offset:56320
	s_barrier
	s_waitcnt lgkmcnt(0)
	v_mfma_f32_16x16x32_bf16 v[38:41], v[152:155], v[6:9], v[62:65]
	v_mfma_f32_16x16x32_bf16 v[62:65], v[156:159], v[10:13], v[38:41]
	v_mfma_f32_16x16x32_bf16 v[38:41], v[152:155], v[14:17], v[58:61]
	v_mfma_f32_16x16x32_bf16 v[46:49], v[156:159], v[148:151], v[38:41]
	v_mfma_f32_16x16x32_bf16 v[38:41], v[160:163], v[6:9], v[54:57]
	v_mfma_f32_16x16x32_bf16 v[58:61], v[164:167], v[10:13], v[38:41]
	v_mfma_f32_16x16x32_bf16 v[38:41], v[160:163], v[14:17], v[50:53]
	v_mfma_f32_16x16x32_bf16 v[42:45], v[164:167], v[148:151], v[38:41]
	v_mfma_f32_16x16x32_bf16 v[38:41], v[190:193], v[6:9], v[202:205]
	v_mfma_f32_16x16x32_bf16 v[6:9], v[198:201], v[6:9], v[130:133]
	v_mfma_f32_16x16x32_bf16 v[54:57], v[194:197], v[10:13], v[38:41]
	v_mfma_f32_16x16x32_bf16 v[38:41], v[190:193], v[14:17], v[226:229]
	v_mfma_f32_16x16x32_bf16 v[50:53], v[206:209], v[10:13], v[6:9]
	v_mfma_f32_16x16x32_bf16 v[6:9], v[198:201], v[14:17], v[34:37]
	v_mfma_f32_16x16x32_bf16 v[38:41], v[194:197], v[148:151], v[38:41]
	v_mfma_f32_16x16x32_bf16 v[34:37], v[206:209], v[148:151], v[6:9]
	v_mfma_f32_16x16x32_bf16 v[6:9], v[152:155], v[218:221], v[30:33]
	v_mfma_f32_16x16x32_bf16 v[30:33], v[156:159], v[230:233], v[6:9]
	v_mfma_f32_16x16x32_bf16 v[6:9], v[152:155], v[234:237], v[26:29]
	v_mfma_f32_16x16x32_bf16 v[14:17], v[156:159], v[238:241], v[6:9]
	v_mfma_f32_16x16x32_bf16 v[6:9], v[160:163], v[218:221], v[22:25]
	v_mfma_f32_16x16x32_bf16 v[26:29], v[164:167], v[230:233], v[6:9]
	v_mfma_f32_16x16x32_bf16 v[6:9], v[160:163], v[234:237], v[18:21]
	v_mfma_f32_16x16x32_bf16 v[10:13], v[164:167], v[238:241], v[6:9]
	v_mfma_f32_16x16x32_bf16 v[6:9], v[190:193], v[218:221], v[134:137]
	v_mfma_f32_16x16x32_bf16 v[22:25], v[194:197], v[230:233], v[6:9]
	v_mfma_f32_16x16x32_bf16 v[6:9], v[190:193], v[234:237], v[138:141]
	v_mfma_f32_16x16x32_bf16 v[18:21], v[198:201], v[218:221], v[144:147]
	v_mfma_f32_16x16x32_bf16 v[2:5], v[198:201], v[234:237], v[2:5]
	v_mfma_f32_16x16x32_bf16 v[6:9], v[194:197], v[238:241], v[6:9]
	v_mfma_f32_16x16x32_bf16 v[18:21], v[206:209], v[230:233], v[18:21]
	v_mfma_f32_16x16x32_bf16 v[2:5], v[206:209], v[238:241], v[2:5]
	s_cmpk_lt_u32 s14, 0x100
	s_barrier
	s_cbranch_scc0 .LBB0_620
	s_barrier
